# cross-attention QK and PV stages: LDS fragment reads hoisted 8 operands ahead of their MFMAs into spare VGPRs with counted lgkmcnt waits; on top of the mixing-phase wait fixes
# speedup vs baseline: 1.0052x; 1.0052x over previous
.LBB0_318:
	s_or_b64 exec, exec, s[6:7]
	s_lshl_b32 s6, s52, 7
	s_add_u32 s6, s71, s6
	s_waitcnt lgkmcnt(0)
	s_barrier
	s_addc_u32 s7, s72, 0
	v_lshlrev_b32_e32 v1, 5, v144
	global_load_dwordx4 v[136:139], v1, s[6:7] offset:16
	global_load_dwordx4 v[144:147], v1, s[6:7]
	s_waitcnt lgkmcnt(0)
	global_load_dwordx4 v[132:135], v1, s[6:7] offset:528
	global_load_dwordx4 v[140:143], v1, s[6:7] offset:512
	s_lshl_b32 s6, s55, 10
	s_add_i32 s6, s6, 0
	v_lshl_add_u32 v3, v3, 4, s6
	v_add_u32_e32 v1, 0x20000, v3
	ds_read_b128 v[154:157], v1
	s_lshl_b32 s8, s52, 6
	s_add_i32 s15, s8, 0
	s_movk_i32 s16, 0x210
	s_ashr_i32 s6, s54, 3
	s_waitcnt lgkmcnt(0)
	v_mov_b32_e32 v158, v155
	v_mov_b32_e32 v159, v156
	v_mov_b32_e32 v155, v157
	v_pk_add_f32 v[154:155], v[158:159], v[154:155]
	v_readlane_b32 s10, v254, 18
	v_add_f32_e32 v1, v154, v155
	v_fmamk_f32 v1, v1, 0x3b800000, v213
	v_rsq_f32_e32 v1, v1
	v_readlane_b32 s11, v254, 19
	v_readlane_b32 s48, v254, 41
	v_readlane_b32 s49, v254, 42
	v_mul_f32_e32 v160, v0, v1
	v_add_u32_e32 v0, 0x20100, v3
	ds_read_b128 v[154:157], v0
	v_pk_mul_f32 v[128:129], v[128:129], v[160:161] op_sel_hi:[1,0]
	v_pk_mul_f32 v[120:121], v[120:121], v[160:161] op_sel_hi:[1,0]
	v_pk_mul_f32 v[124:125], v[124:125], v[160:161] op_sel_hi:[1,0]
	v_pk_mul_f32 v[126:127], v[126:127], v[160:161] op_sel_hi:[1,0]
	s_waitcnt lgkmcnt(0)
	v_mov_b32_e32 v0, v155
	v_mov_b32_e32 v1, v156
	v_mov_b32_e32 v155, v157
	v_pk_add_f32 v[0:1], v[0:1], v[154:155]
	v_pk_mul_f32 v[116:117], v[116:117], v[160:161] op_sel_hi:[1,0]
	v_add_f32_e32 v0, v0, v1
	v_fmamk_f32 v0, v0, 0x3b800000, v213
	v_rsq_f32_e32 v0, v0
	v_pk_mul_f32 v[118:119], v[118:119], v[160:161] op_sel_hi:[1,0]
	v_pk_mul_f32 v[130:131], v[130:131], v[160:161] op_sel_hi:[1,0]
	v_pk_mul_f32 v[122:123], v[122:123], v[160:161] op_sel_hi:[1,0]
	v_mul_f32_e32 v158, v148, v0
	v_add_u32_e32 v0, 0x20200, v3
	ds_read_b128 v[154:157], v0
	v_pk_mul_f32 v[112:113], v[112:113], v[158:159] op_sel_hi:[1,0]
	v_pk_mul_f32 v[100:101], v[100:101], v[158:159] op_sel_hi:[1,0]
	v_pk_mul_f32 v[108:109], v[108:109], v[158:159] op_sel_hi:[1,0]
	v_pk_mul_f32 v[110:111], v[110:111], v[158:159] op_sel_hi:[1,0]
	s_waitcnt lgkmcnt(0)
	v_mov_b32_e32 v0, v155
	v_mov_b32_e32 v1, v156
	v_mov_b32_e32 v155, v157
	v_pk_add_f32 v[0:1], v[0:1], v[154:155]
	v_pk_mul_f32 v[92:93], v[92:93], v[158:159] op_sel_hi:[1,0]
	v_add_f32_e32 v0, v0, v1
	v_fmamk_f32 v0, v0, 0x3b800000, v213
	v_rsq_f32_e32 v0, v0
	v_pk_mul_f32 v[94:95], v[94:95], v[158:159] op_sel_hi:[1,0]
	v_pk_mul_f32 v[102:103], v[102:103], v[158:159] op_sel_hi:[1,0]
	v_pk_mul_f32 v[114:115], v[114:115], v[158:159] op_sel_hi:[1,0]
	v_mul_f32_e32 v156, v150, v0
	v_add_u32_e32 v0, 0x20300, v3
	ds_read_b128 v[174:177], v0
	v_pk_mul_f32 v[84:85], v[84:85], v[156:157] op_sel_hi:[1,0]
	v_pk_mul_f32 v[96:97], v[96:97], v[156:157] op_sel_hi:[1,0]
	v_pk_mul_f32 v[98:99], v[98:99], v[156:157] op_sel_hi:[1,0]
	v_pk_mul_f32 v[76:77], v[76:77], v[156:157] op_sel_hi:[1,0]
	s_waitcnt lgkmcnt(0)
	v_mov_b32_e32 v0, v175
	v_mov_b32_e32 v1, v176
	v_mov_b32_e32 v175, v177
	v_pk_add_f32 v[0:1], v[0:1], v[174:175]
	v_pk_mul_f32 v[78:79], v[78:79], v[156:157] op_sel_hi:[1,0]
	v_add_f32_e32 v0, v0, v1
	v_fmamk_f32 v0, v0, 0x3b800000, v213
	v_rsq_f32_e32 v0, v0
	v_pk_mul_f32 v[86:87], v[86:87], v[156:157] op_sel_hi:[1,0]
	v_mul_f32_e32 v154, v152, v0
	v_add_u32_e32 v0, 0x20800, v3
	ds_read_b128 v[174:177], v0
	s_waitcnt vmcnt(0)
	v_pk_mul_f32 v[128:129], v[144:145], v[128:129]
	v_pk_mul_f32 v[112:113], v[144:145], v[112:113]
	v_pk_mul_f32 v[120:121], v[140:141], v[120:121]
	v_pk_mul_f32 v[100:101], v[140:141], v[100:101]
	s_waitcnt lgkmcnt(0)
	v_mov_b32_e32 v0, v175
	v_mov_b32_e32 v1, v176
	v_mov_b32_e32 v175, v177
	v_pk_add_f32 v[0:1], v[0:1], v[174:175]
	v_pk_mul_f32 v[84:85], v[140:141], v[84:85]
	v_add_f32_e32 v0, v0, v1
	v_fmamk_f32 v0, v0, 0x3b800000, v213
	v_rsq_f32_e32 v0, v0
	v_pk_mul_f32 v[72:73], v[72:73], v[154:155] op_sel_hi:[1,0]
	v_pk_mul_f32 v[80:81], v[80:81], v[154:155] op_sel_hi:[1,0]
	v_pk_mul_f32 v[82:83], v[82:83], v[154:155] op_sel_hi:[1,0]
	v_mul_f32_e32 v152, v162, v0
	v_add_u32_e32 v0, 0x20900, v3
	ds_read_b128 v[174:177], v0
	v_pk_mul_f32 v[72:73], v[140:141], v[72:73]
	v_pk_mul_f32 v[68:69], v[68:69], v[154:155] op_sel_hi:[1,0]
	v_pk_mul_f32 v[70:71], v[70:71], v[154:155] op_sel_hi:[1,0]
	v_pk_mul_f32 v[102:103], v[142:143], v[102:103]
	s_waitcnt lgkmcnt(0)
	v_mov_b32_e32 v0, v175
	v_mov_b32_e32 v1, v176
	v_mov_b32_e32 v175, v177
	v_pk_add_f32 v[0:1], v[0:1], v[174:175]
	v_pk_mul_f32 v[86:87], v[142:143], v[86:87]
	v_add_f32_e32 v0, v0, v1
	v_fmamk_f32 v0, v0, 0x3b800000, v213
	v_rsq_f32_e32 v0, v0
	v_pk_mul_f32 v[130:131], v[146:147], v[130:131]
	v_pk_mul_f32 v[74:75], v[74:75], v[154:155] op_sel_hi:[1,0]
	v_pk_mul_f32 v[122:123], v[142:143], v[122:123]
	v_mul_f32_e32 v150, v164, v0
	v_add_u32_e32 v0, 0x20a00, v3
	ds_read_b128 v[162:165], v0
	v_pk_mul_f32 v[56:57], v[56:57], v[150:151] op_sel_hi:[1,0]
	v_pk_mul_f32 v[20:21], v[20:21], v[150:151] op_sel_hi:[1,0]
	v_pk_mul_f32 v[22:23], v[22:23], v[150:151] op_sel_hi:[1,0]
	v_pk_mul_f32 v[56:57], v[136:137], v[56:57]
	s_waitcnt lgkmcnt(0)
	v_mov_b32_e32 v0, v163
	v_mov_b32_e32 v1, v164
	v_mov_b32_e32 v163, v165
	v_pk_add_f32 v[0:1], v[0:1], v[162:163]
	v_pk_mul_f32 v[22:23], v[142:143], v[22:23]
	v_add_f32_e32 v0, v0, v1
	v_fmamk_f32 v0, v0, 0x3b800000, v213
	v_rsq_f32_e32 v0, v0
	v_pk_mul_f32 v[20:21], v[140:141], v[20:21]
	v_pk_mul_f32 v[16:17], v[16:17], v[150:151] op_sel_hi:[1,0]
	v_pk_mul_f32 v[18:19], v[18:19], v[150:151] op_sel_hi:[1,0]
	v_mul_f32_e32 v148, v166, v0
	v_add_u32_e32 v0, 0x20b00, v3
	ds_read_b128 v[162:165], v0
	v_mov_b32_e32 v3, v217
	v_pk_mul_f32 v[48:49], v[48:49], v[148:149] op_sel_hi:[1,0]
	v_and_b32_e32 v153, 48, v3
	s_waitcnt lgkmcnt(0)
	v_mov_b32_e32 v0, v163
	v_mov_b32_e32 v1, v164
	v_mov_b32_e32 v163, v165
	v_pk_add_f32 v[0:1], v[0:1], v[162:163]
	v_pk_mul_f32 v[162:163], v[138:139], v[126:127]
	v_pk_mul_f32 v[126:127], v[136:137], v[124:125]
	v_cvt_pk_bf16_f32 v124, v128, v129
	v_pk_mul_f32 v[128:129], v[134:135], v[118:119]
	v_pk_mul_f32 v[118:119], v[132:133], v[116:117]
	v_cvt_pk_bf16_f32 v116, v120, v121
	v_pk_mul_f32 v[120:121], v[138:139], v[110:111]
	v_pk_mul_f32 v[110:111], v[136:137], v[108:109]
	v_cvt_pk_bf16_f32 v108, v112, v113
	v_pk_mul_f32 v[112:113], v[134:135], v[94:95]
	v_pk_mul_f32 v[94:95], v[132:133], v[92:93]
	v_cvt_pk_bf16_f32 v92, v100, v101
	v_pk_mul_f32 v[100:101], v[104:105], v[156:157] op_sel_hi:[1,0]
	v_add_f32_e32 v0, v0, v1
	v_pk_mul_f32 v[100:101], v[144:145], v[100:101]
	v_fmamk_f32 v0, v0, 0x3b800000, v213
	v_pk_mul_f32 v[104:105], v[138:139], v[98:99]
	v_pk_mul_f32 v[98:99], v[136:137], v[96:97]
	v_cvt_pk_bf16_f32 v96, v100, v101
	v_pk_mul_f32 v[100:101], v[134:135], v[78:79]
	v_pk_mul_f32 v[78:79], v[132:133], v[76:77]
	v_cvt_pk_bf16_f32 v76, v84, v85
	v_pk_mul_f32 v[84:85], v[88:89], v[154:155] op_sel_hi:[1,0]
	v_pk_mul_f32 v[64:65], v[64:65], v[152:153] op_sel_hi:[1,0]
	v_pk_mul_f32 v[12:13], v[12:13], v[152:153] op_sel_hi:[1,0]
	v_pk_mul_f32 v[14:15], v[14:15], v[152:153] op_sel_hi:[1,0]
	v_rsq_f32_e32 v0, v0
	v_pk_mul_f32 v[84:85], v[144:145], v[84:85]
	v_pk_mul_f32 v[64:65], v[144:145], v[64:65]
	v_pk_mul_f32 v[4:5], v[4:5], v[152:153] op_sel_hi:[1,0]
	v_pk_mul_f32 v[6:7], v[6:7], v[152:153] op_sel_hi:[1,0]
	v_pk_mul_f32 v[14:15], v[142:143], v[14:15]
	v_pk_mul_f32 v[12:13], v[140:141], v[12:13]
	v_pk_mul_f32 v[8:9], v[8:9], v[152:153] op_sel_hi:[1,0]
	v_pk_mul_f32 v[10:11], v[10:11], v[152:153] op_sel_hi:[1,0]
	v_pk_mul_f32 v[88:89], v[138:139], v[82:83]
	v_pk_mul_f32 v[82:83], v[136:137], v[80:81]
	v_cvt_pk_bf16_f32 v80, v84, v85
	v_pk_mul_f32 v[84:85], v[134:135], v[70:71]
	v_pk_mul_f32 v[70:71], v[132:133], v[68:69]
	v_cvt_pk_bf16_f32 v68, v72, v73
	v_pk_mul_f32 v[72:73], v[138:139], v[6:7]
	v_pk_mul_f32 v[6:7], v[136:137], v[4:5]
	v_cvt_pk_bf16_f32 v4, v64, v65
	v_pk_mul_f32 v[64:65], v[134:135], v[10:11]
	v_pk_mul_f32 v[10:11], v[132:133], v[8:9]
	v_cvt_pk_bf16_f32 v8, v12, v13
	v_cvt_pk_bf16_f32 v9, v14, v15
	v_pk_mul_f32 v[12:13], v[60:61], v[150:151] op_sel_hi:[1,0]
	v_pk_mul_f32 v[14:15], v[62:63], v[150:151] op_sel_hi:[1,0]
	v_pk_mul_f32 v[12:13], v[144:145], v[12:13]
	v_pk_mul_f32 v[14:15], v[146:147], v[14:15]
	v_cvt_pk_bf16_f32 v12, v12, v13
	v_cvt_pk_bf16_f32 v13, v14, v15
	v_cvt_pk_bf16_f32 v14, v56, v57
	v_pk_mul_f32 v[56:57], v[134:135], v[18:19]
	v_pk_mul_f32 v[18:19], v[132:133], v[16:17]
	v_cvt_pk_bf16_f32 v16, v20, v21
	v_cvt_pk_bf16_f32 v17, v22, v23
	v_pk_mul_f32 v[20:21], v[52:53], v[148:149] op_sel_hi:[1,0]
	v_pk_mul_f32 v[22:23], v[54:55], v[148:149] op_sel_hi:[1,0]
	v_pk_mul_f32 v[28:29], v[28:29], v[148:149] op_sel_hi:[1,0]
	v_pk_mul_f32 v[30:31], v[30:31], v[148:149] op_sel_hi:[1,0]
	v_mul_f32_e32 v0, v168, v0
	v_pk_mul_f32 v[22:23], v[146:147], v[22:23]
	v_pk_mul_f32 v[20:21], v[144:145], v[20:21]
	v_pk_mul_f32 v[48:49], v[136:137], v[48:49]
	v_pk_mul_f32 v[30:31], v[142:143], v[30:31]
	v_pk_mul_f32 v[28:29], v[140:141], v[28:29]
	v_pk_mul_f32 v[24:25], v[24:25], v[148:149] op_sel_hi:[1,0]
	v_pk_mul_f32 v[26:27], v[26:27], v[148:149] op_sel_hi:[1,0]
	v_cvt_pk_bf16_f32 v20, v20, v21
	v_cvt_pk_bf16_f32 v21, v22, v23
	v_cvt_pk_bf16_f32 v22, v48, v49
	v_pk_mul_f32 v[48:49], v[134:135], v[26:27]
	v_pk_mul_f32 v[26:27], v[132:133], v[24:25]
	v_cvt_pk_bf16_f32 v24, v28, v29
	v_cvt_pk_bf16_f32 v25, v30, v31
	v_pk_mul_f32 v[28:29], v[44:45], v[0:1] op_sel_hi:[1,0]
	v_pk_mul_f32 v[30:31], v[46:47], v[0:1] op_sel_hi:[1,0]
	v_pk_mul_f32 v[40:41], v[40:41], v[0:1] op_sel_hi:[1,0]
	v_pk_mul_f32 v[42:43], v[42:43], v[0:1] op_sel_hi:[1,0]
	v_pk_mul_f32 v[36:37], v[36:37], v[0:1] op_sel_hi:[1,0]
	v_pk_mul_f32 v[38:39], v[38:39], v[0:1] op_sel_hi:[1,0]
	v_pk_mul_f32 v[32:33], v[32:33], v[0:1] op_sel_hi:[1,0]
	v_pk_mul_f32 v[0:1], v[34:35], v[0:1] op_sel_hi:[1,0]
	v_readfirstlane_b32 s7, v3
	v_pk_mul_f32 v[0:1], v[134:135], v[0:1]
	v_pk_mul_f32 v[34:35], v[132:133], v[32:33]
	s_ashr_i32 s8, s7, 2
	v_pk_mul_f32 v[36:37], v[140:141], v[36:37]
	v_cvt_pk_bf16_f32 v34, v34, v35
	v_cvt_pk_bf16_f32 v35, v0, v1
	v_bfi_b32 v1, -16, s8, v3
	v_cvt_pk_bf16_f32 v32, v36, v37
	v_mul_lo_u32 v36, v1, s16
	v_add3_u32 v175, 0, v36, v153
	v_ashrrev_i32_e32 v36, 3, v3
	v_pk_mul_f32 v[30:31], v[146:147], v[30:31]
	v_pk_mul_f32 v[28:29], v[144:145], v[28:29]
	v_pk_mul_f32 v[40:41], v[136:137], v[40:41]
	v_pk_mul_f32 v[38:39], v[142:143], v[38:39]
	v_ashrrev_i32_e32 v37, 31, v36
	v_cvt_pk_bf16_f32 v28, v28, v29
	v_cvt_pk_bf16_f32 v29, v30, v31
	v_cvt_pk_bf16_f32 v30, v40, v41
	v_cvt_pk_bf16_f32 v33, v38, v39
	v_and_b32_e32 v38, 15, v3
	v_bfe_u32 v39, v3, 4, 2
	v_lshlrev_b64 v[44:45], 13, v[36:37]
	v_lshlrev_b32_e32 v37, 3, v3
	v_lshlrev_b32_e32 v40, 4, v3
	v_bfe_u32 v3, v3, 2, 2
	v_mul_lo_u32 v36, v36, s16
	v_and_b32_e32 v180, 0x70, v40
	v_lshl_or_b32 v3, v39, 2, v3
	s_ashr_i32 s7, s6, 31
	s_lshl_b32 s8, s53, 8
	v_add3_u32 v170, s10, v36, v180
	v_mul_u32_u24_e32 v38, 0x210, v38
	v_add3_u32 v168, s11, v36, v180
	v_mul_u32_u24_e32 v3, 0x210, v3
	v_and_b32_e32 v36, 24, v37
	s_lshl_b64 s[12:13], s[6:7], 21
	s_ashr_i32 s9, s8, 31
	v_add3_u32 v174, s10, v153, v38
	v_add3_u32 v173, s11, v153, v38
	v_add3_u32 v169, s10, v3, v36
	v_add3_u32 v3, s11, v3, v36
	s_lshl_b64 s[10:11], s[6:7], 22
	s_add_u32 s12, s60, s12
	s_addc_u32 s13, s61, s13
	v_lshl_add_u64 v[44:45], s[12:13], 0, v[44:45]
	s_lshl_b32 s12, s0, 11
	s_ashr_i32 s13, s12, 31
	v_cvt_pk_bf16_f32 v93, v102, v103
	v_pk_mul_f32 v[102:103], v[106:107], v[156:157] op_sel_hi:[1,0]
	v_cvt_pk_bf16_f32 v77, v86, v87
	v_pk_mul_f32 v[86:87], v[90:91], v[154:155] op_sel_hi:[1,0]
	v_mul_lo_u32 v36, v149, s16
	v_lshl_add_u64 v[44:45], s[12:13], 1, v[44:45]
	s_lshl_b64 s[8:9], s[8:9], 1
	v_cvt_pk_bf16_f32 v125, v130, v131
	v_cvt_pk_bf16_f32 v126, v126, v127
	v_cvt_pk_bf16_f32 v127, v162, v163
	v_pk_mul_f32 v[114:115], v[146:147], v[114:115]
	v_pk_mul_f32 v[102:103], v[146:147], v[102:103]
	v_pk_mul_f32 v[86:87], v[146:147], v[86:87]
	v_pk_mul_f32 v[74:75], v[142:143], v[74:75]
	v_add3_u32 v176, s15, v151, v36
	v_lshl_add_u64 v[44:45], v[44:45], 0, s[8:9]
	v_cvt_pk_bf16_f32 v117, v122, v123
	v_cvt_pk_bf16_f32 v118, v118, v119
	v_cvt_pk_bf16_f32 v119, v128, v129
	v_cvt_pk_bf16_f32 v109, v114, v115
	v_cvt_pk_bf16_f32 v110, v110, v111
	v_cvt_pk_bf16_f32 v111, v120, v121
	v_cvt_pk_bf16_f32 v94, v94, v95
	v_cvt_pk_bf16_f32 v95, v112, v113
	v_cvt_pk_bf16_f32 v97, v102, v103
	v_cvt_pk_bf16_f32 v98, v98, v99
	v_cvt_pk_bf16_f32 v99, v104, v105
	v_cvt_pk_bf16_f32 v78, v78, v79
	v_cvt_pk_bf16_f32 v79, v100, v101
	v_cvt_pk_bf16_f32 v81, v86, v87
	v_cvt_pk_bf16_f32 v82, v82, v83
	v_cvt_pk_bf16_f32 v83, v88, v89
	v_cvt_pk_bf16_f32 v69, v74, v75
	v_cvt_pk_bf16_f32 v70, v70, v71
	v_cvt_pk_bf16_f32 v71, v84, v85
	s_waitcnt lgkmcnt(0)
	s_barrier
	ds_write_b128 v176, v[124:127]
	ds_write_b128 v176, v[116:119] offset:256
	ds_write_b128 v176, v[108:111] offset:8448
	ds_write_b128 v176, v[92:95] offset:8704
	ds_write_b128 v176, v[96:99] offset:16896
	ds_write_b128 v176, v[76:79] offset:17152
	ds_write_b128 v176, v[80:83] offset:25344
	ds_write_b128 v176, v[68:71] offset:25600
	v_lshl_add_u64 v[166:167], v[44:45], 0, v[180:181]
	s_mov_b32 s7, 0x80000
	v_pk_mul_f32 v[66:67], v[66:67], v[152:153] op_sel_hi:[1,0]
	v_pk_mul_f32 v[58:59], v[58:59], v[150:151] op_sel_hi:[1,0]
	v_pk_mul_f32 v[50:51], v[50:51], v[148:149] op_sel_hi:[1,0]
	v_pk_mul_f32 v[42:43], v[138:139], v[42:43]
	s_waitcnt lgkmcnt(0)
	s_barrier
	v_add_co_u32_e32 v164, vcc, s7, v166
	v_pk_mul_f32 v[66:67], v[146:147], v[66:67]
	v_pk_mul_f32 v[58:59], v[138:139], v[58:59]
	v_pk_mul_f32 v[50:51], v[138:139], v[50:51]
	v_cvt_pk_bf16_f32 v31, v42, v43
	v_lshlrev_b32_e32 v0, 3, v39
	ds_read_b128 v[124:127], v175
	ds_read_b128 v[120:123], v175 offset:64
	ds_read_b128 v[116:119], v175 offset:128
	ds_read_b128 v[108:111], v175 offset:192
	ds_read_b128 v[80:83], v175 offset:256
	ds_read_b128 v[76:79], v175 offset:320
	ds_read_b128 v[40:43], v175 offset:384
	ds_read_b128 v[36:39], v175 offset:448
	global_load_dwordx4 v[60:63], v[166:167], off
	v_addc_co_u32_e32 v165, vcc, 0, v167, vcc
	v_cvt_pk_bf16_f32 v5, v66, v67
	v_cvt_pk_bf16_f32 v6, v6, v7
	v_cvt_pk_bf16_f32 v7, v72, v73
	v_cvt_pk_bf16_f32 v10, v10, v11
	v_cvt_pk_bf16_f32 v11, v64, v65
	v_cvt_pk_bf16_f32 v15, v58, v59
	v_cvt_pk_bf16_f32 v18, v18, v19
	v_cvt_pk_bf16_f32 v19, v56, v57
	v_cvt_pk_bf16_f32 v23, v50, v51
	v_cvt_pk_bf16_f32 v26, v26, v27
	v_cvt_pk_bf16_f32 v27, v48, v49
	global_load_dwordx4 v[44:47], v[164:165], off
	global_load_dwordx4 v[64:67], v[166:167], off offset:128
	global_load_dwordx4 v[48:51], v[164:165], off offset:128
	global_load_dwordx4 v[68:71], v[166:167], off offset:256
	global_load_dwordx4 v[52:55], v[164:165], off offset:256
	global_load_dwordx4 v[72:75], v[166:167], off offset:384
	global_load_dwordx4 v[56:59], v[164:165], off offset:384
	s_mov_b32 s7, 0x100000
	v_add_co_u32_e32 v162, vcc, s7, v166
	s_waitcnt vmcnt(7)
	ds_write_b128 v170, v[60:63]
	s_waitcnt vmcnt(5)
	ds_write_b128 v170, v[64:67] offset:128
	s_waitcnt vmcnt(3)
	ds_write_b128 v170, v[68:71] offset:256
	s_waitcnt vmcnt(1)
	ds_write_b128 v170, v[72:75] offset:384
	v_addc_co_u32_e32 v163, vcc, 0, v167, vcc
	global_load_dwordx4 v[60:63], v[162:163], off
	global_load_dwordx4 v[64:67], v[162:163], off offset:128
	global_load_dwordx4 v[68:71], v[162:163], off offset:256
	global_load_dwordx4 v[72:75], v[162:163], off offset:384
	s_waitcnt lgkmcnt(0)
	s_barrier
	ds_read_b128 v[204:207], v174
	ds_read_b128 v[208:211], v174 offset:64
	ds_read_b128 v[218:221], v174 offset:128
	ds_read_b128 v[224:227], v174 offset:192
	ds_read_b128 v[228:231], v174 offset:256
	ds_read_b128 v[232:235], v174 offset:320
	ds_read_b128 v[236:239], v174 offset:384
	ds_read_b128 v[240:243], v174 offset:448
	s_waitcnt lgkmcnt(7)
	v_mfma_f32_16x16x32_bf16 v[84:87], v[204:207], v[124:127], 0
	ds_read_b128 v[204:207], v174 offset:8448
	s_waitcnt lgkmcnt(7)
	v_mfma_f32_16x16x32_bf16 v[84:87], v[208:211], v[120:123], v[84:87]
	ds_read_b128 v[208:211], v174 offset:8512
	s_mov_b32 s7, 0x180000
	v_add_co_u32_e32 v160, vcc, s7, v166
	s_waitcnt lgkmcnt(7)
	v_mfma_f32_16x16x32_bf16 v[84:87], v[218:221], v[116:119], v[84:87]
	ds_read_b128 v[218:221], v174 offset:8576
	v_addc_co_u32_e32 v161, vcc, 0, v167, vcc
	s_waitcnt lgkmcnt(7)
	v_mfma_f32_16x16x32_bf16 v[84:87], v[224:227], v[108:111], v[84:87]
	ds_read_b128 v[224:227], v174 offset:8640
	s_mov_b32 s7, 0xf149f2ca
	s_waitcnt lgkmcnt(7)
	v_mfma_f32_16x16x32_bf16 v[84:87], v[228:231], v[80:83], v[84:87]
	ds_read_b128 v[228:231], v174 offset:8704
	s_waitcnt lgkmcnt(7)
	v_mfma_f32_16x16x32_bf16 v[84:87], v[232:235], v[76:79], v[84:87]
	ds_read_b128 v[232:235], v174 offset:8768
	s_waitcnt lgkmcnt(7)
	v_mfma_f32_16x16x32_bf16 v[84:87], v[236:239], v[40:43], v[84:87]
	ds_read_b128 v[236:239], v174 offset:8832
	s_waitcnt lgkmcnt(7)
	v_mfma_f32_16x16x32_bf16 v[84:87], v[240:243], v[36:39], v[84:87]
	ds_read_b128 v[240:243], v174 offset:8896
	s_waitcnt lgkmcnt(7)
	v_mfma_f32_16x16x32_bf16 v[88:91], v[204:207], v[124:127], 0
	ds_read_b128 v[204:207], v174 offset:16896
	s_waitcnt lgkmcnt(7)
	v_mfma_f32_16x16x32_bf16 v[88:91], v[208:211], v[120:123], v[88:91]
	ds_read_b128 v[208:211], v174 offset:16960
	s_waitcnt lgkmcnt(7)
	v_mfma_f32_16x16x32_bf16 v[88:91], v[218:221], v[116:119], v[88:91]
	ds_read_b128 v[218:221], v174 offset:17024
	s_waitcnt lgkmcnt(7)
	v_mfma_f32_16x16x32_bf16 v[88:91], v[224:227], v[108:111], v[88:91]
	ds_read_b128 v[224:227], v174 offset:17088
	s_waitcnt lgkmcnt(7)
	v_mfma_f32_16x16x32_bf16 v[88:91], v[228:231], v[80:83], v[88:91]
	ds_read_b128 v[228:231], v174 offset:17152
	s_waitcnt lgkmcnt(7)
	v_mfma_f32_16x16x32_bf16 v[88:91], v[232:235], v[76:79], v[88:91]
	ds_read_b128 v[232:235], v174 offset:17216
	s_waitcnt lgkmcnt(7)
	v_mfma_f32_16x16x32_bf16 v[88:91], v[236:239], v[40:43], v[88:91]
	ds_read_b128 v[236:239], v174 offset:17280
	s_waitcnt lgkmcnt(7)
	v_mfma_f32_16x16x32_bf16 v[88:91], v[240:243], v[36:39], v[88:91]
	ds_read_b128 v[240:243], v174 offset:17344
	s_waitcnt lgkmcnt(7)
	v_mfma_f32_16x16x32_bf16 v[92:95], v[204:207], v[124:127], 0
	ds_read_b128 v[204:207], v174 offset:25344
	s_waitcnt lgkmcnt(7)
	v_mfma_f32_16x16x32_bf16 v[92:95], v[208:211], v[120:123], v[92:95]
	ds_read_b128 v[208:211], v174 offset:25408
	s_waitcnt lgkmcnt(7)
	v_mfma_f32_16x16x32_bf16 v[92:95], v[218:221], v[116:119], v[92:95]
	ds_read_b128 v[218:221], v174 offset:25472
	s_waitcnt lgkmcnt(7)
	v_mfma_f32_16x16x32_bf16 v[92:95], v[224:227], v[108:111], v[92:95]
	ds_read_b128 v[224:227], v174 offset:25536
	s_waitcnt lgkmcnt(7)
	v_mfma_f32_16x16x32_bf16 v[92:95], v[228:231], v[80:83], v[92:95]
	ds_read_b128 v[228:231], v174 offset:25600
	s_waitcnt lgkmcnt(7)
	v_mfma_f32_16x16x32_bf16 v[92:95], v[232:235], v[76:79], v[92:95]
	ds_read_b128 v[232:235], v174 offset:25664
	s_waitcnt lgkmcnt(7)
	v_mfma_f32_16x16x32_bf16 v[92:95], v[236:239], v[40:43], v[92:95]
	ds_read_b128 v[236:239], v174 offset:25728
	s_waitcnt lgkmcnt(7)
	v_mfma_f32_16x16x32_bf16 v[92:95], v[240:243], v[36:39], v[92:95]
	s_waitcnt lgkmcnt(6)
	v_mfma_f32_16x16x32_bf16 v[96:99], v[204:207], v[124:127], 0
	s_waitcnt lgkmcnt(5)
	v_mfma_f32_16x16x32_bf16 v[96:99], v[208:211], v[120:123], v[96:99]
	s_waitcnt lgkmcnt(4)
	v_mfma_f32_16x16x32_bf16 v[96:99], v[218:221], v[116:119], v[96:99]
	s_waitcnt lgkmcnt(3)
	v_mfma_f32_16x16x32_bf16 v[96:99], v[224:227], v[108:111], v[96:99]
	s_waitcnt lgkmcnt(2)
	v_mfma_f32_16x16x32_bf16 v[96:99], v[228:231], v[80:83], v[96:99]
	s_waitcnt lgkmcnt(1)
	v_mfma_f32_16x16x32_bf16 v[96:99], v[232:235], v[76:79], v[96:99]
	s_waitcnt lgkmcnt(0)
	v_mfma_f32_16x16x32_bf16 v[96:99], v[236:239], v[40:43], v[96:99]
	ds_read_b128 v[100:103], v174 offset:25792
	ds_write_b128 v168, v[44:47]
	ds_write_b128 v168, v[48:51] offset:128
	ds_write_b128 v168, v[52:55] offset:256
	s_waitcnt vmcnt(4)
	ds_write_b128 v168, v[56:59] offset:384
	global_load_dwordx4 v[44:47], v[160:161], off
	global_load_dwordx4 v[48:51], v[160:161], off offset:128
	global_load_dwordx4 v[52:55], v[160:161], off offset:256
	global_load_dwordx4 v[56:59], v[160:161], off offset:384
	s_waitcnt lgkmcnt(0)
	s_barrier
	s_waitcnt lgkmcnt(4)
	v_mfma_f32_16x16x32_bf16 v[96:99], v[100:103], v[36:39], v[96:99]
	ds_read_b128 v[204:207], v173
	ds_read_b128 v[208:211], v173 offset:64
	ds_read_b128 v[218:221], v173 offset:128
	ds_read_b128 v[224:227], v173 offset:192
	ds_read_b128 v[228:231], v173 offset:256
	ds_read_b128 v[232:235], v173 offset:320
	ds_read_b128 v[236:239], v173 offset:384
	ds_read_b128 v[240:243], v173 offset:448
	s_waitcnt lgkmcnt(7)
	v_mfma_f32_16x16x32_bf16 v[100:103], v[204:207], v[124:127], 0
	ds_read_b128 v[204:207], v173 offset:8448
	s_waitcnt lgkmcnt(7)
	v_mfma_f32_16x16x32_bf16 v[100:103], v[208:211], v[120:123], v[100:103]
	ds_read_b128 v[208:211], v173 offset:8512
	s_waitcnt lgkmcnt(7)
	v_mfma_f32_16x16x32_bf16 v[100:103], v[218:221], v[116:119], v[100:103]
	ds_read_b128 v[218:221], v173 offset:8576
	s_waitcnt lgkmcnt(7)
	v_mfma_f32_16x16x32_bf16 v[100:103], v[224:227], v[108:111], v[100:103]
	ds_read_b128 v[224:227], v173 offset:8640
	s_waitcnt lgkmcnt(7)
	v_mfma_f32_16x16x32_bf16 v[100:103], v[228:231], v[80:83], v[100:103]
	ds_read_b128 v[228:231], v173 offset:8704
	s_waitcnt lgkmcnt(7)
	v_mfma_f32_16x16x32_bf16 v[100:103], v[232:235], v[76:79], v[100:103]
	ds_read_b128 v[232:235], v173 offset:8768
	s_waitcnt lgkmcnt(7)
	v_mfma_f32_16x16x32_bf16 v[100:103], v[236:239], v[40:43], v[100:103]
	ds_read_b128 v[236:239], v173 offset:8832
	s_waitcnt lgkmcnt(7)
	v_mfma_f32_16x16x32_bf16 v[100:103], v[240:243], v[36:39], v[100:103]
	ds_read_b128 v[240:243], v173 offset:8896
	s_waitcnt lgkmcnt(7)
	v_mfma_f32_16x16x32_bf16 v[104:107], v[204:207], v[124:127], 0
	ds_read_b128 v[204:207], v173 offset:16896
	s_waitcnt lgkmcnt(7)
	v_mfma_f32_16x16x32_bf16 v[104:107], v[208:211], v[120:123], v[104:107]
	ds_read_b128 v[208:211], v173 offset:16960
	s_waitcnt lgkmcnt(7)
	v_mfma_f32_16x16x32_bf16 v[104:107], v[218:221], v[116:119], v[104:107]
	ds_read_b128 v[218:221], v173 offset:17024
	s_waitcnt lgkmcnt(7)
	v_mfma_f32_16x16x32_bf16 v[104:107], v[224:227], v[108:111], v[104:107]
	ds_read_b128 v[224:227], v173 offset:17088
	s_waitcnt lgkmcnt(7)
	v_mfma_f32_16x16x32_bf16 v[104:107], v[228:231], v[80:83], v[104:107]
	ds_read_b128 v[228:231], v173 offset:17152
	s_waitcnt lgkmcnt(7)
	v_mfma_f32_16x16x32_bf16 v[104:107], v[232:235], v[76:79], v[104:107]
	ds_read_b128 v[232:235], v173 offset:17216
	s_waitcnt lgkmcnt(7)
	v_mfma_f32_16x16x32_bf16 v[104:107], v[236:239], v[40:43], v[104:107]
	ds_read_b128 v[236:239], v173 offset:17280
	s_waitcnt lgkmcnt(7)
	v_mfma_f32_16x16x32_bf16 v[104:107], v[240:243], v[36:39], v[104:107]
	ds_read_b128 v[240:243], v173 offset:17344
	s_waitcnt lgkmcnt(7)
	v_mfma_f32_16x16x32_bf16 v[112:115], v[204:207], v[124:127], 0
	ds_read_b128 v[204:207], v173 offset:25344
	s_waitcnt lgkmcnt(7)
	v_mfma_f32_16x16x32_bf16 v[112:115], v[208:211], v[120:123], v[112:115]
	ds_read_b128 v[208:211], v173 offset:25408
	s_waitcnt lgkmcnt(7)
	v_mfma_f32_16x16x32_bf16 v[112:115], v[218:221], v[116:119], v[112:115]
	ds_read_b128 v[218:221], v173 offset:25472
	s_waitcnt lgkmcnt(7)
	v_mfma_f32_16x16x32_bf16 v[112:115], v[224:227], v[108:111], v[112:115]
	ds_read_b128 v[224:227], v173 offset:25536
	s_waitcnt lgkmcnt(7)
	v_mfma_f32_16x16x32_bf16 v[112:115], v[228:231], v[80:83], v[112:115]
	ds_read_b128 v[228:231], v173 offset:25600
	s_waitcnt lgkmcnt(7)
	v_mfma_f32_16x16x32_bf16 v[112:115], v[232:235], v[76:79], v[112:115]
	ds_read_b128 v[232:235], v173 offset:25664
	s_waitcnt lgkmcnt(7)
	v_mfma_f32_16x16x32_bf16 v[112:115], v[236:239], v[40:43], v[112:115]
	ds_read_b128 v[236:239], v173 offset:25728
	s_waitcnt lgkmcnt(7)
	v_mfma_f32_16x16x32_bf16 v[112:115], v[240:243], v[36:39], v[112:115]
	s_waitcnt lgkmcnt(6)
	v_mfma_f32_16x16x32_bf16 v[128:131], v[204:207], v[124:127], 0
	s_waitcnt lgkmcnt(5)
	v_mfma_f32_16x16x32_bf16 v[128:131], v[208:211], v[120:123], v[128:131]
	s_waitcnt lgkmcnt(4)
	v_mfma_f32_16x16x32_bf16 v[128:131], v[218:221], v[116:119], v[128:131]
	s_waitcnt lgkmcnt(3)
	v_mfma_f32_16x16x32_bf16 v[128:131], v[224:227], v[108:111], v[128:131]
	s_waitcnt lgkmcnt(2)
	v_mfma_f32_16x16x32_bf16 v[128:131], v[228:231], v[80:83], v[128:131]
	s_waitcnt lgkmcnt(1)
	v_mfma_f32_16x16x32_bf16 v[128:131], v[232:235], v[76:79], v[128:131]
	s_waitcnt lgkmcnt(0)
	v_mfma_f32_16x16x32_bf16 v[128:131], v[236:239], v[40:43], v[128:131]
	ds_read_b128 v[132:135], v173 offset:25792
	s_waitcnt vmcnt(7)
	ds_write_b128 v170, v[60:63]
	s_waitcnt vmcnt(6)
	ds_write_b128 v170, v[64:67] offset:128
	s_waitcnt vmcnt(5)
	ds_write_b128 v170, v[68:71] offset:256
	s_waitcnt vmcnt(4)
	ds_write_b128 v170, v[72:75] offset:384
	global_load_dwordx4 v[60:63], v[166:167], off offset:2048
	global_load_dwordx4 v[64:67], v[166:167], off offset:2176
	global_load_dwordx4 v[68:71], v[166:167], off offset:2304
	global_load_dwordx4 v[72:75], v[166:167], off offset:2432
	s_waitcnt lgkmcnt(0)
	s_barrier
	s_waitcnt lgkmcnt(4)
	v_mfma_f32_16x16x32_bf16 v[128:131], v[132:135], v[36:39], v[128:131]
	ds_read_b128 v[204:207], v174
	ds_read_b128 v[208:211], v174 offset:64
	ds_read_b128 v[218:221], v174 offset:128
	ds_read_b128 v[224:227], v174 offset:192
	ds_read_b128 v[228:231], v174 offset:256
	ds_read_b128 v[232:235], v174 offset:320
	ds_read_b128 v[236:239], v174 offset:384
	ds_read_b128 v[240:243], v174 offset:448
	s_waitcnt lgkmcnt(7)
	v_mfma_f32_16x16x32_bf16 v[132:135], v[204:207], v[124:127], 0
	ds_read_b128 v[204:207], v174 offset:8448
	s_waitcnt lgkmcnt(7)
	v_mfma_f32_16x16x32_bf16 v[132:135], v[208:211], v[120:123], v[132:135]
	ds_read_b128 v[208:211], v174 offset:8512
	s_waitcnt lgkmcnt(7)
	v_mfma_f32_16x16x32_bf16 v[132:135], v[218:221], v[116:119], v[132:135]
	ds_read_b128 v[218:221], v174 offset:8576
	s_waitcnt lgkmcnt(7)
	v_mfma_f32_16x16x32_bf16 v[132:135], v[224:227], v[108:111], v[132:135]
	ds_read_b128 v[224:227], v174 offset:8640
	s_waitcnt lgkmcnt(7)
	v_mfma_f32_16x16x32_bf16 v[132:135], v[228:231], v[80:83], v[132:135]
	ds_read_b128 v[228:231], v174 offset:8704
	s_waitcnt lgkmcnt(7)
	v_mfma_f32_16x16x32_bf16 v[132:135], v[232:235], v[76:79], v[132:135]
	ds_read_b128 v[232:235], v174 offset:8768
	s_waitcnt lgkmcnt(7)
	v_mfma_f32_16x16x32_bf16 v[132:135], v[236:239], v[40:43], v[132:135]
	ds_read_b128 v[236:239], v174 offset:8832
	s_waitcnt lgkmcnt(7)
	v_mfma_f32_16x16x32_bf16 v[132:135], v[240:243], v[36:39], v[132:135]
	ds_read_b128 v[240:243], v174 offset:8896
	s_waitcnt lgkmcnt(7)
	v_mfma_f32_16x16x32_bf16 v[136:139], v[204:207], v[124:127], 0
	ds_read_b128 v[204:207], v174 offset:16896
	s_waitcnt lgkmcnt(7)
	v_mfma_f32_16x16x32_bf16 v[136:139], v[208:211], v[120:123], v[136:139]
	ds_read_b128 v[208:211], v174 offset:16960
	s_waitcnt lgkmcnt(7)
	v_mfma_f32_16x16x32_bf16 v[136:139], v[218:221], v[116:119], v[136:139]
	ds_read_b128 v[218:221], v174 offset:17024
	s_waitcnt lgkmcnt(7)
	v_mfma_f32_16x16x32_bf16 v[136:139], v[224:227], v[108:111], v[136:139]
	ds_read_b128 v[224:227], v174 offset:17088
	s_waitcnt lgkmcnt(7)
	v_mfma_f32_16x16x32_bf16 v[136:139], v[228:231], v[80:83], v[136:139]
	ds_read_b128 v[228:231], v174 offset:17152
	s_waitcnt lgkmcnt(7)
	v_mfma_f32_16x16x32_bf16 v[136:139], v[232:235], v[76:79], v[136:139]
	ds_read_b128 v[232:235], v174 offset:17216
	s_waitcnt lgkmcnt(7)
	v_mfma_f32_16x16x32_bf16 v[136:139], v[236:239], v[40:43], v[136:139]
	ds_read_b128 v[236:239], v174 offset:17280
	s_waitcnt lgkmcnt(7)
	v_mfma_f32_16x16x32_bf16 v[136:139], v[240:243], v[36:39], v[136:139]
	ds_read_b128 v[240:243], v174 offset:17344
	s_waitcnt lgkmcnt(7)
	v_mfma_f32_16x16x32_bf16 v[140:143], v[204:207], v[124:127], 0
	ds_read_b128 v[204:207], v174 offset:25344
	s_waitcnt lgkmcnt(7)
	v_mfma_f32_16x16x32_bf16 v[140:143], v[208:211], v[120:123], v[140:143]
	ds_read_b128 v[208:211], v174 offset:25408
	s_waitcnt lgkmcnt(7)
	v_mfma_f32_16x16x32_bf16 v[140:143], v[218:221], v[116:119], v[140:143]
	ds_read_b128 v[218:221], v174 offset:25472
	s_waitcnt lgkmcnt(7)
	v_mfma_f32_16x16x32_bf16 v[140:143], v[224:227], v[108:111], v[140:143]
	ds_read_b128 v[224:227], v174 offset:25536
	s_waitcnt lgkmcnt(7)
	v_mfma_f32_16x16x32_bf16 v[140:143], v[228:231], v[80:83], v[140:143]
	ds_read_b128 v[228:231], v174 offset:25600
	s_waitcnt lgkmcnt(7)
	v_mfma_f32_16x16x32_bf16 v[140:143], v[232:235], v[76:79], v[140:143]
	ds_read_b128 v[232:235], v174 offset:25664
	s_waitcnt lgkmcnt(7)
	v_mfma_f32_16x16x32_bf16 v[140:143], v[236:239], v[40:43], v[140:143]
	ds_read_b128 v[236:239], v174 offset:25728
	s_waitcnt lgkmcnt(7)
	v_mfma_f32_16x16x32_bf16 v[140:143], v[240:243], v[36:39], v[140:143]
	s_waitcnt lgkmcnt(6)
	v_mfma_f32_16x16x32_bf16 v[144:147], v[204:207], v[124:127], 0
	s_waitcnt lgkmcnt(5)
	v_mfma_f32_16x16x32_bf16 v[144:147], v[208:211], v[120:123], v[144:147]
	s_waitcnt lgkmcnt(4)
	v_mfma_f32_16x16x32_bf16 v[144:147], v[218:221], v[116:119], v[144:147]
	s_waitcnt lgkmcnt(3)
	v_mfma_f32_16x16x32_bf16 v[144:147], v[224:227], v[108:111], v[144:147]
	s_waitcnt lgkmcnt(2)
	v_mfma_f32_16x16x32_bf16 v[144:147], v[228:231], v[80:83], v[144:147]
	s_waitcnt lgkmcnt(1)
	v_mfma_f32_16x16x32_bf16 v[144:147], v[232:235], v[76:79], v[144:147]
	s_waitcnt lgkmcnt(0)
	v_mfma_f32_16x16x32_bf16 v[144:147], v[236:239], v[40:43], v[144:147]
	ds_read_b128 v[148:151], v174 offset:25792
	s_waitcnt vmcnt(7)
	ds_write_b128 v168, v[44:47]
	s_waitcnt vmcnt(6)
	ds_write_b128 v168, v[48:51] offset:128
	s_waitcnt vmcnt(5)
	ds_write_b128 v168, v[52:55] offset:256
	s_waitcnt vmcnt(4)
	ds_write_b128 v168, v[56:59] offset:384
	global_load_dwordx4 v[44:47], v[164:165], off offset:2048
	global_load_dwordx4 v[48:51], v[164:165], off offset:2176
	global_load_dwordx4 v[52:55], v[164:165], off offset:2304
	global_load_dwordx4 v[56:59], v[164:165], off offset:2432
	s_waitcnt lgkmcnt(0)
	s_barrier
	s_waitcnt lgkmcnt(4)
	v_mfma_f32_16x16x32_bf16 v[144:147], v[148:151], v[36:39], v[144:147]
	ds_read_b128 v[148:151], v173
	ds_read_b128 v[152:155], v173 offset:64
	ds_read_b128 v[156:159], v173 offset:8512
	s_waitcnt lgkmcnt(2)
	v_mfma_f32_16x16x32_bf16 v[148:151], v[148:151], v[124:127], 0
	ds_read_b128 v[190:193], v173 offset:16960
	s_waitcnt lgkmcnt(2)
	v_mfma_f32_16x16x32_bf16 v[148:151], v[152:155], v[120:123], v[148:151]
	ds_read_b128 v[152:155], v173 offset:128
	s_waitcnt lgkmcnt(0)
	v_mfma_f32_16x16x32_bf16 v[148:151], v[152:155], v[116:119], v[148:151]
	ds_read_b128 v[152:155], v173 offset:192
	s_waitcnt lgkmcnt(0)
	v_mfma_f32_16x16x32_bf16 v[148:151], v[152:155], v[108:111], v[148:151]
	ds_read_b128 v[152:155], v173 offset:256
	s_waitcnt lgkmcnt(0)
	v_mfma_f32_16x16x32_bf16 v[148:151], v[152:155], v[80:83], v[148:151]
	ds_read_b128 v[152:155], v173 offset:320
	s_waitcnt lgkmcnt(0)
	v_mfma_f32_16x16x32_bf16 v[148:151], v[152:155], v[76:79], v[148:151]
	ds_read_b128 v[152:155], v173 offset:384
	s_waitcnt lgkmcnt(0)
	v_mfma_f32_16x16x32_bf16 v[148:151], v[152:155], v[40:43], v[148:151]
	ds_read_b128 v[152:155], v173 offset:448
	s_waitcnt lgkmcnt(0)
	v_mfma_f32_16x16x32_bf16 v[148:151], v[152:155], v[36:39], v[148:151]
	ds_read_b128 v[152:155], v173 offset:8448
	s_waitcnt lgkmcnt(0)
	v_mfma_f32_16x16x32_bf16 v[152:155], v[152:155], v[124:127], 0
	v_mfma_f32_16x16x32_bf16 v[152:155], v[156:159], v[120:123], v[152:155]
	ds_read_b128 v[156:159], v173 offset:8576
	s_waitcnt lgkmcnt(0)
	v_mfma_f32_16x16x32_bf16 v[152:155], v[156:159], v[116:119], v[152:155]
	ds_read_b128 v[156:159], v173 offset:8640
	s_waitcnt lgkmcnt(0)
	v_mfma_f32_16x16x32_bf16 v[152:155], v[156:159], v[108:111], v[152:155]
	ds_read_b128 v[156:159], v173 offset:8704
	s_waitcnt lgkmcnt(0)
	v_mfma_f32_16x16x32_bf16 v[152:155], v[156:159], v[80:83], v[152:155]
	ds_read_b128 v[156:159], v173 offset:8768
	s_waitcnt lgkmcnt(0)
	v_mfma_f32_16x16x32_bf16 v[152:155], v[156:159], v[76:79], v[152:155]
	ds_read_b128 v[156:159], v173 offset:8832
	s_waitcnt lgkmcnt(0)
	v_mfma_f32_16x16x32_bf16 v[152:155], v[156:159], v[40:43], v[152:155]
	ds_read_b128 v[156:159], v173 offset:8896
	s_waitcnt lgkmcnt(0)
	v_mfma_f32_16x16x32_bf16 v[152:155], v[156:159], v[36:39], v[152:155]
	ds_read_b128 v[156:159], v173 offset:16896
	s_waitcnt lgkmcnt(0)
	v_mfma_f32_16x16x32_bf16 v[156:159], v[156:159], v[124:127], 0
	v_mfma_f32_16x16x32_bf16 v[156:159], v[190:193], v[120:123], v[156:159]
	ds_read_b128 v[190:193], v173 offset:17024
	s_waitcnt lgkmcnt(0)
	v_mfma_f32_16x16x32_bf16 v[156:159], v[190:193], v[116:119], v[156:159]
	ds_read_b128 v[190:193], v173 offset:17088
	s_waitcnt lgkmcnt(0)
	v_mfma_f32_16x16x32_bf16 v[156:159], v[190:193], v[108:111], v[156:159]
	ds_read_b128 v[190:193], v173 offset:17152
	s_waitcnt lgkmcnt(0)
	v_mfma_f32_16x16x32_bf16 v[156:159], v[190:193], v[80:83], v[156:159]
	ds_read_b128 v[190:193], v173 offset:17216
	s_waitcnt lgkmcnt(0)
	v_mfma_f32_16x16x32_bf16 v[156:159], v[190:193], v[76:79], v[156:159]
	ds_read_b128 v[190:193], v173 offset:17280
	s_waitcnt lgkmcnt(0)
	v_mfma_f32_16x16x32_bf16 v[156:159], v[190:193], v[40:43], v[156:159]
	ds_read_b128 v[190:193], v173 offset:17344
	s_waitcnt lgkmcnt(0)
	v_mfma_f32_16x16x32_bf16 v[156:159], v[190:193], v[36:39], v[156:159]
	ds_read_b128 v[190:193], v173 offset:25344
	s_waitcnt lgkmcnt(0)
	v_mfma_f32_16x16x32_bf16 v[124:127], v[190:193], v[124:127], 0
	ds_read_b128 v[190:193], v173 offset:25408
	s_waitcnt lgkmcnt(0)
	v_mfma_f32_16x16x32_bf16 v[120:123], v[190:193], v[120:123], v[124:127]
	s_nop 4
	ds_read_b128 v[124:127], v173 offset:25472
	s_waitcnt lgkmcnt(0)
	v_mfma_f32_16x16x32_bf16 v[116:119], v[124:127], v[116:119], v[120:123]
	s_nop 2
	ds_read_b128 v[120:123], v173 offset:25536
	s_waitcnt lgkmcnt(0)
	v_mfma_f32_16x16x32_bf16 v[108:111], v[120:123], v[108:111], v[116:119]
	s_nop 2
	ds_read_b128 v[116:119], v173 offset:25600
	s_waitcnt lgkmcnt(0)
	v_mfma_f32_16x16x32_bf16 v[80:83], v[116:119], v[80:83], v[108:111]
	s_nop 2
	ds_read_b128 v[108:111], v173 offset:25664
	s_waitcnt lgkmcnt(0)
	v_mfma_f32_16x16x32_bf16 v[76:79], v[108:111], v[76:79], v[80:83]
	s_nop 2
	ds_read_b128 v[80:83], v173 offset:25728
	s_waitcnt lgkmcnt(0)
	v_mfma_f32_16x16x32_bf16 v[40:43], v[80:83], v[40:43], v[76:79]
	s_nop 2
	ds_read_b128 v[76:79], v173 offset:25792
	s_waitcnt vmcnt(7)
	ds_write_b128 v170, v[60:63]
	s_waitcnt vmcnt(6)
	ds_write_b128 v170, v[64:67] offset:128
	s_waitcnt vmcnt(5)
	ds_write_b128 v170, v[68:71] offset:256
	s_waitcnt vmcnt(4)
	ds_write_b128 v170, v[72:75] offset:384
	global_load_dwordx4 v[60:63], v[162:163], off offset:2048
	global_load_dwordx4 v[64:67], v[162:163], off offset:2176
	global_load_dwordx4 v[68:71], v[162:163], off offset:2304
	global_load_dwordx4 v[72:75], v[162:163], off offset:2432
	s_waitcnt lgkmcnt(4)
	v_mfma_f32_16x16x32_bf16 v[36:39], v[76:79], v[36:39], v[40:43]
	s_nop 2
	v_max_f32_e32 v40, v87, v87
	v_max_f32_e32 v41, v86, v86
	v_max_f32_e32 v40, v41, v40
	v_max_f32_e32 v41, v91, v91
	v_max_f32_e32 v42, v90, v90
	v_max_f32_e32 v41, v42, v41
	v_max3_f32 v40, v84, v85, v40
	v_max3_f32 v41, v88, v89, v41
	v_max3_f32 v40, v40, s7, v41
	v_max_f32_e32 v41, v95, v95
	v_max_f32_e32 v42, v94, v94
	v_max_f32_e32 v41, v42, v41
	v_max_f32_e32 v42, v99, v99
	v_max_f32_e32 v43, v98, v98
	v_max_f32_e32 v42, v43, v42
	v_max3_f32 v41, v92, v93, v41
	v_max3_f32 v42, v96, v97, v42
	v_max3_f32 v40, v40, v41, v42
	v_max_f32_e32 v41, v103, v103
	v_max_f32_e32 v42, v102, v102
	v_max_f32_e32 v41, v42, v41
	v_max_f32_e32 v42, v107, v107
	v_max_f32_e32 v43, v106, v106
	v_max_f32_e32 v42, v43, v42
	v_max3_f32 v41, v100, v101, v41
	v_max3_f32 v42, v104, v105, v42
	v_max3_f32 v40, v40, v41, v42
	v_max_f32_e32 v41, v115, v115
	v_max_f32_e32 v42, v114, v114
	v_max_f32_e32 v41, v42, v41
	v_max_f32_e32 v42, v131, v131
	v_max_f32_e32 v43, v130, v130
	v_max_f32_e32 v42, v43, v42
	v_max3_f32 v41, v112, v113, v41
	v_max3_f32 v42, v128, v129, v42
	v_max3_f32 v40, v40, v41, v42
	v_max_f32_e32 v41, v135, v135
	v_max_f32_e32 v42, v134, v134
	v_max_f32_e32 v41, v42, v41
	v_max_f32_e32 v42, v139, v139
	v_max_f32_e32 v43, v138, v138
	v_max_f32_e32 v42, v43, v42
	v_max3_f32 v41, v132, v133, v41
	v_max3_f32 v42, v136, v137, v42
	v_max3_f32 v40, v40, v41, v42
	v_max_f32_e32 v41, v143, v143
	v_max_f32_e32 v42, v142, v142
	v_max_f32_e32 v41, v42, v41
	v_max_f32_e32 v42, v147, v147
	v_max_f32_e32 v43, v146, v146
	v_max_f32_e32 v42, v43, v42
	v_max3_f32 v41, v140, v141, v41
	v_max3_f32 v42, v144, v145, v42
	v_max3_f32 v40, v40, v41, v42
	v_max_f32_e32 v41, v151, v151
	v_max_f32_e32 v42, v150, v150
	v_max_f32_e32 v41, v42, v41
	v_max_f32_e32 v42, v155, v155
	v_max_f32_e32 v43, v154, v154
	v_max_f32_e32 v42, v43, v42
	v_max3_f32 v41, v148, v149, v41
	v_max3_f32 v42, v152, v153, v42
	v_max3_f32 v40, v40, v41, v42
	v_max_f32_e32 v41, v159, v159
	v_max_f32_e32 v42, v158, v158
	v_max_f32_e32 v41, v42, v41
	v_max_f32_e32 v42, v39, v39
	v_max_f32_e32 v43, v38, v38
	v_max_f32_e32 v42, v43, v42
	v_max3_f32 v41, v156, v157, v41
	v_max3_f32 v42, v36, v37, v42
	v_max3_f32 v40, v40, v41, v42
	ds_bpermute_b32 v41, v171, v40
	s_waitcnt lgkmcnt(0)
	s_barrier
	s_waitcnt lgkmcnt(0)
	v_max_f32_e32 v41, v41, v41
	v_max_f32_e32 v40, v40, v41
	ds_bpermute_b32 v41, v172, v40
	s_waitcnt lgkmcnt(0)
	v_max_f32_e32 v41, v41, v41
	v_max_f32_e32 v182, v40, v41
	v_sub_f32_e32 v40, v84, v182
	v_mul_f32_e32 v40, 0x3d800000, v40
	v_sub_f32_e32 v41, v85, v182
	v_mul_f32_e32 v40, 0x3fb8aa3b, v40
	v_mul_f32_e32 v41, 0x3d800000, v41
	v_exp_f32_e32 v40, v40
	v_mul_f32_e32 v41, 0x3fb8aa3b, v41
	v_exp_f32_e32 v41, v41
	v_sub_f32_e32 v85, v96, v182
	v_add_f32_e32 v42, 0, v40
	v_mul_f32_e32 v85, 0x3d800000, v85
	v_add_f32_e32 v43, v41, v42
	v_sub_f32_e32 v42, v86, v182
	v_mul_f32_e32 v42, 0x3d800000, v42
	v_mul_f32_e32 v42, 0x3fb8aa3b, v42
	v_exp_f32_e32 v42, v42
	v_mul_f32_e32 v85, 0x3fb8aa3b, v85
	v_sub_f32_e32 v36, v36, v182
	v_mul_f32_e32 v36, 0x3d800000, v36
	v_add_f32_e32 v76, v42, v43
	v_sub_f32_e32 v43, v87, v182
	v_mul_f32_e32 v43, 0x3d800000, v43
	v_mul_f32_e32 v43, 0x3fb8aa3b, v43
	v_exp_f32_e32 v43, v43
	v_mul_f32_e32 v36, 0x3fb8aa3b, v36
	v_exp_f32_e32 v195, v36
	v_sub_f32_e32 v37, v37, v182
	v_add_f32_e32 v77, v43, v76
	v_sub_f32_e32 v76, v88, v182
	v_mul_f32_e32 v76, 0x3d800000, v76
	v_mul_f32_e32 v76, 0x3fb8aa3b, v76
	v_exp_f32_e32 v76, v76
	v_exp_f32_e32 v88, v85
	v_sub_f32_e32 v85, v97, v182
	v_mul_f32_e32 v85, 0x3d800000, v85
	v_add_f32_e32 v78, v76, v77
	v_sub_f32_e32 v77, v89, v182
	v_mul_f32_e32 v77, 0x3d800000, v77
	v_mul_f32_e32 v77, 0x3fb8aa3b, v77
	v_exp_f32_e32 v77, v77
	v_mul_f32_e32 v85, 0x3fb8aa3b, v85
	v_exp_f32_e32 v89, v85
	v_sub_f32_e32 v85, v98, v182
	v_add_f32_e32 v79, v77, v78
	v_sub_f32_e32 v78, v90, v182
	v_mul_f32_e32 v78, 0x3d800000, v78
	v_mul_f32_e32 v78, 0x3fb8aa3b, v78
	v_mul_f32_e32 v85, 0x3d800000, v85
	v_exp_f32_e32 v78, v78
	v_mul_f32_e32 v85, 0x3fb8aa3b, v85
	v_exp_f32_e32 v90, v85
	v_sub_f32_e32 v85, v99, v182
	v_mul_f32_e32 v85, 0x3d800000, v85
	v_mul_f32_e32 v85, 0x3fb8aa3b, v85
	v_add_f32_e32 v80, v78, v79
	v_sub_f32_e32 v79, v91, v182
	v_exp_f32_e32 v91, v85
	v_sub_f32_e32 v85, v100, v182
	v_mul_f32_e32 v85, 0x3d800000, v85
	v_mul_f32_e32 v85, 0x3fb8aa3b, v85
	v_exp_f32_e32 v96, v85
	v_sub_f32_e32 v85, v101, v182
	v_mul_f32_e32 v85, 0x3d800000, v85
	v_mul_f32_e32 v85, 0x3fb8aa3b, v85
	v_exp_f32_e32 v97, v85
	v_sub_f32_e32 v85, v102, v182
	v_mul_f32_e32 v85, 0x3d800000, v85
	v_mul_f32_e32 v85, 0x3fb8aa3b, v85
	v_exp_f32_e32 v98, v85
	v_sub_f32_e32 v85, v103, v182
	v_mul_f32_e32 v85, 0x3d800000, v85
	v_mul_f32_e32 v85, 0x3fb8aa3b, v85
	v_exp_f32_e32 v99, v85
	v_sub_f32_e32 v85, v104, v182
	v_mul_f32_e32 v85, 0x3d800000, v85
	v_mul_f32_e32 v85, 0x3fb8aa3b, v85
	v_exp_f32_e32 v100, v85
	v_sub_f32_e32 v85, v105, v182
	v_mul_f32_e32 v85, 0x3d800000, v85
	v_mul_f32_e32 v85, 0x3fb8aa3b, v85
	v_exp_f32_e32 v101, v85
	v_sub_f32_e32 v85, v106, v182
	v_mul_f32_e32 v85, 0x3d800000, v85
	v_mul_f32_e32 v85, 0x3fb8aa3b, v85
	v_exp_f32_e32 v102, v85
	v_sub_f32_e32 v85, v107, v182
	v_mul_f32_e32 v85, 0x3d800000, v85
	v_mul_f32_e32 v85, 0x3fb8aa3b, v85
	v_exp_f32_e32 v103, v85
	v_sub_f32_e32 v85, v112, v182
	v_mul_f32_e32 v85, 0x3d800000, v85
	v_mul_f32_e32 v85, 0x3fb8aa3b, v85
	v_exp_f32_e32 v104, v85
	v_sub_f32_e32 v85, v113, v182
	v_mul_f32_e32 v85, 0x3d800000, v85
	v_mul_f32_e32 v85, 0x3fb8aa3b, v85
	v_exp_f32_e32 v105, v85
	v_sub_f32_e32 v85, v114, v182
	v_mul_f32_e32 v85, 0x3d800000, v85
	v_mul_f32_e32 v85, 0x3fb8aa3b, v85
	v_exp_f32_e32 v106, v85
	v_sub_f32_e32 v85, v115, v182
	v_mul_f32_e32 v85, 0x3d800000, v85
	v_mul_f32_e32 v85, 0x3fb8aa3b, v85
	v_exp_f32_e32 v107, v85
	v_sub_f32_e32 v85, v128, v182
	v_mul_f32_e32 v85, 0x3d800000, v85
	v_mul_f32_e32 v85, 0x3fb8aa3b, v85
	v_exp_f32_e32 v108, v85
	v_sub_f32_e32 v85, v129, v182
	v_mul_f32_e32 v85, 0x3d800000, v85
	v_mul_f32_e32 v85, 0x3fb8aa3b, v85
	v_exp_f32_e32 v109, v85
	v_sub_f32_e32 v85, v130, v182
	v_mul_f32_e32 v85, 0x3d800000, v85
	v_mul_f32_e32 v85, 0x3fb8aa3b, v85
	v_exp_f32_e32 v110, v85
	v_sub_f32_e32 v85, v131, v182
	v_mul_f32_e32 v85, 0x3d800000, v85
	v_mul_f32_e32 v85, 0x3fb8aa3b, v85
	v_exp_f32_e32 v111, v85
	v_sub_f32_e32 v85, v132, v182
	v_mul_f32_e32 v85, 0x3d800000, v85
	v_mul_f32_e32 v85, 0x3fb8aa3b, v85
	v_exp_f32_e32 v112, v85
	v_sub_f32_e32 v85, v133, v182
	v_mul_f32_e32 v85, 0x3d800000, v85
	v_mul_f32_e32 v85, 0x3fb8aa3b, v85
	v_mul_f32_e32 v79, 0x3d800000, v79
	v_exp_f32_e32 v113, v85
	v_sub_f32_e32 v85, v134, v182
	v_mul_f32_e32 v79, 0x3fb8aa3b, v79
	v_mul_f32_e32 v85, 0x3d800000, v85
	v_exp_f32_e32 v79, v79
	v_mul_f32_e32 v85, 0x3fb8aa3b, v85
	v_exp_f32_e32 v114, v85
	v_sub_f32_e32 v85, v135, v182
	v_mul_f32_e32 v85, 0x3d800000, v85
	v_mul_f32_e32 v85, 0x3fb8aa3b, v85
	v_add_f32_e32 v81, v79, v80
	v_sub_f32_e32 v80, v92, v182
	v_exp_f32_e32 v115, v85
	v_sub_f32_e32 v85, v136, v182
	v_mul_f32_e32 v80, 0x3d800000, v80
	v_mul_f32_e32 v85, 0x3d800000, v85
	v_mul_f32_e32 v80, 0x3fb8aa3b, v80
	v_mul_f32_e32 v85, 0x3fb8aa3b, v85
	v_exp_f32_e32 v80, v80
	v_exp_f32_e32 v116, v85
	v_sub_f32_e32 v85, v137, v182
	v_mul_f32_e32 v85, 0x3d800000, v85
	v_mul_f32_e32 v85, 0x3fb8aa3b, v85
	v_exp_f32_e32 v117, v85
	v_sub_f32_e32 v85, v138, v182
	v_add_f32_e32 v82, v80, v81
	v_sub_f32_e32 v81, v93, v182
	v_mul_f32_e32 v85, 0x3d800000, v85
	v_mul_f32_e32 v81, 0x3d800000, v81
	v_mul_f32_e32 v85, 0x3fb8aa3b, v85
	v_mul_f32_e32 v81, 0x3fb8aa3b, v81
	v_exp_f32_e32 v118, v85
	v_sub_f32_e32 v85, v139, v182
	v_exp_f32_e32 v81, v81
	v_mul_f32_e32 v85, 0x3d800000, v85
	v_mul_f32_e32 v85, 0x3fb8aa3b, v85
	v_exp_f32_e32 v119, v85
	v_sub_f32_e32 v85, v140, v182
	v_mul_f32_e32 v85, 0x3d800000, v85
	v_add_f32_e32 v83, v81, v82
	v_sub_f32_e32 v82, v94, v182
	v_mul_f32_e32 v85, 0x3fb8aa3b, v85
	v_mul_f32_e32 v82, 0x3d800000, v82
	v_exp_f32_e32 v120, v85
	v_sub_f32_e32 v85, v141, v182
	v_mul_f32_e32 v82, 0x3fb8aa3b, v82
	v_mul_f32_e32 v85, 0x3d800000, v85
	v_exp_f32_e32 v82, v82
	v_mul_f32_e32 v85, 0x3fb8aa3b, v85
	v_exp_f32_e32 v121, v85
	v_sub_f32_e32 v85, v142, v182
	v_mul_f32_e32 v85, 0x3d800000, v85
	v_mul_f32_e32 v85, 0x3fb8aa3b, v85
	v_add_f32_e32 v84, v82, v83
	v_sub_f32_e32 v83, v95, v182
	v_exp_f32_e32 v122, v85
	v_sub_f32_e32 v85, v143, v182
	v_mul_f32_e32 v83, 0x3d800000, v83
	v_mul_f32_e32 v85, 0x3d800000, v85
	v_mul_f32_e32 v83, 0x3fb8aa3b, v83
	v_mul_f32_e32 v85, 0x3fb8aa3b, v85
	v_exp_f32_e32 v83, v83
	v_exp_f32_e32 v123, v85
	v_sub_f32_e32 v85, v144, v182
	v_mul_f32_e32 v85, 0x3d800000, v85
	v_mul_f32_e32 v85, 0x3fb8aa3b, v85
	v_exp_f32_e32 v124, v85
	v_sub_f32_e32 v85, v145, v182
	v_add_f32_e32 v84, v83, v84
	v_mul_f32_e32 v85, 0x3d800000, v85
	v_add_f32_e32 v84, v88, v84
	v_mul_f32_e32 v85, 0x3fb8aa3b, v85
	v_add_f32_e32 v84, v89, v84
	v_exp_f32_e32 v125, v85
	v_sub_f32_e32 v85, v146, v182
	v_add_f32_e32 v84, v90, v84
	v_mul_f32_e32 v85, 0x3d800000, v85
	v_add_f32_e32 v84, v91, v84
	v_mul_f32_e32 v85, 0x3fb8aa3b, v85
	v_add_f32_e32 v84, v96, v84
	v_exp_f32_e32 v126, v85
	v_sub_f32_e32 v85, v147, v182
	v_add_f32_e32 v84, v97, v84
	v_mul_f32_e32 v85, 0x3d800000, v85
	v_add_f32_e32 v84, v98, v84
	v_mul_f32_e32 v85, 0x3fb8aa3b, v85
	v_add_f32_e32 v84, v99, v84
	v_exp_f32_e32 v127, v85
	v_sub_f32_e32 v85, v148, v182
	v_add_f32_e32 v84, v100, v84
	v_mul_f32_e32 v85, 0x3d800000, v85
	v_add_f32_e32 v84, v101, v84
	v_mul_f32_e32 v85, 0x3fb8aa3b, v85
	v_add_f32_e32 v84, v102, v84
	v_exp_f32_e32 v177, v85
	v_sub_f32_e32 v85, v149, v182
	v_add_f32_e32 v84, v103, v84
	v_mul_f32_e32 v85, 0x3d800000, v85
	v_add_f32_e32 v84, v104, v84
	v_mul_f32_e32 v85, 0x3fb8aa3b, v85
	v_add_f32_e32 v84, v105, v84
	v_exp_f32_e32 v178, v85
	v_sub_f32_e32 v85, v150, v182
	v_add_f32_e32 v84, v106, v84
	v_mul_f32_e32 v85, 0x3d800000, v85
	v_add_f32_e32 v84, v107, v84
	v_mul_f32_e32 v85, 0x3fb8aa3b, v85
	v_add_f32_e32 v84, v108, v84
	v_exp_f32_e32 v179, v85
	v_sub_f32_e32 v85, v151, v182
	v_add_f32_e32 v84, v109, v84
	v_mul_f32_e32 v85, 0x3d800000, v85
	v_add_f32_e32 v84, v110, v84
	v_mul_f32_e32 v85, 0x3fb8aa3b, v85
	v_add_f32_e32 v84, v111, v84
	v_exp_f32_e32 v180, v85
	v_sub_f32_e32 v85, v152, v182
	v_add_f32_e32 v84, v112, v84
	v_mul_f32_e32 v85, 0x3d800000, v85
	v_add_f32_e32 v84, v113, v84
	v_mul_f32_e32 v85, 0x3fb8aa3b, v85
	v_add_f32_e32 v84, v114, v84
	v_exp_f32_e32 v187, v85
	v_sub_f32_e32 v85, v153, v182
	v_add_f32_e32 v84, v115, v84
	v_mul_f32_e32 v85, 0x3d800000, v85
	v_add_f32_e32 v84, v116, v84
	v_mul_f32_e32 v85, 0x3fb8aa3b, v85
	v_add_f32_e32 v84, v117, v84
	v_exp_f32_e32 v190, v85
	v_sub_f32_e32 v85, v154, v182
	v_add_f32_e32 v84, v118, v84
	v_mul_f32_e32 v85, 0x3d800000, v85
	v_add_f32_e32 v84, v119, v84
	v_mul_f32_e32 v85, 0x3fb8aa3b, v85
	v_add_f32_e32 v84, v120, v84
	v_exp_f32_e32 v191, v85
	v_sub_f32_e32 v85, v155, v182
	v_add_f32_e32 v84, v121, v84
	v_mul_f32_e32 v85, 0x3d800000, v85
	v_add_f32_e32 v84, v122, v84
	v_mul_f32_e32 v85, 0x3fb8aa3b, v85
	v_add_f32_e32 v84, v123, v84
	v_exp_f32_e32 v192, v85
	v_sub_f32_e32 v85, v156, v182
	v_add_f32_e32 v84, v124, v84
	v_mul_f32_e32 v85, 0x3d800000, v85
	v_add_f32_e32 v84, v125, v84
	v_mul_f32_e32 v85, 0x3fb8aa3b, v85
	v_add_f32_e32 v84, v126, v84
	v_exp_f32_e32 v193, v85
	v_sub_f32_e32 v85, v157, v182
	v_add_f32_e32 v84, v127, v84
	v_mul_f32_e32 v85, 0x3d800000, v85
	v_add_f32_e32 v84, v177, v84
	v_mul_f32_e32 v85, 0x3fb8aa3b, v85
	v_add_f32_e32 v84, v178, v84
	v_exp_f32_e32 v194, v85
	v_sub_f32_e32 v85, v158, v182
	v_add_f32_e32 v84, v179, v84
	v_mul_f32_e32 v85, 0x3d800000, v85
	v_add_f32_e32 v84, v180, v84
	v_mul_f32_e32 v85, 0x3fb8aa3b, v85
	v_add_f32_e32 v84, v187, v84
	v_exp_f32_e32 v158, v85
	v_sub_f32_e32 v85, v159, v182
	v_add_f32_e32 v84, v190, v84
	v_mul_f32_e32 v85, 0x3d800000, v85
	v_add_f32_e32 v84, v191, v84
	v_mul_f32_e32 v85, 0x3fb8aa3b, v85
	v_add_f32_e32 v84, v192, v84
	v_exp_f32_e32 v159, v85
	v_add_f32_e32 v84, v193, v84
	v_add_f32_e32 v84, v194, v84
	v_add_f32_e32 v84, v158, v84
	v_cvt_pk_bf16_f32 v92, v80, v81
	v_cvt_pk_bf16_f32 v93, v82, v83
	v_cvt_pk_bf16_f32 v94, v88, v89
	v_cvt_pk_bf16_f32 v95, v90, v91
	v_cvt_pk_bf16_f32 v80, v96, v97
	v_cvt_pk_bf16_f32 v81, v98, v99
	v_cvt_pk_bf16_f32 v82, v100, v101
	ds_read_b64_tr_b16 v[88:89], v169
	ds_read_b64_tr_b16 v[96:97], v169 offset:32
	ds_read_b64_tr_b16 v[90:91], v169 offset:8448
	ds_read_b64_tr_b16 v[98:99], v169 offset:16896
	ds_read_b64_tr_b16 v[100:101], v169 offset:25344
	v_add_f32_e32 v84, v159, v84
	v_add_f32_e32 v36, v195, v84
	v_cvt_pk_bf16_f32 v84, v40, v41
	v_cvt_pk_bf16_f32 v85, v42, v43
	v_cvt_pk_bf16_f32 v86, v76, v77
	v_cvt_pk_bf16_f32 v87, v78, v79
	v_cvt_pk_bf16_f32 v83, v102, v103
	v_mul_f32_e32 v37, 0x3d800000, v37
	s_waitcnt lgkmcnt(2)
	v_mfma_f32_16x16x32_bf16 v[88:91], v[88:91], v[84:87], 0
	v_mul_f32_e32 v37, 0x3fb8aa3b, v37
	v_exp_f32_e32 v196, v37
	v_sub_f32_e32 v37, v38, v182
	s_waitcnt lgkmcnt(0)
	v_mfma_f32_16x16x32_bf16 v[152:155], v[98:101], v[92:95], v[88:91]
	ds_read_b64_tr_b16 v[98:99], v169 offset:8480
	s_nop 1
	ds_read_b64_tr_b16 v[88:89], v169 offset:16928
	ds_read_b64_tr_b16 v[90:91], v169 offset:25376
	v_mul_f32_e32 v37, 0x3d800000, v37
	v_mul_f32_e32 v37, 0x3fb8aa3b, v37
	s_waitcnt lgkmcnt(2)
	v_mfma_f32_16x16x32_bf16 v[96:99], v[96:99], v[84:87], 0
	v_cvt_pk_bf16_f32 v76, v104, v105
	v_cvt_pk_bf16_f32 v77, v106, v107
	v_exp_f32_e32 v197, v37
	s_waitcnt lgkmcnt(0)
	v_mfma_f32_16x16x32_bf16 v[88:91], v[88:91], v[92:95], v[96:99]
	s_nop 2
	ds_read_b64_tr_b16 v[96:97], v169 offset:64
	ds_read_b64_tr_b16 v[98:99], v169 offset:8512
	ds_read_b64_tr_b16 v[100:101], v169 offset:16960
	ds_read_b64_tr_b16 v[102:103], v169 offset:25408
	v_sub_f32_e32 v37, v39, v182
	v_mul_f32_e32 v37, 0x3d800000, v37
	s_waitcnt lgkmcnt(2)
	v_mfma_f32_16x16x32_bf16 v[96:99], v[96:99], v[84:87], 0
	v_mul_f32_e32 v37, 0x3fb8aa3b, v37
	v_exp_f32_e32 v198, v37
	v_add_f32_e32 v36, v196, v36
	s_waitcnt lgkmcnt(0)
	v_mfma_f32_16x16x32_bf16 v[128:131], v[100:103], v[92:95], v[96:99]
	s_nop 2
	ds_read_b64_tr_b16 v[96:97], v169 offset:96
	ds_read_b64_tr_b16 v[98:99], v169 offset:8544
	ds_read_b64_tr_b16 v[100:101], v169 offset:16992
	ds_read_b64_tr_b16 v[102:103], v169 offset:25440
	v_add_f32_e32 v36, v197, v36
	v_add_f32_e32 v36, v198, v36
	s_waitcnt lgkmcnt(2)
	v_mfma_f32_16x16x32_bf16 v[96:99], v[96:99], v[84:87], 0
	ds_bpermute_b32 v37, v171, v36
	v_cvt_pk_bf16_f32 v38, v124, v125
	v_cvt_pk_bf16_f32 v39, v126, v127
	s_waitcnt lgkmcnt(1)
	v_mfma_f32_16x16x32_bf16 v[104:107], v[100:103], v[92:95], v[96:99]
	s_nop 2
	ds_read_b64_tr_b16 v[96:97], v169 offset:128
	ds_read_b64_tr_b16 v[98:99], v169 offset:8576
	ds_read_b64_tr_b16 v[100:101], v169 offset:17024
	ds_read_b64_tr_b16 v[102:103], v169 offset:25472
	s_waitcnt lgkmcnt(4)
	v_add_f32_e32 v156, v36, v37
	v_cvt_pk_bf16_f32 v36, v120, v121
	s_waitcnt lgkmcnt(2)
	v_mfma_f32_16x16x32_bf16 v[96:99], v[96:99], v[84:87], 0
	v_cvt_pk_bf16_f32 v37, v122, v123
	v_cvt_pk_bf16_f32 v78, v108, v109
	v_cvt_pk_bf16_f32 v79, v110, v111
	s_waitcnt lgkmcnt(0)
	v_mfma_f32_16x16x32_bf16 v[148:151], v[100:103], v[92:95], v[96:99]
	s_nop 2
	ds_read_b64_tr_b16 v[96:97], v169 offset:160
	ds_read_b64_tr_b16 v[98:99], v169 offset:8608
	ds_read_b64_tr_b16 v[100:101], v169 offset:17056
	ds_read_b64_tr_b16 v[102:103], v169 offset:25504
	v_cvt_pk_bf16_f32 v40, v112, v113
	v_cvt_pk_bf16_f32 v41, v114, v115
	s_waitcnt lgkmcnt(2)
	v_mfma_f32_16x16x32_bf16 v[96:99], v[96:99], v[84:87], 0
	v_cvt_pk_bf16_f32 v42, v116, v117
	v_cvt_pk_bf16_f32 v43, v118, v119
	ds_bpermute_b32 v157, v172, v156
	s_waitcnt lgkmcnt(1)
	v_mfma_f32_16x16x32_bf16 v[120:123], v[100:103], v[92:95], v[96:99]
	s_nop 2
	ds_read_b64_tr_b16 v[96:97], v169 offset:192
	ds_read_b64_tr_b16 v[98:99], v169 offset:8640
	ds_read_b64_tr_b16 v[100:101], v169 offset:17088
	ds_read_b64_tr_b16 v[102:103], v169 offset:25536
	s_waitcnt lgkmcnt(2)
	v_mfma_f32_16x16x32_bf16 v[96:99], v[96:99], v[84:87], 0
	s_waitcnt lgkmcnt(0)
	v_mfma_f32_16x16x32_bf16 v[124:127], v[100:103], v[92:95], v[96:99]
	s_nop 5
	ds_read_b64_tr_b16 v[96:97], v169 offset:224
	ds_read_b64_tr_b16 v[98:99], v169 offset:8672
	ds_read_b64_tr_b16 v[100:101], v169 offset:17120
	ds_read_b64_tr_b16 v[102:103], v169 offset:25568
	s_waitcnt lgkmcnt(2)
	v_mfma_f32_16x16x32_bf16 v[96:99], v[96:99], v[84:87], 0
	s_waitcnt lgkmcnt(0)
	v_mfma_f32_16x16x32_bf16 v[108:111], v[100:103], v[92:95], v[96:99]
	s_nop 5
	ds_read_b64_tr_b16 v[96:97], v169 offset:256
	ds_read_b64_tr_b16 v[98:99], v169 offset:8704
	ds_read_b64_tr_b16 v[100:101], v169 offset:17152
	ds_read_b64_tr_b16 v[102:103], v169 offset:25600
	s_waitcnt lgkmcnt(2)
	v_mfma_f32_16x16x32_bf16 v[96:99], v[96:99], v[84:87], 0
	s_waitcnt lgkmcnt(0)
	v_mfma_f32_16x16x32_bf16 v[100:103], v[100:103], v[92:95], v[96:99]
	s_nop 5
	ds_read_b64_tr_b16 v[96:97], v169 offset:288
	ds_read_b64_tr_b16 v[98:99], v169 offset:8736
	ds_read_b64_tr_b16 v[112:113], v169 offset:17184
	ds_read_b64_tr_b16 v[114:115], v169 offset:25632
	s_waitcnt lgkmcnt(2)
	v_mfma_f32_16x16x32_bf16 v[96:99], v[96:99], v[84:87], 0
	s_waitcnt lgkmcnt(0)
	v_mfma_f32_16x16x32_bf16 v[112:115], v[112:115], v[92:95], v[96:99]
	s_nop 5
	ds_read_b64_tr_b16 v[96:97], v169 offset:320
	ds_read_b64_tr_b16 v[98:99], v169 offset:8768
	ds_read_b64_tr_b16 v[116:117], v169 offset:17216
	ds_read_b64_tr_b16 v[118:119], v169 offset:25664
	s_waitcnt lgkmcnt(2)
	v_mfma_f32_16x16x32_bf16 v[96:99], v[96:99], v[84:87], 0
	s_waitcnt lgkmcnt(0)
	v_mfma_f32_16x16x32_bf16 v[116:119], v[116:119], v[92:95], v[96:99]
	s_nop 5
	ds_read_b64_tr_b16 v[96:97], v169 offset:352
	ds_read_b64_tr_b16 v[98:99], v169 offset:8800
	ds_read_b64_tr_b16 v[132:133], v169 offset:17248
	ds_read_b64_tr_b16 v[134:135], v169 offset:25696
	s_waitcnt lgkmcnt(2)
	v_mfma_f32_16x16x32_bf16 v[96:99], v[96:99], v[84:87], 0
	s_waitcnt lgkmcnt(0)
	v_mfma_f32_16x16x32_bf16 v[132:135], v[132:135], v[92:95], v[96:99]
	s_nop 5
	ds_read_b64_tr_b16 v[96:97], v169 offset:384
	ds_read_b64_tr_b16 v[98:99], v169 offset:8832
	ds_read_b64_tr_b16 v[136:137], v169 offset:17280
	ds_read_b64_tr_b16 v[138:139], v169 offset:25728
	s_waitcnt lgkmcnt(2)
	v_mfma_f32_16x16x32_bf16 v[96:99], v[96:99], v[84:87], 0
	s_waitcnt lgkmcnt(0)
	v_mfma_f32_16x16x32_bf16 v[136:139], v[136:139], v[92:95], v[96:99]
	s_nop 5
	ds_read_b64_tr_b16 v[96:97], v169 offset:416
	ds_read_b64_tr_b16 v[98:99], v169 offset:8864
	ds_read_b64_tr_b16 v[140:141], v169 offset:17312
	ds_read_b64_tr_b16 v[142:143], v169 offset:25760
	s_waitcnt lgkmcnt(2)
	v_mfma_f32_16x16x32_bf16 v[96:99], v[96:99], v[84:87], 0
	s_waitcnt lgkmcnt(0)
	v_mfma_f32_16x16x32_bf16 v[140:143], v[140:143], v[92:95], v[96:99]
	s_nop 5
	ds_read_b64_tr_b16 v[96:97], v169 offset:448
	ds_read_b64_tr_b16 v[98:99], v169 offset:8896
	ds_read_b64_tr_b16 v[144:145], v169 offset:17344
	ds_read_b64_tr_b16 v[146:147], v169 offset:25792
	s_waitcnt lgkmcnt(2)
	v_mfma_f32_16x16x32_bf16 v[96:99], v[96:99], v[84:87], 0
	s_waitcnt lgkmcnt(0)
	v_mfma_f32_16x16x32_bf16 v[144:147], v[144:147], v[92:95], v[96:99]
	s_nop 5
	ds_read_b64_tr_b16 v[96:97], v169 offset:480
	ds_read_b64_tr_b16 v[98:99], v169 offset:8928
	ds_read_b64_tr_b16 v[200:201], v169 offset:17376
	ds_read_b64_tr_b16 v[202:203], v169 offset:25824
	s_waitcnt vmcnt(7)
	ds_write_b128 v168, v[44:47]
	s_waitcnt vmcnt(6)
	ds_write_b128 v168, v[48:51] offset:128
	s_waitcnt vmcnt(5)
	ds_write_b128 v168, v[52:55] offset:256
	s_waitcnt vmcnt(4)
	ds_write_b128 v168, v[56:59] offset:384
	global_load_dwordx4 v[44:47], v[160:161], off offset:2048
	global_load_dwordx4 v[48:51], v[160:161], off offset:2176
	global_load_dwordx4 v[52:55], v[160:161], off offset:2304
	global_load_dwordx4 v[56:59], v[160:161], off offset:2432
	s_waitcnt lgkmcnt(6)
	v_mfma_f32_16x16x32_bf16 v[84:87], v[96:99], v[84:87], 0
	s_waitcnt lgkmcnt(0)
	s_barrier
	s_waitcnt lgkmcnt(4)
	v_mfma_f32_16x16x32_bf16 v[96:99], v[200:203], v[92:95], v[84:87]
	s_nop 4
	ds_read_b64_tr_b16 v[204:205], v3
	ds_read_b64_tr_b16 v[206:207], v3 offset:8448
	ds_read_b64_tr_b16 v[208:209], v3 offset:32
	ds_read_b64_tr_b16 v[210:211], v3 offset:8480
	ds_read_b64_tr_b16 v[218:219], v3 offset:16928
	ds_read_b64_tr_b16 v[220:221], v3 offset:25376
	ds_read_b64_tr_b16 v[224:225], v3 offset:64
	ds_read_b64_tr_b16 v[226:227], v3 offset:8512
	ds_read_b64_tr_b16 v[228:229], v3 offset:16960
	ds_read_b64_tr_b16 v[230:231], v3 offset:25408
	ds_read_b64_tr_b16 v[232:233], v3 offset:96
	ds_read_b64_tr_b16 v[234:235], v3 offset:8544
	ds_read_b64_tr_b16 v[236:237], v3 offset:16992
	ds_read_b64_tr_b16 v[238:239], v3 offset:25440
	ds_read_b64_tr_b16 v[240:241], v3 offset:128
	ds_read_b64_tr_b16 v[242:243], v3 offset:8576
	s_waitcnt lgkmcnt(14)
	v_mfma_f32_16x16x32_bf16 v[84:87], v[204:207], v[80:83], v[152:155]
	ds_read_b64_tr_b16 v[204:205], v3 offset:17024
	ds_read_b64_tr_b16 v[206:207], v3 offset:25472
	s_waitcnt lgkmcnt(14)
	v_mfma_f32_16x16x32_bf16 v[88:91], v[208:211], v[80:83], v[88:91]
	ds_read_b64_tr_b16 v[208:209], v3 offset:160
	ds_read_b64_tr_b16 v[210:211], v3 offset:8608
	s_waitcnt lgkmcnt(14)
	v_mfma_f32_16x16x32_bf16 v[92:95], v[218:221], v[76:79], v[88:91]
	ds_read_b64_tr_b16 v[218:219], v3 offset:17056
	ds_read_b64_tr_b16 v[220:221], v3 offset:25504
	s_waitcnt lgkmcnt(14)
	v_mfma_f32_16x16x32_bf16 v[88:91], v[224:227], v[80:83], v[128:131]
	ds_read_b64_tr_b16 v[224:225], v3 offset:192
	ds_read_b64_tr_b16 v[226:227], v3 offset:8640
	s_waitcnt lgkmcnt(14)
	v_mfma_f32_16x16x32_bf16 v[88:91], v[228:231], v[76:79], v[88:91]
	ds_read_b64_tr_b16 v[228:229], v3 offset:17088
	ds_read_b64_tr_b16 v[230:231], v3 offset:25536
	s_waitcnt lgkmcnt(14)
	v_mfma_f32_16x16x32_bf16 v[104:107], v[232:235], v[80:83], v[104:107]
	ds_read_b64_tr_b16 v[232:233], v3 offset:224
	ds_read_b64_tr_b16 v[234:235], v3 offset:8672
	s_waitcnt lgkmcnt(14)
	v_mfma_f32_16x16x32_bf16 v[128:131], v[236:239], v[76:79], v[104:107]
	ds_read_b64_tr_b16 v[236:237], v3 offset:17120
	ds_read_b64_tr_b16 v[238:239], v3 offset:25568
	s_waitcnt lgkmcnt(14)
	v_mfma_f32_16x16x32_bf16 v[104:107], v[240:243], v[80:83], v[148:151]
	ds_read_b64_tr_b16 v[240:241], v3 offset:256
	ds_read_b64_tr_b16 v[242:243], v3 offset:8704
	s_waitcnt lgkmcnt(14)
	v_mfma_f32_16x16x32_bf16 v[104:107], v[204:207], v[76:79], v[104:107]
	ds_read_b64_tr_b16 v[204:205], v3 offset:17152
	ds_read_b64_tr_b16 v[206:207], v3 offset:25600
	s_waitcnt lgkmcnt(14)
	v_mfma_f32_16x16x32_bf16 v[120:123], v[208:211], v[80:83], v[120:123]
	ds_read_b64_tr_b16 v[208:209], v3 offset:288
	ds_read_b64_tr_b16 v[210:211], v3 offset:8736
	s_waitcnt lgkmcnt(14)
	v_mfma_f32_16x16x32_bf16 v[120:123], v[218:221], v[76:79], v[120:123]
	ds_read_b64_tr_b16 v[218:219], v3 offset:17184
	ds_read_b64_tr_b16 v[220:221], v3 offset:25632
	s_waitcnt lgkmcnt(14)
	v_mfma_f32_16x16x32_bf16 v[124:127], v[224:227], v[80:83], v[124:127]
	ds_read_b64_tr_b16 v[224:225], v3 offset:320
	ds_read_b64_tr_b16 v[226:227], v3 offset:8768
	s_waitcnt lgkmcnt(14)
	v_mfma_f32_16x16x32_bf16 v[124:127], v[228:231], v[76:79], v[124:127]
	ds_read_b64_tr_b16 v[228:229], v3 offset:17216
	ds_read_b64_tr_b16 v[230:231], v3 offset:25664
	s_waitcnt lgkmcnt(14)
	v_mfma_f32_16x16x32_bf16 v[108:111], v[232:235], v[80:83], v[108:111]
	ds_read_b64_tr_b16 v[232:233], v3 offset:352
	ds_read_b64_tr_b16 v[234:235], v3 offset:8800
	s_waitcnt lgkmcnt(14)
	v_mfma_f32_16x16x32_bf16 v[108:111], v[236:239], v[76:79], v[108:111]
	ds_read_b64_tr_b16 v[236:237], v3 offset:17248
	ds_read_b64_tr_b16 v[238:239], v3 offset:25696
	s_waitcnt lgkmcnt(14)
	v_mfma_f32_16x16x32_bf16 v[100:103], v[240:243], v[80:83], v[100:103]
	ds_read_b64_tr_b16 v[240:241], v3 offset:384
	ds_read_b64_tr_b16 v[242:243], v3 offset:8832
	s_waitcnt lgkmcnt(14)
	v_mfma_f32_16x16x32_bf16 v[100:103], v[204:207], v[76:79], v[100:103]
	ds_read_b64_tr_b16 v[204:205], v3 offset:17280
	ds_read_b64_tr_b16 v[206:207], v3 offset:25728
	s_waitcnt lgkmcnt(14)
	v_mfma_f32_16x16x32_bf16 v[112:115], v[208:211], v[80:83], v[112:115]
	ds_read_b64_tr_b16 v[208:209], v3 offset:416
	ds_read_b64_tr_b16 v[210:211], v3 offset:8864
	s_waitcnt lgkmcnt(14)
	v_mfma_f32_16x16x32_bf16 v[112:115], v[218:221], v[76:79], v[112:115]
	ds_read_b64_tr_b16 v[218:219], v3 offset:17312
	ds_read_b64_tr_b16 v[220:221], v3 offset:25760
	s_waitcnt lgkmcnt(14)
	v_mfma_f32_16x16x32_bf16 v[116:119], v[224:227], v[80:83], v[116:119]
	ds_read_b64_tr_b16 v[224:225], v3 offset:448
	ds_read_b64_tr_b16 v[226:227], v3 offset:8896
	s_waitcnt lgkmcnt(14)
	v_mfma_f32_16x16x32_bf16 v[116:119], v[228:231], v[76:79], v[116:119]
	ds_read_b64_tr_b16 v[228:229], v3 offset:17344
	ds_read_b64_tr_b16 v[230:231], v3 offset:25792
	s_waitcnt lgkmcnt(14)
	v_mfma_f32_16x16x32_bf16 v[132:135], v[232:235], v[80:83], v[132:135]
	ds_read_b64_tr_b16 v[232:233], v3 offset:16896
	ds_read_b64_tr_b16 v[234:235], v3 offset:25344
	s_waitcnt lgkmcnt(14)
	v_mfma_f32_16x16x32_bf16 v[132:135], v[236:239], v[76:79], v[132:135]
	s_waitcnt lgkmcnt(12)
	v_mfma_f32_16x16x32_bf16 v[136:139], v[240:243], v[80:83], v[136:139]
	s_waitcnt lgkmcnt(10)
	v_mfma_f32_16x16x32_bf16 v[136:139], v[204:207], v[76:79], v[136:139]
	s_waitcnt lgkmcnt(8)
	v_mfma_f32_16x16x32_bf16 v[140:143], v[208:211], v[80:83], v[140:143]
	s_waitcnt lgkmcnt(6)
	v_mfma_f32_16x16x32_bf16 v[140:143], v[218:221], v[76:79], v[140:143]
	s_waitcnt lgkmcnt(4)
	v_mfma_f32_16x16x32_bf16 v[144:147], v[224:227], v[80:83], v[144:147]
	s_waitcnt lgkmcnt(2)
	v_mfma_f32_16x16x32_bf16 v[144:147], v[228:231], v[76:79], v[144:147]
	ds_read_b64_tr_b16 v[152:153], v3 offset:480
	ds_read_b64_tr_b16 v[154:155], v3 offset:8928
	ds_read_b64_tr_b16 v[148:149], v3 offset:17376
	ds_read_b64_tr_b16 v[150:151], v3 offset:25824
	s_waitcnt vmcnt(7)
	ds_write_b128 v170, v[60:63]
	s_waitcnt vmcnt(6)
	ds_write_b128 v170, v[64:67] offset:128
	s_waitcnt vmcnt(5)
	ds_write_b128 v170, v[68:71] offset:256
	s_waitcnt vmcnt(4)
	ds_write_b128 v170, v[72:75] offset:384
	s_waitcnt lgkmcnt(0)
	s_waitcnt lgkmcnt(8)
	v_mfma_f32_16x16x32_bf16 v[84:87], v[232:235], v[76:79], v[84:87]
	s_barrier
	ds_read_b64_tr_b16 v[204:205], v169
	ds_read_b64_tr_b16 v[206:207], v169 offset:8448
	ds_read_b64_tr_b16 v[208:209], v169 offset:16896
	ds_read_b64_tr_b16 v[210:211], v169 offset:25344
	ds_read_b64_tr_b16 v[218:219], v169 offset:32
	ds_read_b64_tr_b16 v[220:221], v169 offset:8480
	ds_read_b64_tr_b16 v[224:225], v169 offset:16928
	ds_read_b64_tr_b16 v[226:227], v169 offset:25376
	ds_read_b64_tr_b16 v[228:229], v169 offset:64
	ds_read_b64_tr_b16 v[230:231], v169 offset:8512
	ds_read_b64_tr_b16 v[232:233], v169 offset:16960
	ds_read_b64_tr_b16 v[234:235], v169 offset:25408
	ds_read_b64_tr_b16 v[236:237], v169 offset:96
	ds_read_b64_tr_b16 v[238:239], v169 offset:8544
	ds_read_b64_tr_b16 v[240:241], v169 offset:16992
	ds_read_b64_tr_b16 v[242:243], v169 offset:25440
	s_waitcnt lgkmcnt(14)
	v_mfma_f32_16x16x32_bf16 v[60:63], v[204:207], v[40:43], v[84:87]
	ds_read_b64_tr_b16 v[204:205], v169 offset:128
	ds_read_b64_tr_b16 v[206:207], v169 offset:8576
	s_waitcnt lgkmcnt(14)
	v_mfma_f32_16x16x32_bf16 v[60:63], v[208:211], v[36:39], v[60:63]
	ds_read_b64_tr_b16 v[208:209], v169 offset:17024
	ds_read_b64_tr_b16 v[210:211], v169 offset:25472
	s_waitcnt lgkmcnt(14)
	v_mfma_f32_16x16x32_bf16 v[64:67], v[218:221], v[40:43], v[92:95]
	ds_read_b64_tr_b16 v[218:219], v169 offset:160
	ds_read_b64_tr_b16 v[220:221], v169 offset:8608
	s_waitcnt lgkmcnt(14)
	v_mfma_f32_16x16x32_bf16 v[64:67], v[224:227], v[36:39], v[64:67]
	ds_read_b64_tr_b16 v[224:225], v169 offset:17056
	ds_read_b64_tr_b16 v[226:227], v169 offset:25504
	v_mfma_f32_16x16x32_bf16 v[80:83], v[152:155], v[80:83], v[96:99]
	v_mov_b32_e32 v155, 0xa00000
	s_waitcnt lgkmcnt(14)
	v_mfma_f32_16x16x32_bf16 v[68:71], v[228:231], v[40:43], v[88:91]
	ds_read_b64_tr_b16 v[228:229], v169 offset:192
	ds_read_b64_tr_b16 v[230:231], v169 offset:8640
	v_mfma_f32_16x16x32_bf16 v[76:79], v[148:151], v[76:79], v[80:83]
	s_waitcnt lgkmcnt(14)
	v_mfma_f32_16x16x32_bf16 v[68:71], v[232:235], v[36:39], v[68:71]
	ds_read_b64_tr_b16 v[232:233], v169 offset:17088
	ds_read_b64_tr_b16 v[234:235], v169 offset:25536
	s_waitcnt lgkmcnt(14)
	v_mfma_f32_16x16x32_bf16 v[72:75], v[236:239], v[40:43], v[128:131]
	ds_read_b64_tr_b16 v[236:237], v169 offset:224
	ds_read_b64_tr_b16 v[238:239], v169 offset:8672
	s_waitcnt lgkmcnt(14)
	v_mfma_f32_16x16x32_bf16 v[128:131], v[240:243], v[36:39], v[72:75]
	ds_read_b64_tr_b16 v[240:241], v169 offset:17120
	ds_read_b64_tr_b16 v[242:243], v169 offset:25568
	s_waitcnt lgkmcnt(14)
	v_mfma_f32_16x16x32_bf16 v[72:75], v[204:207], v[40:43], v[104:107]
	ds_read_b64_tr_b16 v[204:205], v169 offset:256
	ds_read_b64_tr_b16 v[206:207], v169 offset:8704
	s_waitcnt lgkmcnt(14)
	v_mfma_f32_16x16x32_bf16 v[72:75], v[208:211], v[36:39], v[72:75]
	ds_read_b64_tr_b16 v[208:209], v169 offset:17152
	ds_read_b64_tr_b16 v[210:211], v169 offset:25600
	s_waitcnt lgkmcnt(14)
	v_mfma_f32_16x16x32_bf16 v[80:83], v[218:221], v[40:43], v[120:123]
	ds_read_b64_tr_b16 v[218:219], v169 offset:288
	ds_read_b64_tr_b16 v[220:221], v169 offset:8736
	s_waitcnt lgkmcnt(14)
	v_mfma_f32_16x16x32_bf16 v[80:83], v[224:227], v[36:39], v[80:83]
	ds_read_b64_tr_b16 v[224:225], v169 offset:17184
	ds_read_b64_tr_b16 v[226:227], v169 offset:25632
	s_waitcnt lgkmcnt(14)
	v_mfma_f32_16x16x32_bf16 v[84:87], v[228:231], v[40:43], v[124:127]
	ds_read_b64_tr_b16 v[228:229], v169 offset:320
	ds_read_b64_tr_b16 v[230:231], v169 offset:8768
	s_waitcnt lgkmcnt(14)
	v_mfma_f32_16x16x32_bf16 v[84:87], v[232:235], v[36:39], v[84:87]
	ds_read_b64_tr_b16 v[232:233], v169 offset:17216
	ds_read_b64_tr_b16 v[234:235], v169 offset:25664
	s_waitcnt lgkmcnt(14)
	v_mfma_f32_16x16x32_bf16 v[88:91], v[236:239], v[40:43], v[108:111]
	ds_read_b64_tr_b16 v[236:237], v169 offset:352
	ds_read_b64_tr_b16 v[238:239], v169 offset:8800
	s_waitcnt lgkmcnt(14)
	v_mfma_f32_16x16x32_bf16 v[120:123], v[240:243], v[36:39], v[88:91]
	ds_read_b64_tr_b16 v[240:241], v169 offset:17248
	ds_read_b64_tr_b16 v[242:243], v169 offset:25696
	s_waitcnt lgkmcnt(14)
	v_mfma_f32_16x16x32_bf16 v[88:91], v[204:207], v[40:43], v[100:103]
	ds_read_b64_tr_b16 v[204:205], v169 offset:384
	ds_read_b64_tr_b16 v[206:207], v169 offset:8832
	s_waitcnt lgkmcnt(14)
	v_mfma_f32_16x16x32_bf16 v[88:91], v[208:211], v[36:39], v[88:91]
	ds_read_b64_tr_b16 v[208:209], v169 offset:17280
	ds_read_b64_tr_b16 v[210:211], v169 offset:25728
	s_waitcnt lgkmcnt(14)
	v_mfma_f32_16x16x32_bf16 v[92:95], v[218:221], v[40:43], v[112:115]
	ds_read_b64_tr_b16 v[218:219], v169 offset:416
	ds_read_b64_tr_b16 v[220:221], v169 offset:8864
	s_waitcnt lgkmcnt(14)
	v_mfma_f32_16x16x32_bf16 v[92:95], v[224:227], v[36:39], v[92:95]
	ds_read_b64_tr_b16 v[224:225], v169 offset:17312
	ds_read_b64_tr_b16 v[226:227], v169 offset:25760
	s_waitcnt lgkmcnt(14)
	v_mfma_f32_16x16x32_bf16 v[96:99], v[228:231], v[40:43], v[116:119]
	ds_read_b64_tr_b16 v[228:229], v169 offset:448
	ds_read_b64_tr_b16 v[230:231], v169 offset:8896
	s_waitcnt lgkmcnt(14)
	v_mfma_f32_16x16x32_bf16 v[96:99], v[232:235], v[36:39], v[96:99]
	ds_read_b64_tr_b16 v[232:233], v169 offset:17344
	ds_read_b64_tr_b16 v[234:235], v169 offset:25792
	s_waitcnt lgkmcnt(14)
	v_mfma_f32_16x16x32_bf16 v[100:103], v[236:239], v[40:43], v[132:135]
	ds_read_b64_tr_b16 v[236:237], v169 offset:480
	ds_read_b64_tr_b16 v[238:239], v169 offset:8928
	s_waitcnt lgkmcnt(14)
	v_mfma_f32_16x16x32_bf16 v[112:115], v[240:243], v[36:39], v[100:103]
	s_waitcnt lgkmcnt(12)
	v_mfma_f32_16x16x32_bf16 v[100:103], v[204:207], v[40:43], v[136:139]
	s_waitcnt lgkmcnt(10)
	v_mfma_f32_16x16x32_bf16 v[100:103], v[208:211], v[36:39], v[100:103]
	v_add_u32_e32 v136, s14, v1
	v_add_f32_e32 v1, v156, v157
	s_waitcnt lgkmcnt(8)
	v_mfma_f32_16x16x32_bf16 v[104:107], v[218:221], v[40:43], v[140:143]
	v_ashrrev_i32_e32 v137, 31, v136
	s_waitcnt lgkmcnt(6)
	v_mfma_f32_16x16x32_bf16 v[104:107], v[224:227], v[36:39], v[104:107]
	s_waitcnt lgkmcnt(4)
	v_mfma_f32_16x16x32_bf16 v[108:111], v[228:231], v[40:43], v[144:147]
	s_waitcnt lgkmcnt(2)
	v_mfma_f32_16x16x32_bf16 v[108:111], v[232:235], v[36:39], v[108:111]
	ds_read_b64_tr_b16 v[124:125], v169 offset:17376
	ds_read_b64_tr_b16 v[126:127], v169 offset:25824
	s_waitcnt vmcnt(3)
	ds_write_b128 v168, v[44:47]
	s_waitcnt vmcnt(2)
	ds_write_b128 v168, v[48:51] offset:128
	s_waitcnt vmcnt(1)
	ds_write_b128 v168, v[52:55] offset:256
	s_waitcnt vmcnt(0)
	ds_write_b128 v168, v[56:59] offset:384
	s_waitcnt lgkmcnt(0)
	s_waitcnt lgkmcnt(6)
	v_mfma_f32_16x16x32_bf16 v[40:43], v[236:239], v[40:43], v[76:79]
	s_barrier
	v_cvt_pk_bf16_f32 v52, v177, v178
	s_waitcnt lgkmcnt(4)
	v_mfma_f32_16x16x32_bf16 v[36:39], v[124:127], v[36:39], v[40:43]
	s_nop 3
	ds_read_b64_tr_b16 v[204:205], v3
	ds_read_b64_tr_b16 v[206:207], v3 offset:8448
	ds_read_b64_tr_b16 v[208:209], v3 offset:16896
	ds_read_b64_tr_b16 v[210:211], v3 offset:25344
	ds_read_b64_tr_b16 v[218:219], v3 offset:32
	ds_read_b64_tr_b16 v[220:221], v3 offset:8480
	ds_read_b64_tr_b16 v[224:225], v3 offset:16928
	ds_read_b64_tr_b16 v[226:227], v3 offset:25376
	ds_read_b64_tr_b16 v[228:229], v3 offset:64
	ds_read_b64_tr_b16 v[230:231], v3 offset:8512
	ds_read_b64_tr_b16 v[232:233], v3 offset:16960
	ds_read_b64_tr_b16 v[234:235], v3 offset:25408
	ds_read_b64_tr_b16 v[236:237], v3 offset:96
	ds_read_b64_tr_b16 v[238:239], v3 offset:8544
	ds_read_b64_tr_b16 v[240:241], v3 offset:16992
	ds_read_b64_tr_b16 v[242:243], v3 offset:25440
	v_cvt_pk_bf16_f32 v53, v179, v180
	v_cvt_pk_bf16_f32 v54, v187, v190
	v_cvt_pk_bf16_f32 v55, v191, v192
	v_cvt_pk_bf16_f32 v48, v193, v194
	v_cvt_pk_bf16_f32 v49, v158, v159
	s_waitcnt lgkmcnt(14)
	v_mfma_f32_16x16x32_bf16 v[40:43], v[204:207], v[52:55], v[60:63]
	ds_read_b64_tr_b16 v[204:205], v3 offset:128
	ds_read_b64_tr_b16 v[206:207], v3 offset:8576
	v_cvt_pk_bf16_f32 v50, v195, v196
	v_cvt_pk_bf16_f32 v51, v197, v198
	s_waitcnt lgkmcnt(14)
	v_mfma_f32_16x16x32_bf16 v[44:47], v[208:211], v[48:51], v[40:43]
	ds_read_b64_tr_b16 v[208:209], v3 offset:17024
	ds_read_b64_tr_b16 v[210:211], v3 offset:25472
	s_waitcnt lgkmcnt(14)
	v_mfma_f32_16x16x32_bf16 v[56:59], v[218:221], v[52:55], v[64:67]
	ds_read_b64_tr_b16 v[218:219], v3 offset:160
	ds_read_b64_tr_b16 v[220:221], v3 offset:8608
	s_waitcnt lgkmcnt(14)
	v_mfma_f32_16x16x32_bf16 v[40:43], v[224:227], v[48:51], v[56:59]
	ds_read_b64_tr_b16 v[224:225], v3 offset:17056
	ds_read_b64_tr_b16 v[226:227], v3 offset:25504
	s_waitcnt lgkmcnt(14)
	v_mfma_f32_16x16x32_bf16 v[56:59], v[228:231], v[52:55], v[68:71]
	ds_read_b64_tr_b16 v[228:229], v3 offset:192
	ds_read_b64_tr_b16 v[230:231], v3 offset:8640
	s_waitcnt lgkmcnt(14)
	v_mfma_f32_16x16x32_bf16 v[56:59], v[232:235], v[48:51], v[56:59]
	ds_read_b64_tr_b16 v[232:233], v3 offset:17088
	ds_read_b64_tr_b16 v[234:235], v3 offset:25536
	s_waitcnt lgkmcnt(14)
	v_mfma_f32_16x16x32_bf16 v[60:63], v[236:239], v[52:55], v[128:131]
	ds_read_b64_tr_b16 v[236:237], v3 offset:224
	ds_read_b64_tr_b16 v[238:239], v3 offset:8672
	s_waitcnt lgkmcnt(14)
	v_mfma_f32_16x16x32_bf16 v[60:63], v[240:243], v[48:51], v[60:63]
	ds_read_b64_tr_b16 v[240:241], v3 offset:17120
	ds_read_b64_tr_b16 v[242:243], v3 offset:25568
	s_waitcnt lgkmcnt(14)
	v_mfma_f32_16x16x32_bf16 v[64:67], v[204:207], v[52:55], v[72:75]
	ds_read_b64_tr_b16 v[204:205], v3 offset:256
	ds_read_b64_tr_b16 v[206:207], v3 offset:8704
	s_waitcnt lgkmcnt(14)
	v_mfma_f32_16x16x32_bf16 v[64:67], v[208:211], v[48:51], v[64:67]
	ds_read_b64_tr_b16 v[208:209], v3 offset:17152
	ds_read_b64_tr_b16 v[210:211], v3 offset:25600
	s_waitcnt lgkmcnt(14)
	v_mfma_f32_16x16x32_bf16 v[68:71], v[218:221], v[52:55], v[80:83]
	ds_read_b64_tr_b16 v[218:219], v3 offset:288
	ds_read_b64_tr_b16 v[220:221], v3 offset:8736
	s_waitcnt lgkmcnt(14)
	v_mfma_f32_16x16x32_bf16 v[68:71], v[224:227], v[48:51], v[68:71]
	ds_read_b64_tr_b16 v[224:225], v3 offset:17184
	ds_read_b64_tr_b16 v[226:227], v3 offset:25632
	s_waitcnt lgkmcnt(14)
	v_mfma_f32_16x16x32_bf16 v[72:75], v[228:231], v[52:55], v[84:87]
	ds_read_b64_tr_b16 v[228:229], v3 offset:320
	ds_read_b64_tr_b16 v[230:231], v3 offset:8768
	s_waitcnt lgkmcnt(14)
	v_mfma_f32_16x16x32_bf16 v[72:75], v[232:235], v[48:51], v[72:75]
	ds_read_b64_tr_b16 v[232:233], v3 offset:17216
	ds_read_b64_tr_b16 v[234:235], v3 offset:25664
	s_waitcnt lgkmcnt(14)
	v_mfma_f32_16x16x32_bf16 v[76:79], v[236:239], v[52:55], v[120:123]
	ds_read_b64_tr_b16 v[236:237], v3 offset:352
	ds_read_b64_tr_b16 v[238:239], v3 offset:8800
	s_waitcnt lgkmcnt(14)
	v_mfma_f32_16x16x32_bf16 v[76:79], v[240:243], v[48:51], v[76:79]
	ds_read_b64_tr_b16 v[240:241], v3 offset:17248
	ds_read_b64_tr_b16 v[242:243], v3 offset:25696
	s_waitcnt lgkmcnt(14)
	v_mfma_f32_16x16x32_bf16 v[80:83], v[204:207], v[52:55], v[88:91]
	ds_read_b64_tr_b16 v[204:205], v3 offset:384
	ds_read_b64_tr_b16 v[206:207], v3 offset:8832
	s_waitcnt lgkmcnt(14)
	v_mfma_f32_16x16x32_bf16 v[80:83], v[208:211], v[48:51], v[80:83]
	ds_read_b64_tr_b16 v[208:209], v3 offset:17280
	ds_read_b64_tr_b16 v[210:211], v3 offset:25728
	s_waitcnt lgkmcnt(14)
	v_mfma_f32_16x16x32_bf16 v[84:87], v[218:221], v[52:55], v[92:95]
	ds_read_b64_tr_b16 v[218:219], v3 offset:416
	ds_read_b64_tr_b16 v[220:221], v3 offset:8864
	s_waitcnt lgkmcnt(14)
	v_mfma_f32_16x16x32_bf16 v[84:87], v[224:227], v[48:51], v[84:87]
	ds_read_b64_tr_b16 v[224:225], v3 offset:17312
	ds_read_b64_tr_b16 v[226:227], v3 offset:25760
	s_waitcnt lgkmcnt(14)
	v_mfma_f32_16x16x32_bf16 v[88:91], v[228:231], v[52:55], v[96:99]
	ds_read_b64_tr_b16 v[228:229], v3 offset:448
	ds_read_b64_tr_b16 v[230:231], v3 offset:8896
	s_waitcnt lgkmcnt(14)
	v_mfma_f32_16x16x32_bf16 v[88:91], v[232:235], v[48:51], v[88:91]
	ds_read_b64_tr_b16 v[232:233], v3 offset:17344
	ds_read_b64_tr_b16 v[234:235], v3 offset:25792
	s_waitcnt lgkmcnt(14)
	v_mfma_f32_16x16x32_bf16 v[92:95], v[236:239], v[52:55], v[112:115]
	ds_read_b64_tr_b16 v[236:237], v3 offset:480
	ds_read_b64_tr_b16 v[238:239], v3 offset:8928
	s_waitcnt lgkmcnt(14)
	v_mfma_f32_16x16x32_bf16 v[92:95], v[240:243], v[48:51], v[92:95]
	ds_read_b64_tr_b16 v[240:241], v3 offset:17376
	ds_read_b64_tr_b16 v[242:243], v3 offset:25824
	s_waitcnt lgkmcnt(14)
	v_mfma_f32_16x16x32_bf16 v[96:99], v[204:207], v[52:55], v[100:103]
	s_waitcnt lgkmcnt(12)
	v_mfma_f32_16x16x32_bf16 v[96:99], v[208:211], v[48:51], v[96:99]
	s_waitcnt lgkmcnt(10)
	v_mfma_f32_16x16x32_bf16 v[100:103], v[218:221], v[52:55], v[104:107]
	s_waitcnt lgkmcnt(8)
	v_mfma_f32_16x16x32_bf16 v[100:103], v[224:227], v[48:51], v[100:103]
	s_waitcnt lgkmcnt(6)
	v_mfma_f32_16x16x32_bf16 v[104:107], v[228:231], v[52:55], v[108:111]
	s_waitcnt lgkmcnt(4)
	v_mfma_f32_16x16x32_bf16 v[104:107], v[232:235], v[48:51], v[104:107]
	s_waitcnt lgkmcnt(2)
	v_mfma_f32_16x16x32_bf16 v[36:39], v[236:239], v[52:55], v[36:39]
	s_waitcnt lgkmcnt(0)
	v_mfma_f32_16x16x32_bf16 v[36:39], v[240:243], v[48:51], v[36:39]
	v_div_scale_f32 v48, s[12:13], v1, v1, 1.0
	v_rcp_f32_e32 v49, v48
	v_readlane_b32 s12, v253, 35
	v_readlane_b32 s13, v253, 36
	s_add_u32 s10, s12, s10
	v_fma_f32 v50, -v48, v49, 1.0
	v_fmac_f32_e32 v49, v50, v49
	v_div_scale_f32 v50, vcc, 1.0, v1, 1.0
	v_mul_f32_e32 v51, v50, v49
	v_fma_f32 v52, -v48, v51, v50
	v_fmac_f32_e32 v51, v52, v49
	v_fma_f32 v48, -v48, v51, v50
	v_div_fmas_f32 v48, v48, v49, v51
	s_addc_u32 s11, s13, s11
	v_lshlrev_b64 v[50:51], 11, v[136:137]
	v_lshl_add_u64 v[50:51], s[10:11], 0, v[50:51]
	v_div_fixup_f32 v48, v48, v1, 1.0
	v_mad_i64_i32 v[50:51], s[12:13], s6, v155, v[50:51]
	v_lshl_add_u64 v[50:51], v[50:51], 0, s[8:9]
	v_mov_b32_e32 v1, v181
	v_pk_mul_f32 v[40:41], v[48:49], v[40:41] op_sel_hi:[0,1]
	v_pk_mul_f32 v[42:43], v[48:49], v[42:43] op_sel_hi:[0,1]
	v_lshl_add_u64 v[50:51], v[50:51], 0, v[0:1]
	v_cvt_pk_bf16_f32 v40, v40, v41
	v_cvt_pk_bf16_f32 v41, v42, v43
	global_store_dwordx2 v[50:51], v[40:41], off offset:32
	v_pk_mul_f32 v[40:41], v[48:49], v[56:57] op_sel_hi:[0,1]
	v_pk_mul_f32 v[42:43], v[48:49], v[58:59] op_sel_hi:[0,1]
	v_cvt_pk_bf16_f32 v40, v40, v41
	v_cvt_pk_bf16_f32 v41, v42, v43
	global_store_dwordx2 v[50:51], v[40:41], off offset:64
	v_pk_mul_f32 v[40:41], v[48:49], v[60:61] op_sel_hi:[0,1]
	v_pk_mul_f32 v[42:43], v[48:49], v[62:63] op_sel_hi:[0,1]
	v_cvt_pk_bf16_f32 v40, v40, v41
	v_cvt_pk_bf16_f32 v41, v42, v43
	global_store_dwordx2 v[50:51], v[40:41], off offset:96
	v_pk_mul_f32 v[40:41], v[48:49], v[64:65] op_sel_hi:[0,1]
	v_pk_mul_f32 v[42:43], v[48:49], v[66:67] op_sel_hi:[0,1]
	v_cvt_pk_bf16_f32 v40, v40, v41
	v_cvt_pk_bf16_f32 v41, v42, v43
	global_store_dwordx2 v[50:51], v[40:41], off offset:128
	v_pk_mul_f32 v[40:41], v[48:49], v[68:69] op_sel_hi:[0,1]
	v_pk_mul_f32 v[42:43], v[48:49], v[70:71] op_sel_hi:[0,1]
	v_cvt_pk_bf16_f32 v40, v40, v41
	v_cvt_pk_bf16_f32 v41, v42, v43
	global_store_dwordx2 v[50:51], v[40:41], off offset:160
	v_pk_mul_f32 v[40:41], v[48:49], v[72:73] op_sel_hi:[0,1]
	v_pk_mul_f32 v[42:43], v[48:49], v[74:75] op_sel_hi:[0,1]
	v_cvt_pk_bf16_f32 v40, v40, v41
	v_cvt_pk_bf16_f32 v41, v42, v43
	global_store_dwordx2 v[50:51], v[40:41], off offset:192
	v_pk_mul_f32 v[40:41], v[48:49], v[76:77] op_sel_hi:[0,1]
	v_pk_mul_f32 v[42:43], v[48:49], v[78:79] op_sel_hi:[0,1]
	v_cvt_pk_bf16_f32 v40, v40, v41
	v_cvt_pk_bf16_f32 v41, v42, v43
	global_store_dwordx2 v[50:51], v[40:41], off offset:224
	v_pk_mul_f32 v[40:41], v[48:49], v[80:81] op_sel_hi:[0,1]
	v_pk_mul_f32 v[42:43], v[48:49], v[82:83] op_sel_hi:[0,1]
	v_cvt_pk_bf16_f32 v40, v40, v41
	v_cvt_pk_bf16_f32 v41, v42, v43
	global_store_dwordx2 v[50:51], v[40:41], off offset:256
	v_pk_mul_f32 v[40:41], v[48:49], v[84:85] op_sel_hi:[0,1]
	v_pk_mul_f32 v[42:43], v[48:49], v[86:87] op_sel_hi:[0,1]
	v_cvt_pk_bf16_f32 v40, v40, v41
	v_cvt_pk_bf16_f32 v41, v42, v43
	global_store_dwordx2 v[50:51], v[40:41], off offset:288
	v_pk_mul_f32 v[40:41], v[48:49], v[88:89] op_sel_hi:[0,1]
	v_pk_mul_f32 v[42:43], v[48:49], v[90:91] op_sel_hi:[0,1]
	v_cvt_pk_bf16_f32 v40, v40, v41
	v_cvt_pk_bf16_f32 v41, v42, v43
	global_store_dwordx2 v[50:51], v[40:41], off offset:320
	v_pk_mul_f32 v[40:41], v[48:49], v[92:93] op_sel_hi:[0,1]
	v_pk_mul_f32 v[42:43], v[48:49], v[94:95] op_sel_hi:[0,1]
	v_cvt_pk_bf16_f32 v40, v40, v41
	v_cvt_pk_bf16_f32 v41, v42, v43
	global_store_dwordx2 v[50:51], v[40:41], off offset:352
	v_pk_mul_f32 v[40:41], v[48:49], v[96:97] op_sel_hi:[0,1]
	v_pk_mul_f32 v[42:43], v[48:49], v[98:99] op_sel_hi:[0,1]
	v_cvt_pk_bf16_f32 v40, v40, v41
	v_cvt_pk_bf16_f32 v41, v42, v43
	global_store_dwordx2 v[50:51], v[40:41], off offset:384
	v_pk_mul_f32 v[40:41], v[48:49], v[100:101] op_sel_hi:[0,1]
	v_pk_mul_f32 v[42:43], v[48:49], v[102:103] op_sel_hi:[0,1]
	v_cvt_pk_bf16_f32 v40, v40, v41
	v_cvt_pk_bf16_f32 v41, v42, v43
	v_pk_mul_f32 v[44:45], v[48:49], v[44:45] op_sel_hi:[0,1]
	v_pk_mul_f32 v[46:47], v[48:49], v[46:47] op_sel_hi:[0,1]
	global_store_dwordx2 v[50:51], v[40:41], off offset:416
	v_pk_mul_f32 v[40:41], v[48:49], v[104:105] op_sel_hi:[0,1]
	v_pk_mul_f32 v[42:43], v[48:49], v[106:107] op_sel_hi:[0,1]
	v_pk_mul_f32 v[36:37], v[48:49], v[36:37] op_sel_hi:[0,1]
	v_pk_mul_f32 v[38:39], v[48:49], v[38:39] op_sel_hi:[0,1]
	v_cvt_pk_bf16_f32 v44, v44, v45
	v_cvt_pk_bf16_f32 v45, v46, v47
	v_cvt_pk_bf16_f32 v40, v40, v41
	v_cvt_pk_bf16_f32 v41, v42, v43
	v_cvt_pk_bf16_f32 v36, v36, v37
	v_cvt_pk_bf16_f32 v37, v38, v39
	global_store_dwordx2 v[50:51], v[44:45], off
	global_store_dwordx2 v[50:51], v[40:41], off offset:448
	global_store_dwordx2 v[50:51], v[36:37], off offset:480
	s_waitcnt lgkmcnt(0)
	s_barrier
	s_waitcnt lgkmcnt(0)
	s_barrier
	ds_write_b128 v176, v[4:7]
	ds_write_b128 v176, v[8:11] offset:256
	ds_write_b128 v176, v[12:15] offset:8448
	ds_write_b128 v176, v[16:19] offset:8704
	ds_write_b128 v176, v[20:23] offset:16896
	ds_write_b128 v176, v[24:27] offset:17152
	ds_write_b128 v176, v[28:31] offset:25344
	ds_write_b128 v176, v[32:35] offset:25600
	s_waitcnt lgkmcnt(0)
	s_barrier
	ds_read_b128 v[64:67], v175
	ds_read_b128 v[60:63], v175 offset:64
	ds_read_b128 v[56:59], v175 offset:128
	ds_read_b128 v[52:55], v175 offset:192
	ds_read_b128 v[48:51], v175 offset:256
	ds_read_b128 v[44:47], v175 offset:320
	ds_read_b128 v[8:11], v175 offset:384
	ds_read_b128 v[4:7], v175 offset:448
	global_load_dwordx4 v[28:31], v[166:167], off
	global_load_dwordx4 v[12:15], v[164:165], off
	global_load_dwordx4 v[32:35], v[166:167], off offset:128
	global_load_dwordx4 v[16:19], v[164:165], off offset:128
	global_load_dwordx4 v[36:39], v[166:167], off offset:256
	global_load_dwordx4 v[20:23], v[164:165], off offset:256
	global_load_dwordx4 v[40:43], v[166:167], off offset:384
	global_load_dwordx4 v[24:27], v[164:165], off offset:384
	s_waitcnt vmcnt(7)
	ds_write_b128 v170, v[28:31]
	s_waitcnt vmcnt(5)
	ds_write_b128 v170, v[32:35] offset:128
	s_waitcnt vmcnt(3)
	ds_write_b128 v170, v[36:39] offset:256
	s_waitcnt vmcnt(1)
	ds_write_b128 v170, v[40:43] offset:384
	global_load_dwordx4 v[28:31], v[162:163], off
	global_load_dwordx4 v[32:35], v[162:163], off offset:128
	global_load_dwordx4 v[36:39], v[162:163], off offset:256
	global_load_dwordx4 v[40:43], v[162:163], off offset:384
	s_waitcnt lgkmcnt(0)
	s_barrier
	ds_read_b128 v[204:207], v174
	ds_read_b128 v[208:211], v174 offset:64
	ds_read_b128 v[218:221], v174 offset:128
	ds_read_b128 v[224:227], v174 offset:192
	ds_read_b128 v[228:231], v174 offset:256
	ds_read_b128 v[232:235], v174 offset:320
	ds_read_b128 v[236:239], v174 offset:384
	ds_read_b128 v[240:243], v174 offset:448
	s_waitcnt lgkmcnt(7)
	v_mfma_f32_16x16x32_bf16 v[68:71], v[204:207], v[64:67], 0
	ds_read_b128 v[204:207], v174 offset:8448
	s_waitcnt lgkmcnt(7)
	v_mfma_f32_16x16x32_bf16 v[68:71], v[208:211], v[60:63], v[68:71]
	ds_read_b128 v[208:211], v174 offset:8512
	s_waitcnt lgkmcnt(7)
	v_mfma_f32_16x16x32_bf16 v[68:71], v[218:221], v[56:59], v[68:71]
	ds_read_b128 v[218:221], v174 offset:8576
	s_waitcnt lgkmcnt(7)
	v_mfma_f32_16x16x32_bf16 v[68:71], v[224:227], v[52:55], v[68:71]
	ds_read_b128 v[224:227], v174 offset:8640
	s_waitcnt lgkmcnt(7)
	v_mfma_f32_16x16x32_bf16 v[68:71], v[228:231], v[48:51], v[68:71]
	ds_read_b128 v[228:231], v174 offset:8704
	s_waitcnt lgkmcnt(7)
	v_mfma_f32_16x16x32_bf16 v[68:71], v[232:235], v[44:47], v[68:71]
	ds_read_b128 v[232:235], v174 offset:8768
	s_waitcnt lgkmcnt(7)
	v_mfma_f32_16x16x32_bf16 v[68:71], v[236:239], v[8:11], v[68:71]
	ds_read_b128 v[236:239], v174 offset:8832
	s_waitcnt lgkmcnt(7)
	v_mfma_f32_16x16x32_bf16 v[68:71], v[240:243], v[4:7], v[68:71]
	ds_read_b128 v[240:243], v174 offset:8896
	s_waitcnt lgkmcnt(7)
	v_mfma_f32_16x16x32_bf16 v[72:75], v[204:207], v[64:67], 0
	ds_read_b128 v[204:207], v174 offset:16896
	s_waitcnt lgkmcnt(7)
	v_mfma_f32_16x16x32_bf16 v[72:75], v[208:211], v[60:63], v[72:75]
	ds_read_b128 v[208:211], v174 offset:16960
	s_waitcnt lgkmcnt(7)
	v_mfma_f32_16x16x32_bf16 v[72:75], v[218:221], v[56:59], v[72:75]
	ds_read_b128 v[218:221], v174 offset:17024
	s_waitcnt lgkmcnt(7)
	v_mfma_f32_16x16x32_bf16 v[72:75], v[224:227], v[52:55], v[72:75]
	ds_read_b128 v[224:227], v174 offset:17088
	s_waitcnt lgkmcnt(7)
	v_mfma_f32_16x16x32_bf16 v[72:75], v[228:231], v[48:51], v[72:75]
	ds_read_b128 v[228:231], v174 offset:17152
	s_waitcnt lgkmcnt(7)
	v_mfma_f32_16x16x32_bf16 v[72:75], v[232:235], v[44:47], v[72:75]
	ds_read_b128 v[232:235], v174 offset:17216
	s_waitcnt lgkmcnt(7)
	v_mfma_f32_16x16x32_bf16 v[72:75], v[236:239], v[8:11], v[72:75]
	ds_read_b128 v[236:239], v174 offset:17280
	s_waitcnt lgkmcnt(7)
	v_mfma_f32_16x16x32_bf16 v[72:75], v[240:243], v[4:7], v[72:75]
	ds_read_b128 v[240:243], v174 offset:17344
	s_waitcnt lgkmcnt(7)
	v_mfma_f32_16x16x32_bf16 v[76:79], v[204:207], v[64:67], 0
	ds_read_b128 v[204:207], v174 offset:25344
	s_waitcnt lgkmcnt(7)
	v_mfma_f32_16x16x32_bf16 v[76:79], v[208:211], v[60:63], v[76:79]
	ds_read_b128 v[208:211], v174 offset:25408
	s_waitcnt lgkmcnt(7)
	v_mfma_f32_16x16x32_bf16 v[76:79], v[218:221], v[56:59], v[76:79]
	ds_read_b128 v[218:221], v174 offset:25472
	s_waitcnt lgkmcnt(7)
	v_mfma_f32_16x16x32_bf16 v[76:79], v[224:227], v[52:55], v[76:79]
	ds_read_b128 v[224:227], v174 offset:25536
	s_waitcnt lgkmcnt(7)
	v_mfma_f32_16x16x32_bf16 v[76:79], v[228:231], v[48:51], v[76:79]
	ds_read_b128 v[228:231], v174 offset:25600
	s_waitcnt lgkmcnt(7)
	v_mfma_f32_16x16x32_bf16 v[76:79], v[232:235], v[44:47], v[76:79]
	ds_read_b128 v[232:235], v174 offset:25664
	s_waitcnt lgkmcnt(7)
	v_mfma_f32_16x16x32_bf16 v[76:79], v[236:239], v[8:11], v[76:79]
	ds_read_b128 v[236:239], v174 offset:25728
	s_waitcnt lgkmcnt(7)
	v_mfma_f32_16x16x32_bf16 v[76:79], v[240:243], v[4:7], v[76:79]
	s_waitcnt lgkmcnt(6)
	v_mfma_f32_16x16x32_bf16 v[80:83], v[204:207], v[64:67], 0
	s_waitcnt lgkmcnt(5)
	v_mfma_f32_16x16x32_bf16 v[80:83], v[208:211], v[60:63], v[80:83]
	s_waitcnt lgkmcnt(4)
	v_mfma_f32_16x16x32_bf16 v[80:83], v[218:221], v[56:59], v[80:83]
	s_waitcnt lgkmcnt(3)
	v_mfma_f32_16x16x32_bf16 v[80:83], v[224:227], v[52:55], v[80:83]
	s_waitcnt lgkmcnt(2)
	v_mfma_f32_16x16x32_bf16 v[80:83], v[228:231], v[48:51], v[80:83]
	s_waitcnt lgkmcnt(1)
	v_mfma_f32_16x16x32_bf16 v[80:83], v[232:235], v[44:47], v[80:83]
	s_waitcnt lgkmcnt(0)
	v_mfma_f32_16x16x32_bf16 v[80:83], v[236:239], v[8:11], v[80:83]
	ds_read_b128 v[84:87], v174 offset:25792
	ds_write_b128 v168, v[12:15]
	ds_write_b128 v168, v[16:19] offset:128
	ds_write_b128 v168, v[20:23] offset:256
	s_waitcnt vmcnt(4)
	ds_write_b128 v168, v[24:27] offset:384
	global_load_dwordx4 v[12:15], v[160:161], off
	global_load_dwordx4 v[16:19], v[160:161], off offset:128
	global_load_dwordx4 v[20:23], v[160:161], off offset:256
	global_load_dwordx4 v[24:27], v[160:161], off offset:384
	s_waitcnt lgkmcnt(0)
	s_barrier
	s_waitcnt lgkmcnt(4)
	v_mfma_f32_16x16x32_bf16 v[80:83], v[84:87], v[4:7], v[80:83]
	ds_read_b128 v[204:207], v173
	ds_read_b128 v[208:211], v173 offset:64
	ds_read_b128 v[218:221], v173 offset:128
	ds_read_b128 v[224:227], v173 offset:192
	ds_read_b128 v[228:231], v173 offset:256
	ds_read_b128 v[232:235], v173 offset:320
	ds_read_b128 v[236:239], v173 offset:384
	ds_read_b128 v[240:243], v173 offset:448
	s_waitcnt lgkmcnt(7)
	v_mfma_f32_16x16x32_bf16 v[84:87], v[204:207], v[64:67], 0
	ds_read_b128 v[204:207], v173 offset:8448
	s_waitcnt lgkmcnt(7)
	v_mfma_f32_16x16x32_bf16 v[84:87], v[208:211], v[60:63], v[84:87]
	ds_read_b128 v[208:211], v173 offset:8512
	s_waitcnt lgkmcnt(7)
	v_mfma_f32_16x16x32_bf16 v[84:87], v[218:221], v[56:59], v[84:87]
	ds_read_b128 v[218:221], v173 offset:8576
	s_waitcnt lgkmcnt(7)
	v_mfma_f32_16x16x32_bf16 v[84:87], v[224:227], v[52:55], v[84:87]
	ds_read_b128 v[224:227], v173 offset:8640
	s_waitcnt lgkmcnt(7)
	v_mfma_f32_16x16x32_bf16 v[84:87], v[228:231], v[48:51], v[84:87]
	ds_read_b128 v[228:231], v173 offset:8704
	s_waitcnt lgkmcnt(7)
	v_mfma_f32_16x16x32_bf16 v[84:87], v[232:235], v[44:47], v[84:87]
	ds_read_b128 v[232:235], v173 offset:8768
	s_waitcnt lgkmcnt(7)
	v_mfma_f32_16x16x32_bf16 v[84:87], v[236:239], v[8:11], v[84:87]
	ds_read_b128 v[236:239], v173 offset:8832
	s_waitcnt lgkmcnt(7)
	v_mfma_f32_16x16x32_bf16 v[84:87], v[240:243], v[4:7], v[84:87]
	ds_read_b128 v[240:243], v173 offset:8896
	s_waitcnt lgkmcnt(7)
	v_mfma_f32_16x16x32_bf16 v[88:91], v[204:207], v[64:67], 0
	ds_read_b128 v[204:207], v173 offset:16896
	s_waitcnt lgkmcnt(7)
	v_mfma_f32_16x16x32_bf16 v[88:91], v[208:211], v[60:63], v[88:91]
	ds_read_b128 v[208:211], v173 offset:16960
	s_waitcnt lgkmcnt(7)
	v_mfma_f32_16x16x32_bf16 v[88:91], v[218:221], v[56:59], v[88:91]
	ds_read_b128 v[218:221], v173 offset:17024
	s_waitcnt lgkmcnt(7)
	v_mfma_f32_16x16x32_bf16 v[88:91], v[224:227], v[52:55], v[88:91]
	ds_read_b128 v[224:227], v173 offset:17088
	s_waitcnt lgkmcnt(7)
	v_mfma_f32_16x16x32_bf16 v[88:91], v[228:231], v[48:51], v[88:91]
	ds_read_b128 v[228:231], v173 offset:17152
	s_waitcnt lgkmcnt(7)
	v_mfma_f32_16x16x32_bf16 v[88:91], v[232:235], v[44:47], v[88:91]
	ds_read_b128 v[232:235], v173 offset:17216
	s_waitcnt lgkmcnt(7)
	v_mfma_f32_16x16x32_bf16 v[88:91], v[236:239], v[8:11], v[88:91]
	ds_read_b128 v[236:239], v173 offset:17280
	s_waitcnt lgkmcnt(7)
	v_mfma_f32_16x16x32_bf16 v[88:91], v[240:243], v[4:7], v[88:91]
	ds_read_b128 v[240:243], v173 offset:17344
	s_waitcnt lgkmcnt(7)
	v_mfma_f32_16x16x32_bf16 v[92:95], v[204:207], v[64:67], 0
	ds_read_b128 v[204:207], v173 offset:25344
	s_waitcnt lgkmcnt(7)
	v_mfma_f32_16x16x32_bf16 v[92:95], v[208:211], v[60:63], v[92:95]
	ds_read_b128 v[208:211], v173 offset:25408
	s_waitcnt lgkmcnt(7)
	v_mfma_f32_16x16x32_bf16 v[92:95], v[218:221], v[56:59], v[92:95]
	ds_read_b128 v[218:221], v173 offset:25472
	s_waitcnt lgkmcnt(7)
	v_mfma_f32_16x16x32_bf16 v[92:95], v[224:227], v[52:55], v[92:95]
	ds_read_b128 v[224:227], v173 offset:25536
	s_waitcnt lgkmcnt(7)
	v_mfma_f32_16x16x32_bf16 v[92:95], v[228:231], v[48:51], v[92:95]
	ds_read_b128 v[228:231], v173 offset:25600
	s_waitcnt lgkmcnt(7)
	v_mfma_f32_16x16x32_bf16 v[92:95], v[232:235], v[44:47], v[92:95]
	ds_read_b128 v[232:235], v173 offset:25664
	s_waitcnt lgkmcnt(7)
	v_mfma_f32_16x16x32_bf16 v[92:95], v[236:239], v[8:11], v[92:95]
	ds_read_b128 v[236:239], v173 offset:25728
	s_waitcnt lgkmcnt(7)
	v_mfma_f32_16x16x32_bf16 v[92:95], v[240:243], v[4:7], v[92:95]
	s_waitcnt lgkmcnt(6)
	v_mfma_f32_16x16x32_bf16 v[96:99], v[204:207], v[64:67], 0
	s_waitcnt lgkmcnt(5)
	v_mfma_f32_16x16x32_bf16 v[96:99], v[208:211], v[60:63], v[96:99]
	s_waitcnt lgkmcnt(4)
	v_mfma_f32_16x16x32_bf16 v[96:99], v[218:221], v[56:59], v[96:99]
	s_waitcnt lgkmcnt(3)
	v_mfma_f32_16x16x32_bf16 v[96:99], v[224:227], v[52:55], v[96:99]
	s_waitcnt lgkmcnt(2)
	v_mfma_f32_16x16x32_bf16 v[96:99], v[228:231], v[48:51], v[96:99]
	s_waitcnt lgkmcnt(1)
	v_mfma_f32_16x16x32_bf16 v[96:99], v[232:235], v[44:47], v[96:99]
	s_waitcnt lgkmcnt(0)
	v_mfma_f32_16x16x32_bf16 v[96:99], v[236:239], v[8:11], v[96:99]
	ds_read_b128 v[100:103], v173 offset:25792
	s_waitcnt vmcnt(7)
	ds_write_b128 v170, v[28:31]
	s_waitcnt vmcnt(6)
	ds_write_b128 v170, v[32:35] offset:128
	s_waitcnt vmcnt(5)
	ds_write_b128 v170, v[36:39] offset:256
	s_waitcnt vmcnt(4)
	ds_write_b128 v170, v[40:43] offset:384
	global_load_dwordx4 v[28:31], v[166:167], off offset:2048
	global_load_dwordx4 v[32:35], v[166:167], off offset:2176
	global_load_dwordx4 v[36:39], v[166:167], off offset:2304
	global_load_dwordx4 v[40:43], v[166:167], off offset:2432
	s_waitcnt lgkmcnt(0)
	s_barrier
	s_waitcnt lgkmcnt(4)
	v_mfma_f32_16x16x32_bf16 v[96:99], v[100:103], v[4:7], v[96:99]
	ds_read_b128 v[204:207], v174
	ds_read_b128 v[208:211], v174 offset:64
	ds_read_b128 v[218:221], v174 offset:128
	ds_read_b128 v[224:227], v174 offset:192
	ds_read_b128 v[228:231], v174 offset:256
	ds_read_b128 v[232:235], v174 offset:320
	ds_read_b128 v[236:239], v174 offset:384
	ds_read_b128 v[240:243], v174 offset:448
	s_waitcnt lgkmcnt(7)
	v_mfma_f32_16x16x32_bf16 v[100:103], v[204:207], v[64:67], 0
	ds_read_b128 v[204:207], v174 offset:8448
	s_waitcnt lgkmcnt(7)
	v_mfma_f32_16x16x32_bf16 v[100:103], v[208:211], v[60:63], v[100:103]
	ds_read_b128 v[208:211], v174 offset:8512
	s_waitcnt lgkmcnt(7)
	v_mfma_f32_16x16x32_bf16 v[100:103], v[218:221], v[56:59], v[100:103]
	ds_read_b128 v[218:221], v174 offset:8576
	s_waitcnt lgkmcnt(7)
	v_mfma_f32_16x16x32_bf16 v[100:103], v[224:227], v[52:55], v[100:103]
	ds_read_b128 v[224:227], v174 offset:8640
	s_waitcnt lgkmcnt(7)
	v_mfma_f32_16x16x32_bf16 v[100:103], v[228:231], v[48:51], v[100:103]
	ds_read_b128 v[228:231], v174 offset:8704
	s_waitcnt lgkmcnt(7)
	v_mfma_f32_16x16x32_bf16 v[100:103], v[232:235], v[44:47], v[100:103]
	ds_read_b128 v[232:235], v174 offset:8768
	s_waitcnt lgkmcnt(7)
	v_mfma_f32_16x16x32_bf16 v[100:103], v[236:239], v[8:11], v[100:103]
	ds_read_b128 v[236:239], v174 offset:8832
	s_waitcnt lgkmcnt(7)
	v_mfma_f32_16x16x32_bf16 v[100:103], v[240:243], v[4:7], v[100:103]
	ds_read_b128 v[240:243], v174 offset:8896
	s_waitcnt lgkmcnt(7)
	v_mfma_f32_16x16x32_bf16 v[104:107], v[204:207], v[64:67], 0
	ds_read_b128 v[204:207], v174 offset:16896
	s_waitcnt lgkmcnt(7)
	v_mfma_f32_16x16x32_bf16 v[104:107], v[208:211], v[60:63], v[104:107]
	ds_read_b128 v[208:211], v174 offset:16960
	s_waitcnt lgkmcnt(7)
	v_mfma_f32_16x16x32_bf16 v[104:107], v[218:221], v[56:59], v[104:107]
	ds_read_b128 v[218:221], v174 offset:17024
	s_waitcnt lgkmcnt(7)
	v_mfma_f32_16x16x32_bf16 v[104:107], v[224:227], v[52:55], v[104:107]
	ds_read_b128 v[224:227], v174 offset:17088
	s_waitcnt lgkmcnt(7)
	v_mfma_f32_16x16x32_bf16 v[104:107], v[228:231], v[48:51], v[104:107]
	ds_read_b128 v[228:231], v174 offset:17152
	s_waitcnt lgkmcnt(7)
	v_mfma_f32_16x16x32_bf16 v[104:107], v[232:235], v[44:47], v[104:107]
	ds_read_b128 v[232:235], v174 offset:17216
	s_waitcnt lgkmcnt(7)
	v_mfma_f32_16x16x32_bf16 v[104:107], v[236:239], v[8:11], v[104:107]
	ds_read_b128 v[236:239], v174 offset:17280
	s_waitcnt lgkmcnt(7)
	v_mfma_f32_16x16x32_bf16 v[104:107], v[240:243], v[4:7], v[104:107]
	ds_read_b128 v[240:243], v174 offset:17344
	s_waitcnt lgkmcnt(7)
	v_mfma_f32_16x16x32_bf16 v[108:111], v[204:207], v[64:67], 0
	ds_read_b128 v[204:207], v174 offset:25344
	s_waitcnt lgkmcnt(7)
	v_mfma_f32_16x16x32_bf16 v[108:111], v[208:211], v[60:63], v[108:111]
	ds_read_b128 v[208:211], v174 offset:25408
	s_waitcnt lgkmcnt(7)
	v_mfma_f32_16x16x32_bf16 v[108:111], v[218:221], v[56:59], v[108:111]
	ds_read_b128 v[218:221], v174 offset:25472
	s_waitcnt lgkmcnt(7)
	v_mfma_f32_16x16x32_bf16 v[108:111], v[224:227], v[52:55], v[108:111]
	ds_read_b128 v[224:227], v174 offset:25536
	s_waitcnt lgkmcnt(7)
	v_mfma_f32_16x16x32_bf16 v[108:111], v[228:231], v[48:51], v[108:111]
	ds_read_b128 v[228:231], v174 offset:25600
	s_waitcnt lgkmcnt(7)
	v_mfma_f32_16x16x32_bf16 v[108:111], v[232:235], v[44:47], v[108:111]
	ds_read_b128 v[232:235], v174 offset:25664
	s_waitcnt lgkmcnt(7)
	v_mfma_f32_16x16x32_bf16 v[108:111], v[236:239], v[8:11], v[108:111]
	ds_read_b128 v[236:239], v174 offset:25728
	s_waitcnt lgkmcnt(7)
	v_mfma_f32_16x16x32_bf16 v[108:111], v[240:243], v[4:7], v[108:111]
	s_waitcnt lgkmcnt(6)
	v_mfma_f32_16x16x32_bf16 v[112:115], v[204:207], v[64:67], 0
	s_waitcnt lgkmcnt(5)
	v_mfma_f32_16x16x32_bf16 v[112:115], v[208:211], v[60:63], v[112:115]
	s_waitcnt lgkmcnt(4)
	v_mfma_f32_16x16x32_bf16 v[112:115], v[218:221], v[56:59], v[112:115]
	s_waitcnt lgkmcnt(3)
	v_mfma_f32_16x16x32_bf16 v[112:115], v[224:227], v[52:55], v[112:115]
	s_waitcnt lgkmcnt(2)
	v_mfma_f32_16x16x32_bf16 v[112:115], v[228:231], v[48:51], v[112:115]
	s_waitcnt lgkmcnt(1)
	v_mfma_f32_16x16x32_bf16 v[112:115], v[232:235], v[44:47], v[112:115]
	s_waitcnt lgkmcnt(0)
	v_mfma_f32_16x16x32_bf16 v[112:115], v[236:239], v[8:11], v[112:115]
	ds_read_b128 v[116:119], v174 offset:25792
	s_waitcnt vmcnt(7)
	ds_write_b128 v168, v[12:15]
	s_waitcnt vmcnt(6)
	ds_write_b128 v168, v[16:19] offset:128
	s_waitcnt vmcnt(5)
	ds_write_b128 v168, v[20:23] offset:256
	s_waitcnt vmcnt(4)
	ds_write_b128 v168, v[24:27] offset:384
	global_load_dwordx4 v[12:15], v[164:165], off offset:2048
	global_load_dwordx4 v[16:19], v[164:165], off offset:2176
	global_load_dwordx4 v[20:23], v[164:165], off offset:2304
	global_load_dwordx4 v[24:27], v[164:165], off offset:2432
	s_waitcnt lgkmcnt(0)
	s_barrier
	s_waitcnt lgkmcnt(4)
	v_mfma_f32_16x16x32_bf16 v[112:115], v[116:119], v[4:7], v[112:115]
	ds_read_b128 v[116:119], v173
	ds_read_b128 v[120:123], v173 offset:64
	ds_read_b128 v[124:127], v173 offset:8512
	s_waitcnt lgkmcnt(2)
	v_mfma_f32_16x16x32_bf16 v[116:119], v[116:119], v[64:67], 0
	ds_read_b128 v[128:131], v173 offset:16960
	s_waitcnt lgkmcnt(2)
	v_mfma_f32_16x16x32_bf16 v[116:119], v[120:123], v[60:63], v[116:119]
	ds_read_b128 v[120:123], v173 offset:128
	s_waitcnt lgkmcnt(0)
	v_mfma_f32_16x16x32_bf16 v[116:119], v[120:123], v[56:59], v[116:119]
	ds_read_b128 v[120:123], v173 offset:192
	s_waitcnt lgkmcnt(0)
	v_mfma_f32_16x16x32_bf16 v[116:119], v[120:123], v[52:55], v[116:119]
	ds_read_b128 v[120:123], v173 offset:256
	s_waitcnt lgkmcnt(0)
	v_mfma_f32_16x16x32_bf16 v[116:119], v[120:123], v[48:51], v[116:119]
	ds_read_b128 v[120:123], v173 offset:320
	s_waitcnt lgkmcnt(0)
	v_mfma_f32_16x16x32_bf16 v[116:119], v[120:123], v[44:47], v[116:119]
	ds_read_b128 v[120:123], v173 offset:384
	s_waitcnt lgkmcnt(0)
	v_mfma_f32_16x16x32_bf16 v[116:119], v[120:123], v[8:11], v[116:119]
	ds_read_b128 v[120:123], v173 offset:448
	s_waitcnt lgkmcnt(0)
	v_mfma_f32_16x16x32_bf16 v[116:119], v[120:123], v[4:7], v[116:119]
	ds_read_b128 v[120:123], v173 offset:8448
	s_waitcnt lgkmcnt(0)
	v_mfma_f32_16x16x32_bf16 v[120:123], v[120:123], v[64:67], 0
	v_mfma_f32_16x16x32_bf16 v[120:123], v[124:127], v[60:63], v[120:123]
	ds_read_b128 v[124:127], v173 offset:8576
	s_waitcnt lgkmcnt(0)
	v_mfma_f32_16x16x32_bf16 v[120:123], v[124:127], v[56:59], v[120:123]
	ds_read_b128 v[124:127], v173 offset:8640
	s_waitcnt lgkmcnt(0)
	v_mfma_f32_16x16x32_bf16 v[120:123], v[124:127], v[52:55], v[120:123]
	ds_read_b128 v[124:127], v173 offset:8704
	s_waitcnt lgkmcnt(0)
	v_mfma_f32_16x16x32_bf16 v[120:123], v[124:127], v[48:51], v[120:123]
	ds_read_b128 v[124:127], v173 offset:8768
	s_waitcnt lgkmcnt(0)
	v_mfma_f32_16x16x32_bf16 v[120:123], v[124:127], v[44:47], v[120:123]
	ds_read_b128 v[124:127], v173 offset:8832
	s_waitcnt lgkmcnt(0)
	v_mfma_f32_16x16x32_bf16 v[120:123], v[124:127], v[8:11], v[120:123]
	ds_read_b128 v[124:127], v173 offset:8896
	s_waitcnt lgkmcnt(0)
	v_mfma_f32_16x16x32_bf16 v[120:123], v[124:127], v[4:7], v[120:123]
	ds_read_b128 v[124:127], v173 offset:16896
	s_waitcnt lgkmcnt(0)
	v_mfma_f32_16x16x32_bf16 v[124:127], v[124:127], v[64:67], 0
	v_mfma_f32_16x16x32_bf16 v[124:127], v[128:131], v[60:63], v[124:127]
	ds_read_b128 v[128:131], v173 offset:17024
	s_waitcnt lgkmcnt(0)
	v_mfma_f32_16x16x32_bf16 v[124:127], v[128:131], v[56:59], v[124:127]
	ds_read_b128 v[128:131], v173 offset:17088
	s_waitcnt lgkmcnt(0)
	v_mfma_f32_16x16x32_bf16 v[124:127], v[128:131], v[52:55], v[124:127]
	ds_read_b128 v[128:131], v173 offset:17152
	s_waitcnt lgkmcnt(0)
	v_mfma_f32_16x16x32_bf16 v[124:127], v[128:131], v[48:51], v[124:127]
	ds_read_b128 v[128:131], v173 offset:17216
	s_waitcnt lgkmcnt(0)
	v_mfma_f32_16x16x32_bf16 v[124:127], v[128:131], v[44:47], v[124:127]
	ds_read_b128 v[128:131], v173 offset:17280
	s_waitcnt lgkmcnt(0)
	v_mfma_f32_16x16x32_bf16 v[124:127], v[128:131], v[8:11], v[124:127]
	ds_read_b128 v[128:131], v173 offset:17344
	s_waitcnt lgkmcnt(0)
	v_mfma_f32_16x16x32_bf16 v[124:127], v[128:131], v[4:7], v[124:127]
	ds_read_b128 v[128:131], v173 offset:25344
	s_waitcnt lgkmcnt(0)
	v_mfma_f32_16x16x32_bf16 v[64:67], v[128:131], v[64:67], 0
	ds_read_b128 v[128:131], v173 offset:25408
	s_waitcnt lgkmcnt(0)
	v_mfma_f32_16x16x32_bf16 v[60:63], v[128:131], v[60:63], v[64:67]
	s_nop 4
	ds_read_b128 v[64:67], v173 offset:25472
	s_waitcnt lgkmcnt(0)
	v_mfma_f32_16x16x32_bf16 v[56:59], v[64:67], v[56:59], v[60:63]
	s_nop 2
	ds_read_b128 v[60:63], v173 offset:25536
	s_waitcnt lgkmcnt(0)
	v_mfma_f32_16x16x32_bf16 v[52:55], v[60:63], v[52:55], v[56:59]
	s_nop 2
	ds_read_b128 v[56:59], v173 offset:25600
	s_waitcnt lgkmcnt(0)
	v_mfma_f32_16x16x32_bf16 v[48:51], v[56:59], v[48:51], v[52:55]
	s_nop 2
	ds_read_b128 v[52:55], v173 offset:25664
	s_waitcnt lgkmcnt(0)
	v_mfma_f32_16x16x32_bf16 v[44:47], v[52:55], v[44:47], v[48:51]
	s_nop 2
	ds_read_b128 v[48:51], v173 offset:25728
	s_waitcnt lgkmcnt(0)
	v_mfma_f32_16x16x32_bf16 v[8:11], v[48:51], v[8:11], v[44:47]
	s_nop 2
	ds_read_b128 v[44:47], v173 offset:25792
	s_waitcnt vmcnt(7)
	ds_write_b128 v170, v[28:31]
	s_waitcnt vmcnt(6)
	ds_write_b128 v170, v[32:35] offset:128
	s_waitcnt vmcnt(5)
	ds_write_b128 v170, v[36:39] offset:256
	s_waitcnt vmcnt(4)
	ds_write_b128 v170, v[40:43] offset:384
	global_load_dwordx4 v[28:31], v[162:163], off offset:2048
	global_load_dwordx4 v[32:35], v[162:163], off offset:2176
	global_load_dwordx4 v[36:39], v[162:163], off offset:2304
	global_load_dwordx4 v[40:43], v[162:163], off offset:2432
	s_waitcnt lgkmcnt(4)
	v_mfma_f32_16x16x32_bf16 v[4:7], v[44:47], v[4:7], v[8:11]
	s_nop 2
	v_max_f32_e32 v8, v71, v71
	v_max_f32_e32 v9, v70, v70
	v_max_f32_e32 v8, v9, v8
	v_max_f32_e32 v9, v75, v75
	v_max_f32_e32 v10, v74, v74
	v_max_f32_e32 v9, v10, v9
	v_max3_f32 v8, v68, v69, v8
	v_max3_f32 v9, v72, v73, v9
	v_max3_f32 v8, v8, s7, v9
	v_max_f32_e32 v9, v79, v79
	v_max_f32_e32 v10, v78, v78
	v_max_f32_e32 v9, v10, v9
	v_max_f32_e32 v10, v83, v83
	v_max_f32_e32 v11, v82, v82
	v_max_f32_e32 v10, v11, v10
	v_max3_f32 v9, v76, v77, v9
	v_max3_f32 v10, v80, v81, v10
	v_max3_f32 v8, v8, v9, v10
	v_max_f32_e32 v9, v87, v87
	v_max_f32_e32 v10, v86, v86
	v_max_f32_e32 v9, v10, v9
	v_max_f32_e32 v10, v91, v91
	v_max_f32_e32 v11, v90, v90
	v_max_f32_e32 v10, v11, v10
	v_max3_f32 v9, v84, v85, v9
	v_max3_f32 v10, v88, v89, v10
	v_max3_f32 v8, v8, v9, v10
	v_max_f32_e32 v9, v95, v95
	v_max_f32_e32 v10, v94, v94
	v_max_f32_e32 v9, v10, v9
	v_max_f32_e32 v10, v99, v99
	v_max_f32_e32 v11, v98, v98
	v_max_f32_e32 v10, v11, v10
	v_max3_f32 v9, v92, v93, v9
	v_max3_f32 v10, v96, v97, v10
	v_max3_f32 v8, v8, v9, v10
	v_max_f32_e32 v9, v103, v103
	v_max_f32_e32 v10, v102, v102
	v_max_f32_e32 v9, v10, v9
	v_max_f32_e32 v10, v107, v107
	v_max_f32_e32 v11, v106, v106
	v_max_f32_e32 v10, v11, v10
	v_max3_f32 v9, v100, v101, v9
	v_max3_f32 v10, v104, v105, v10
	v_max3_f32 v8, v8, v9, v10
	v_max_f32_e32 v9, v111, v111
	v_max_f32_e32 v10, v110, v110
	v_max_f32_e32 v9, v10, v9
	v_max_f32_e32 v10, v115, v115
	v_max_f32_e32 v11, v114, v114
	v_max_f32_e32 v10, v11, v10
	v_max3_f32 v9, v108, v109, v9
	v_max3_f32 v10, v112, v113, v10
	v_max3_f32 v8, v8, v9, v10
	v_max_f32_e32 v9, v119, v119
	v_max_f32_e32 v10, v118, v118
	v_max_f32_e32 v9, v10, v9
	v_max_f32_e32 v10, v123, v123
	v_max_f32_e32 v11, v122, v122
	v_max_f32_e32 v10, v11, v10
	v_max3_f32 v9, v116, v117, v9
	v_max3_f32 v10, v120, v121, v10
	v_max3_f32 v8, v8, v9, v10
	v_max_f32_e32 v9, v127, v127
	v_max_f32_e32 v10, v126, v126
	v_max_f32_e32 v9, v10, v9
	v_max_f32_e32 v10, v7, v7
	v_max_f32_e32 v11, v6, v6
	v_max_f32_e32 v10, v11, v10
	v_max3_f32 v9, v124, v125, v9
	v_max3_f32 v10, v4, v5, v10
	v_max3_f32 v8, v8, v9, v10
	ds_bpermute_b32 v9, v171, v8
	s_waitcnt lgkmcnt(0)
	s_barrier
	s_waitcnt lgkmcnt(0)
	v_max_f32_e32 v9, v9, v9
	v_max_f32_e32 v8, v8, v9
	ds_bpermute_b32 v9, v172, v8
	s_waitcnt lgkmcnt(0)
	v_max_f32_e32 v9, v9, v9
	v_max_f32_e32 v52, v8, v9
	v_sub_f32_e32 v8, v68, v52
	v_mul_f32_e32 v8, 0x3d800000, v8
	v_sub_f32_e32 v9, v69, v52
	v_mul_f32_e32 v8, 0x3fb8aa3b, v8
	v_mul_f32_e32 v9, 0x3d800000, v9
	v_exp_f32_e32 v8, v8
	v_mul_f32_e32 v9, 0x3fb8aa3b, v9
	v_exp_f32_e32 v9, v9
	v_sub_f32_e32 v56, v82, v52
	v_add_f32_e32 v10, 0, v8
	v_mul_f32_e32 v56, 0x3d800000, v56
	v_add_f32_e32 v11, v9, v10
	v_sub_f32_e32 v10, v70, v52
	v_mul_f32_e32 v10, 0x3d800000, v10
	v_mul_f32_e32 v10, 0x3fb8aa3b, v10
	v_exp_f32_e32 v10, v10
	v_mul_f32_e32 v56, 0x3fb8aa3b, v56
	v_exp_f32_e32 v60, v56
	v_sub_f32_e32 v56, v83, v52
	v_add_f32_e32 v44, v10, v11
	v_sub_f32_e32 v11, v71, v52
	v_mul_f32_e32 v56, 0x3d800000, v56
	v_mul_f32_e32 v11, 0x3d800000, v11
	v_mul_f32_e32 v56, 0x3fb8aa3b, v56
	v_mul_f32_e32 v11, 0x3fb8aa3b, v11
	v_exp_f32_e32 v61, v56
	v_sub_f32_e32 v56, v84, v52
	v_exp_f32_e32 v11, v11
	v_mul_f32_e32 v56, 0x3d800000, v56
	v_mul_f32_e32 v56, 0x3fb8aa3b, v56
	v_exp_f32_e32 v62, v56
	v_sub_f32_e32 v56, v85, v52
	v_mul_f32_e32 v56, 0x3d800000, v56
	v_add_f32_e32 v45, v11, v44
	v_sub_f32_e32 v44, v72, v52
	v_mul_f32_e32 v56, 0x3fb8aa3b, v56
	v_mul_f32_e32 v44, 0x3d800000, v44
	v_exp_f32_e32 v63, v56
	v_sub_f32_e32 v56, v86, v52
	v_mul_f32_e32 v44, 0x3fb8aa3b, v44
	v_mul_f32_e32 v56, 0x3d800000, v56
	v_exp_f32_e32 v44, v44
	v_mul_f32_e32 v56, 0x3fb8aa3b, v56
	v_exp_f32_e32 v64, v56
	v_sub_f32_e32 v56, v87, v52
	v_mul_f32_e32 v56, 0x3d800000, v56
	v_mul_f32_e32 v56, 0x3fb8aa3b, v56
	v_add_f32_e32 v46, v44, v45
	v_sub_f32_e32 v45, v73, v52
	v_exp_f32_e32 v65, v56
	v_sub_f32_e32 v56, v88, v52
	v_mul_f32_e32 v45, 0x3d800000, v45
	v_mul_f32_e32 v56, 0x3d800000, v56
	v_mul_f32_e32 v45, 0x3fb8aa3b, v45
	v_mul_f32_e32 v56, 0x3fb8aa3b, v56
	v_exp_f32_e32 v45, v45
	v_exp_f32_e32 v66, v56
	v_sub_f32_e32 v56, v89, v52
	v_mul_f32_e32 v56, 0x3d800000, v56
	v_mul_f32_e32 v56, 0x3fb8aa3b, v56
	v_exp_f32_e32 v67, v56
	v_sub_f32_e32 v56, v90, v52
	v_add_f32_e32 v47, v45, v46
	v_sub_f32_e32 v46, v74, v52
	v_mul_f32_e32 v56, 0x3d800000, v56
	v_mul_f32_e32 v46, 0x3d800000, v46
	v_mul_f32_e32 v56, 0x3fb8aa3b, v56
	v_mul_f32_e32 v46, 0x3fb8aa3b, v46
	v_exp_f32_e32 v68, v56
	v_sub_f32_e32 v56, v91, v52
	v_exp_f32_e32 v46, v46
	v_mul_f32_e32 v56, 0x3d800000, v56
	v_mul_f32_e32 v56, 0x3fb8aa3b, v56
	v_exp_f32_e32 v69, v56
	v_sub_f32_e32 v56, v92, v52
	v_mul_f32_e32 v56, 0x3d800000, v56
	v_add_f32_e32 v48, v46, v47
	v_sub_f32_e32 v47, v75, v52
	v_mul_f32_e32 v56, 0x3fb8aa3b, v56
	v_mul_f32_e32 v47, 0x3d800000, v47
	v_exp_f32_e32 v70, v56
	v_sub_f32_e32 v56, v93, v52
	v_mul_f32_e32 v47, 0x3fb8aa3b, v47
	v_mul_f32_e32 v56, 0x3d800000, v56
	v_exp_f32_e32 v47, v47
	v_mul_f32_e32 v56, 0x3fb8aa3b, v56
	v_exp_f32_e32 v71, v56
	v_sub_f32_e32 v56, v94, v52
	v_mul_f32_e32 v56, 0x3d800000, v56
	v_mul_f32_e32 v56, 0x3fb8aa3b, v56
	v_add_f32_e32 v49, v47, v48
	v_sub_f32_e32 v48, v76, v52
	v_exp_f32_e32 v72, v56
	v_sub_f32_e32 v56, v95, v52
	v_mul_f32_e32 v48, 0x3d800000, v48
	v_mul_f32_e32 v56, 0x3d800000, v56
	v_mul_f32_e32 v48, 0x3fb8aa3b, v48
	v_mul_f32_e32 v56, 0x3fb8aa3b, v56
	v_exp_f32_e32 v48, v48
	v_exp_f32_e32 v73, v56
	v_sub_f32_e32 v56, v96, v52
	v_mul_f32_e32 v56, 0x3d800000, v56
	v_mul_f32_e32 v56, 0x3fb8aa3b, v56
	v_exp_f32_e32 v74, v56
	v_sub_f32_e32 v56, v97, v52
	v_add_f32_e32 v50, v48, v49
	v_sub_f32_e32 v49, v77, v52
	v_mul_f32_e32 v56, 0x3d800000, v56
	v_mul_f32_e32 v49, 0x3d800000, v49
	v_mul_f32_e32 v56, 0x3fb8aa3b, v56
	v_mul_f32_e32 v49, 0x3fb8aa3b, v49
	v_exp_f32_e32 v75, v56
	v_sub_f32_e32 v56, v98, v52
	v_exp_f32_e32 v49, v49
	v_mul_f32_e32 v56, 0x3d800000, v56
	v_mul_f32_e32 v56, 0x3fb8aa3b, v56
	v_exp_f32_e32 v76, v56
	v_sub_f32_e32 v56, v99, v52
	v_mul_f32_e32 v56, 0x3d800000, v56
	v_add_f32_e32 v51, v49, v50
	v_sub_f32_e32 v50, v78, v52
	v_mul_f32_e32 v56, 0x3fb8aa3b, v56
	v_mul_f32_e32 v50, 0x3d800000, v50
	v_exp_f32_e32 v77, v56
	v_sub_f32_e32 v56, v100, v52
	v_mul_f32_e32 v50, 0x3fb8aa3b, v50
	v_mul_f32_e32 v56, 0x3d800000, v56
	v_exp_f32_e32 v50, v50
	v_mul_f32_e32 v56, 0x3fb8aa3b, v56
	v_exp_f32_e32 v78, v56
	v_sub_f32_e32 v56, v101, v52
	v_mul_f32_e32 v56, 0x3d800000, v56
	v_mul_f32_e32 v56, 0x3fb8aa3b, v56
	v_add_f32_e32 v53, v50, v51
	v_sub_f32_e32 v51, v79, v52
	v_exp_f32_e32 v79, v56
	v_sub_f32_e32 v56, v102, v52
	v_mul_f32_e32 v56, 0x3d800000, v56
	v_mul_f32_e32 v56, 0x3fb8aa3b, v56
	v_sub_f32_e32 v54, v80, v52
	v_exp_f32_e32 v80, v56
	v_sub_f32_e32 v56, v103, v52
	v_mul_f32_e32 v56, 0x3d800000, v56
	v_mul_f32_e32 v56, 0x3fb8aa3b, v56
	v_sub_f32_e32 v55, v81, v52
	v_exp_f32_e32 v81, v56
	v_sub_f32_e32 v56, v104, v52
	v_mul_f32_e32 v56, 0x3d800000, v56
	v_mul_f32_e32 v56, 0x3fb8aa3b, v56
	v_exp_f32_e32 v82, v56
	v_sub_f32_e32 v56, v105, v52
	v_mul_f32_e32 v56, 0x3d800000, v56
	v_mul_f32_e32 v56, 0x3fb8aa3b, v56
	v_exp_f32_e32 v83, v56
	v_sub_f32_e32 v56, v106, v52
	v_mul_f32_e32 v56, 0x3d800000, v56
	v_mul_f32_e32 v56, 0x3fb8aa3b, v56
	v_exp_f32_e32 v84, v56
	v_sub_f32_e32 v56, v107, v52
	v_mul_f32_e32 v56, 0x3d800000, v56
	v_mul_f32_e32 v56, 0x3fb8aa3b, v56
	v_exp_f32_e32 v85, v56
	v_sub_f32_e32 v56, v108, v52
	v_mul_f32_e32 v56, 0x3d800000, v56
	v_mul_f32_e32 v56, 0x3fb8aa3b, v56
	v_exp_f32_e32 v86, v56
	v_sub_f32_e32 v56, v109, v52
	v_mul_f32_e32 v56, 0x3d800000, v56
	v_mul_f32_e32 v56, 0x3fb8aa3b, v56
	v_exp_f32_e32 v87, v56
	v_sub_f32_e32 v56, v110, v52
	v_mul_f32_e32 v56, 0x3d800000, v56
	v_mul_f32_e32 v56, 0x3fb8aa3b, v56
	v_exp_f32_e32 v88, v56
	v_sub_f32_e32 v56, v111, v52
	v_mul_f32_e32 v51, 0x3d800000, v51
	v_mul_f32_e32 v56, 0x3d800000, v56
	v_mul_f32_e32 v51, 0x3fb8aa3b, v51
	v_mul_f32_e32 v54, 0x3d800000, v54
	v_mul_f32_e32 v56, 0x3fb8aa3b, v56
	v_exp_f32_e32 v51, v51
	v_mul_f32_e32 v54, 0x3fb8aa3b, v54
	v_mul_f32_e32 v55, 0x3d800000, v55
	v_exp_f32_e32 v89, v56
	v_sub_f32_e32 v56, v112, v52
	v_exp_f32_e32 v54, v54
	v_mul_f32_e32 v55, 0x3fb8aa3b, v55
	v_mul_f32_e32 v56, 0x3d800000, v56
	v_exp_f32_e32 v55, v55
	v_mul_f32_e32 v56, 0x3fb8aa3b, v56
	v_exp_f32_e32 v90, v56
	v_sub_f32_e32 v56, v113, v52
	v_add_f32_e32 v53, v51, v53
	v_mul_f32_e32 v56, 0x3d800000, v56
	v_add_f32_e32 v53, v54, v53
	v_mul_f32_e32 v56, 0x3fb8aa3b, v56
	v_add_f32_e32 v53, v55, v53
	v_exp_f32_e32 v91, v56
	v_sub_f32_e32 v56, v114, v52
	v_add_f32_e32 v53, v60, v53
	v_mul_f32_e32 v56, 0x3d800000, v56
	v_add_f32_e32 v53, v61, v53
	v_mul_f32_e32 v56, 0x3fb8aa3b, v56
	v_add_f32_e32 v53, v62, v53
	v_exp_f32_e32 v92, v56
	v_sub_f32_e32 v56, v115, v52
	v_add_f32_e32 v53, v63, v53
	v_mul_f32_e32 v56, 0x3d800000, v56
	v_add_f32_e32 v53, v64, v53
	v_mul_f32_e32 v56, 0x3fb8aa3b, v56
	v_add_f32_e32 v53, v65, v53
	v_exp_f32_e32 v93, v56
	v_sub_f32_e32 v56, v116, v52
	v_add_f32_e32 v53, v66, v53
	v_mul_f32_e32 v56, 0x3d800000, v56
	v_add_f32_e32 v53, v67, v53
	v_mul_f32_e32 v56, 0x3fb8aa3b, v56
	v_add_f32_e32 v53, v68, v53
	v_exp_f32_e32 v139, v56
	v_sub_f32_e32 v56, v117, v52
	v_add_f32_e32 v53, v69, v53
	v_mul_f32_e32 v56, 0x3d800000, v56
	v_add_f32_e32 v53, v70, v53
	v_mul_f32_e32 v56, 0x3fb8aa3b, v56
	v_add_f32_e32 v53, v71, v53
	v_exp_f32_e32 v140, v56
	v_sub_f32_e32 v56, v118, v52
	v_add_f32_e32 v53, v72, v53
	v_mul_f32_e32 v56, 0x3d800000, v56
	v_add_f32_e32 v53, v73, v53
	v_mul_f32_e32 v56, 0x3fb8aa3b, v56
	v_add_f32_e32 v53, v74, v53
	v_exp_f32_e32 v141, v56
	v_sub_f32_e32 v56, v119, v52
	v_add_f32_e32 v53, v75, v53
	v_mul_f32_e32 v56, 0x3d800000, v56
	v_add_f32_e32 v53, v76, v53
	v_mul_f32_e32 v56, 0x3fb8aa3b, v56
	v_add_f32_e32 v53, v77, v53
	v_exp_f32_e32 v142, v56
	v_sub_f32_e32 v56, v120, v52
	v_add_f32_e32 v53, v78, v53
	v_mul_f32_e32 v56, 0x3d800000, v56
	v_add_f32_e32 v53, v79, v53
	v_mul_f32_e32 v56, 0x3fb8aa3b, v56
	v_add_f32_e32 v53, v80, v53
	v_exp_f32_e32 v143, v56
	v_sub_f32_e32 v56, v121, v52
	v_add_f32_e32 v53, v81, v53
	v_mul_f32_e32 v56, 0x3d800000, v56
	v_add_f32_e32 v53, v82, v53
	v_mul_f32_e32 v56, 0x3fb8aa3b, v56
	v_add_f32_e32 v53, v83, v53
	v_exp_f32_e32 v144, v56
	v_sub_f32_e32 v56, v122, v52
	v_add_f32_e32 v53, v84, v53
	v_mul_f32_e32 v56, 0x3d800000, v56
	v_add_f32_e32 v53, v85, v53
	v_mul_f32_e32 v56, 0x3fb8aa3b, v56
	v_add_f32_e32 v53, v86, v53
	v_exp_f32_e32 v145, v56
	v_sub_f32_e32 v56, v123, v52
	v_add_f32_e32 v53, v87, v53
	v_mul_f32_e32 v56, 0x3d800000, v56
	v_add_f32_e32 v53, v88, v53
	v_mul_f32_e32 v56, 0x3fb8aa3b, v56
	v_add_f32_e32 v53, v89, v53
	v_exp_f32_e32 v146, v56
	v_sub_f32_e32 v56, v124, v52
	v_add_f32_e32 v53, v90, v53
	v_mul_f32_e32 v56, 0x3d800000, v56
	v_add_f32_e32 v53, v91, v53
	v_mul_f32_e32 v56, 0x3fb8aa3b, v56
	v_add_f32_e32 v53, v92, v53
	v_exp_f32_e32 v147, v56
	v_sub_f32_e32 v56, v125, v52
	v_add_f32_e32 v53, v93, v53
	v_mul_f32_e32 v56, 0x3d800000, v56
	v_add_f32_e32 v53, v139, v53
	v_mul_f32_e32 v56, 0x3fb8aa3b, v56
	v_add_f32_e32 v53, v140, v53
	v_exp_f32_e32 v148, v56
	v_sub_f32_e32 v56, v126, v52
	v_add_f32_e32 v53, v141, v53
	v_mul_f32_e32 v56, 0x3d800000, v56
	v_add_f32_e32 v53, v142, v53
	v_mul_f32_e32 v56, 0x3fb8aa3b, v56
	v_add_f32_e32 v53, v143, v53
	v_exp_f32_e32 v149, v56
	v_sub_f32_e32 v56, v127, v52
	v_add_f32_e32 v53, v144, v53
	v_mul_f32_e32 v56, 0x3d800000, v56
	v_sub_f32_e32 v4, v4, v52
	v_add_f32_e32 v53, v145, v53
	v_mul_f32_e32 v56, 0x3fb8aa3b, v56
	v_mul_f32_e32 v4, 0x3d800000, v4
	v_sub_f32_e32 v5, v5, v52
	v_add_f32_e32 v53, v146, v53
	v_exp_f32_e32 v150, v56
	v_mul_f32_e32 v4, 0x3fb8aa3b, v4
	v_mul_f32_e32 v5, 0x3d800000, v5
	v_add_f32_e32 v53, v147, v53
	v_exp_f32_e32 v151, v4
	v_mul_f32_e32 v5, 0x3fb8aa3b, v5
	v_add_f32_e32 v53, v148, v53
	v_exp_f32_e32 v152, v5
	v_sub_f32_e32 v5, v6, v52
	v_add_f32_e32 v53, v149, v53
	v_mul_f32_e32 v5, 0x3d800000, v5
	v_add_f32_e32 v53, v150, v53
	v_mul_f32_e32 v5, 0x3fb8aa3b, v5
	v_add_f32_e32 v4, v151, v53
	v_exp_f32_e32 v153, v5
	v_sub_f32_e32 v5, v7, v52
	v_cvt_pk_bf16_f32 v52, v48, v49
	v_cvt_pk_bf16_f32 v53, v50, v51
	v_cvt_pk_bf16_f32 v54, v54, v55
	v_cvt_pk_bf16_f32 v55, v60, v61
	v_cvt_pk_bf16_f32 v48, v62, v63
	v_cvt_pk_bf16_f32 v49, v64, v65
	v_cvt_pk_bf16_f32 v50, v66, v67
	v_cvt_pk_bf16_f32 v51, v68, v69
	ds_read_b64_tr_b16 v[60:61], v169
	ds_read_b64_tr_b16 v[64:65], v169 offset:32
	ds_read_b64_tr_b16 v[62:63], v169 offset:8448
	ds_read_b64_tr_b16 v[66:67], v169 offset:16896
	ds_read_b64_tr_b16 v[68:69], v169 offset:25344
	v_cvt_pk_bf16_f32 v56, v8, v9
	v_cvt_pk_bf16_f32 v57, v10, v11
	v_cvt_pk_bf16_f32 v58, v44, v45
	v_cvt_pk_bf16_f32 v59, v46, v47
	v_cvt_pk_bf16_f32 v44, v70, v71
	v_cvt_pk_bf16_f32 v45, v72, v73
	s_waitcnt lgkmcnt(2)
	v_mfma_f32_16x16x32_bf16 v[60:63], v[60:63], v[56:59], 0
	v_cvt_pk_bf16_f32 v46, v74, v75
	v_cvt_pk_bf16_f32 v47, v76, v77
	v_cvt_pk_bf16_f32 v8, v78, v79
	s_waitcnt lgkmcnt(0)
	v_mfma_f32_16x16x32_bf16 v[60:63], v[66:69], v[52:55], v[60:63]
	ds_read_b64_tr_b16 v[66:67], v169 offset:8480
	ds_read_b64_tr_b16 v[68:69], v169 offset:16928
	ds_read_b64_tr_b16 v[70:71], v169 offset:25376
	v_mul_f32_e32 v5, 0x3d800000, v5
	v_mul_f32_e32 v5, 0x3fb8aa3b, v5
	s_waitcnt lgkmcnt(2)
	v_mfma_f32_16x16x32_bf16 v[64:67], v[64:67], v[56:59], 0
	v_exp_f32_e32 v154, v5
	v_add_f32_e32 v4, v152, v4
	v_add_f32_e32 v4, v153, v4
	s_waitcnt lgkmcnt(0)
	v_mfma_f32_16x16x32_bf16 v[64:67], v[68:71], v[52:55], v[64:67]
	ds_read_b64_tr_b16 v[68:69], v169 offset:64
	ds_read_b64_tr_b16 v[70:71], v169 offset:8512
	ds_read_b64_tr_b16 v[72:73], v169 offset:16960
	ds_read_b64_tr_b16 v[74:75], v169 offset:25408
	v_cvt_pk_bf16_f32 v9, v80, v81
	v_cvt_pk_bf16_f32 v10, v82, v83
	s_waitcnt lgkmcnt(2)
	v_mfma_f32_16x16x32_bf16 v[68:71], v[68:71], v[56:59], 0
	v_add_f32_e32 v4, v154, v4
	ds_bpermute_b32 v5, v171, v4
	v_cvt_pk_bf16_f32 v11, v84, v85
	s_waitcnt lgkmcnt(1)
	v_mfma_f32_16x16x32_bf16 v[68:71], v[72:75], v[52:55], v[68:71]
	ds_read_b64_tr_b16 v[72:73], v169 offset:96
	ds_read_b64_tr_b16 v[74:75], v169 offset:8544
	ds_read_b64_tr_b16 v[76:77], v169 offset:16992
	ds_read_b64_tr_b16 v[78:79], v169 offset:25440
	v_cvt_pk_bf16_f32 v6, v90, v91
	s_waitcnt lgkmcnt(4)
	v_add_f32_e32 v137, v4, v5
	s_waitcnt lgkmcnt(2)
	v_mfma_f32_16x16x32_bf16 v[72:75], v[72:75], v[56:59], 0
	v_cvt_pk_bf16_f32 v4, v86, v87
	v_cvt_pk_bf16_f32 v5, v88, v89
	v_cvt_pk_bf16_f32 v7, v92, v93
	s_waitcnt lgkmcnt(0)
	v_mfma_f32_16x16x32_bf16 v[108:111], v[76:79], v[52:55], v[72:75]
	s_nop 2
	ds_read_b64_tr_b16 v[72:73], v169 offset:128
	ds_read_b64_tr_b16 v[74:75], v169 offset:8576
	ds_read_b64_tr_b16 v[76:77], v169 offset:17024
	ds_read_b64_tr_b16 v[78:79], v169 offset:25472
	ds_bpermute_b32 v138, v172, v137
	s_waitcnt lgkmcnt(3)
	v_mfma_f32_16x16x32_bf16 v[72:75], v[72:75], v[56:59], 0
	s_waitcnt lgkmcnt(1)
	v_mfma_f32_16x16x32_bf16 v[72:75], v[76:79], v[52:55], v[72:75]
	ds_read_b64_tr_b16 v[76:77], v169 offset:160
	ds_read_b64_tr_b16 v[78:79], v169 offset:8608
	ds_read_b64_tr_b16 v[80:81], v169 offset:17056
	ds_read_b64_tr_b16 v[82:83], v169 offset:25504
	s_waitcnt lgkmcnt(2)
	v_mfma_f32_16x16x32_bf16 v[76:79], v[76:79], v[56:59], 0
	s_waitcnt lgkmcnt(0)
	v_mfma_f32_16x16x32_bf16 v[76:79], v[80:83], v[52:55], v[76:79]
	ds_read_b64_tr_b16 v[80:81], v169 offset:192
	ds_read_b64_tr_b16 v[82:83], v169 offset:8640
	ds_read_b64_tr_b16 v[84:85], v169 offset:17088
	ds_read_b64_tr_b16 v[86:87], v169 offset:25536
	s_waitcnt lgkmcnt(2)
	v_mfma_f32_16x16x32_bf16 v[80:83], v[80:83], v[56:59], 0
	s_waitcnt lgkmcnt(0)
	v_mfma_f32_16x16x32_bf16 v[80:83], v[84:87], v[52:55], v[80:83]
	ds_read_b64_tr_b16 v[84:85], v169 offset:224
	ds_read_b64_tr_b16 v[86:87], v169 offset:8672
	ds_read_b64_tr_b16 v[88:89], v169 offset:17120
	ds_read_b64_tr_b16 v[90:91], v169 offset:25568
	s_waitcnt lgkmcnt(2)
	v_mfma_f32_16x16x32_bf16 v[84:87], v[84:87], v[56:59], 0
	s_waitcnt lgkmcnt(0)
	v_mfma_f32_16x16x32_bf16 v[112:115], v[88:91], v[52:55], v[84:87]
	s_nop 5
	ds_read_b64_tr_b16 v[84:85], v169 offset:256
	ds_read_b64_tr_b16 v[86:87], v169 offset:8704
	ds_read_b64_tr_b16 v[88:89], v169 offset:17152
	ds_read_b64_tr_b16 v[90:91], v169 offset:25600
	s_waitcnt lgkmcnt(2)
	v_mfma_f32_16x16x32_bf16 v[84:87], v[84:87], v[56:59], 0
	s_waitcnt lgkmcnt(0)
	v_mfma_f32_16x16x32_bf16 v[84:87], v[88:91], v[52:55], v[84:87]
	ds_read_b64_tr_b16 v[88:89], v169 offset:288
	ds_read_b64_tr_b16 v[90:91], v169 offset:8736
	ds_read_b64_tr_b16 v[92:93], v169 offset:17184
	ds_read_b64_tr_b16 v[94:95], v169 offset:25632
	s_waitcnt lgkmcnt(2)
	v_mfma_f32_16x16x32_bf16 v[88:91], v[88:91], v[56:59], 0
	s_waitcnt lgkmcnt(0)
	v_mfma_f32_16x16x32_bf16 v[88:91], v[92:95], v[52:55], v[88:91]
	ds_read_b64_tr_b16 v[92:93], v169 offset:320
	ds_read_b64_tr_b16 v[94:95], v169 offset:8768
	ds_read_b64_tr_b16 v[96:97], v169 offset:17216
	ds_read_b64_tr_b16 v[98:99], v169 offset:25664
	s_waitcnt lgkmcnt(2)
	v_mfma_f32_16x16x32_bf16 v[92:95], v[92:95], v[56:59], 0
	s_waitcnt lgkmcnt(0)
	v_mfma_f32_16x16x32_bf16 v[92:95], v[96:99], v[52:55], v[92:95]
	ds_read_b64_tr_b16 v[96:97], v169 offset:352
	ds_read_b64_tr_b16 v[98:99], v169 offset:8800
	ds_read_b64_tr_b16 v[100:101], v169 offset:17248
	ds_read_b64_tr_b16 v[102:103], v169 offset:25696
	s_waitcnt lgkmcnt(2)
	v_mfma_f32_16x16x32_bf16 v[96:99], v[96:99], v[56:59], 0
	s_waitcnt lgkmcnt(0)
	v_mfma_f32_16x16x32_bf16 v[116:119], v[100:103], v[52:55], v[96:99]
	s_nop 5
	ds_read_b64_tr_b16 v[96:97], v169 offset:384
	ds_read_b64_tr_b16 v[98:99], v169 offset:8832
	ds_read_b64_tr_b16 v[100:101], v169 offset:17280
	ds_read_b64_tr_b16 v[102:103], v169 offset:25728
	s_waitcnt lgkmcnt(2)
	v_mfma_f32_16x16x32_bf16 v[96:99], v[96:99], v[56:59], 0
	s_waitcnt lgkmcnt(0)
	v_mfma_f32_16x16x32_bf16 v[96:99], v[100:103], v[52:55], v[96:99]
	ds_read_b64_tr_b16 v[100:101], v169 offset:416
	ds_read_b64_tr_b16 v[102:103], v169 offset:8864
	ds_read_b64_tr_b16 v[104:105], v169 offset:17312
	ds_read_b64_tr_b16 v[106:107], v169 offset:25760
	s_waitcnt lgkmcnt(2)
	v_mfma_f32_16x16x32_bf16 v[100:103], v[100:103], v[56:59], 0
	s_waitcnt lgkmcnt(0)
	v_mfma_f32_16x16x32_bf16 v[100:103], v[104:107], v[52:55], v[100:103]
	ds_read_b64_tr_b16 v[104:105], v169 offset:448
	ds_read_b64_tr_b16 v[106:107], v169 offset:8896
	ds_read_b64_tr_b16 v[120:121], v169 offset:17344
	ds_read_b64_tr_b16 v[122:123], v169 offset:25792
	s_waitcnt lgkmcnt(2)
	v_mfma_f32_16x16x32_bf16 v[104:107], v[104:107], v[56:59], 0
	s_waitcnt lgkmcnt(0)
	v_mfma_f32_16x16x32_bf16 v[104:107], v[120:123], v[52:55], v[104:107]
	ds_read_b64_tr_b16 v[120:121], v169 offset:480
	ds_read_b64_tr_b16 v[122:123], v169 offset:8928
	ds_read_b64_tr_b16 v[124:125], v169 offset:17376
	ds_read_b64_tr_b16 v[126:127], v169 offset:25824
	s_waitcnt vmcnt(7)
	ds_write_b128 v168, v[12:15]
	s_waitcnt vmcnt(6)
	ds_write_b128 v168, v[16:19] offset:128
	s_waitcnt vmcnt(5)
	ds_write_b128 v168, v[20:23] offset:256
	s_waitcnt vmcnt(4)
	ds_write_b128 v168, v[24:27] offset:384
	global_load_dwordx4 v[12:15], v[160:161], off offset:2048
	global_load_dwordx4 v[16:19], v[160:161], off offset:2176
	global_load_dwordx4 v[20:23], v[160:161], off offset:2304
	global_load_dwordx4 v[24:27], v[160:161], off offset:2432
	s_waitcnt lgkmcnt(6)
	v_mfma_f32_16x16x32_bf16 v[56:59], v[120:123], v[56:59], 0
	s_waitcnt lgkmcnt(0)
	s_barrier
	s_waitcnt lgkmcnt(4)
	v_mfma_f32_16x16x32_bf16 v[120:123], v[124:127], v[52:55], v[56:59]
	ds_read_b64_tr_b16 v[204:205], v3
	ds_read_b64_tr_b16 v[206:207], v3 offset:8448
	ds_read_b64_tr_b16 v[208:209], v3 offset:32
	ds_read_b64_tr_b16 v[210:211], v3 offset:8480
	ds_read_b64_tr_b16 v[218:219], v3 offset:16928
	ds_read_b64_tr_b16 v[220:221], v3 offset:25376
	ds_read_b64_tr_b16 v[224:225], v3 offset:64
	ds_read_b64_tr_b16 v[226:227], v3 offset:8512
	ds_read_b64_tr_b16 v[228:229], v3 offset:16960
	ds_read_b64_tr_b16 v[230:231], v3 offset:25408
	ds_read_b64_tr_b16 v[232:233], v3 offset:96
	ds_read_b64_tr_b16 v[234:235], v3 offset:8544
	ds_read_b64_tr_b16 v[236:237], v3 offset:16992
	ds_read_b64_tr_b16 v[238:239], v3 offset:25440
	ds_read_b64_tr_b16 v[240:241], v3 offset:128
	ds_read_b64_tr_b16 v[242:243], v3 offset:8576
	s_waitcnt lgkmcnt(14)
	v_mfma_f32_16x16x32_bf16 v[52:55], v[204:207], v[48:51], v[60:63]
	ds_read_b64_tr_b16 v[204:205], v3 offset:17024
	ds_read_b64_tr_b16 v[206:207], v3 offset:25472
	s_waitcnt lgkmcnt(14)
	v_mfma_f32_16x16x32_bf16 v[56:59], v[208:211], v[48:51], v[64:67]
	ds_read_b64_tr_b16 v[208:209], v3 offset:160
	ds_read_b64_tr_b16 v[210:211], v3 offset:8608
	s_waitcnt lgkmcnt(14)
	v_mfma_f32_16x16x32_bf16 v[56:59], v[218:221], v[44:47], v[56:59]
	ds_read_b64_tr_b16 v[218:219], v3 offset:17056
	ds_read_b64_tr_b16 v[220:221], v3 offset:25504
	s_waitcnt lgkmcnt(14)
	v_mfma_f32_16x16x32_bf16 v[60:63], v[224:227], v[48:51], v[68:71]
	ds_read_b64_tr_b16 v[224:225], v3 offset:192
	ds_read_b64_tr_b16 v[226:227], v3 offset:8640
	s_waitcnt lgkmcnt(14)
	v_mfma_f32_16x16x32_bf16 v[60:63], v[228:231], v[44:47], v[60:63]
	ds_read_b64_tr_b16 v[228:229], v3 offset:16896
	ds_read_b64_tr_b16 v[230:231], v3 offset:25344
	s_waitcnt lgkmcnt(14)
	v_mfma_f32_16x16x32_bf16 v[64:67], v[232:235], v[48:51], v[108:111]
	ds_read_b64_tr_b16 v[232:233], v3 offset:17088
	ds_read_b64_tr_b16 v[234:235], v3 offset:25536
	s_waitcnt lgkmcnt(14)
	v_mfma_f32_16x16x32_bf16 v[64:67], v[236:239], v[44:47], v[64:67]
	ds_read_b64_tr_b16 v[236:237], v3 offset:224
	ds_read_b64_tr_b16 v[238:239], v3 offset:8672
	s_waitcnt lgkmcnt(14)
	v_mfma_f32_16x16x32_bf16 v[68:71], v[240:243], v[48:51], v[72:75]
	ds_read_b64_tr_b16 v[240:241], v3 offset:17120
	ds_read_b64_tr_b16 v[242:243], v3 offset:25568
	s_waitcnt lgkmcnt(14)
	v_mfma_f32_16x16x32_bf16 v[68:71], v[204:207], v[44:47], v[68:71]
	ds_read_b64_tr_b16 v[204:205], v3 offset:256
	ds_read_b64_tr_b16 v[206:207], v3 offset:8704
	s_waitcnt lgkmcnt(14)
	v_mfma_f32_16x16x32_bf16 v[72:75], v[208:211], v[48:51], v[76:79]
	ds_read_b64_tr_b16 v[208:209], v3 offset:17152
	ds_read_b64_tr_b16 v[210:211], v3 offset:25600
	s_waitcnt lgkmcnt(14)
	v_mfma_f32_16x16x32_bf16 v[108:111], v[218:221], v[44:47], v[72:75]
	ds_read_b64_tr_b16 v[218:219], v3 offset:288
	ds_read_b64_tr_b16 v[220:221], v3 offset:8736
	s_waitcnt lgkmcnt(14)
	v_mfma_f32_16x16x32_bf16 v[72:75], v[224:227], v[48:51], v[80:83]
	ds_read_b64_tr_b16 v[224:225], v3 offset:17184
	ds_read_b64_tr_b16 v[226:227], v3 offset:25632
	s_waitcnt lgkmcnt(14)
	v_mfma_f32_16x16x32_bf16 v[52:55], v[228:231], v[44:47], v[52:55]
	ds_read_b64_tr_b16 v[228:229], v3 offset:320
	ds_read_b64_tr_b16 v[230:231], v3 offset:8768
	s_waitcnt lgkmcnt(14)
	v_mfma_f32_16x16x32_bf16 v[124:127], v[232:235], v[44:47], v[72:75]
	ds_read_b64_tr_b16 v[232:233], v3 offset:17216
	ds_read_b64_tr_b16 v[234:235], v3 offset:25664
	s_waitcnt lgkmcnt(14)
	v_mfma_f32_16x16x32_bf16 v[72:75], v[236:239], v[48:51], v[112:115]
	ds_read_b64_tr_b16 v[236:237], v3 offset:352
	ds_read_b64_tr_b16 v[238:239], v3 offset:8800
	s_waitcnt lgkmcnt(14)
	v_mfma_f32_16x16x32_bf16 v[132:135], v[240:243], v[44:47], v[72:75]
	ds_read_b64_tr_b16 v[240:241], v3 offset:17248
	ds_read_b64_tr_b16 v[242:243], v3 offset:25696
	s_waitcnt lgkmcnt(14)
	v_mfma_f32_16x16x32_bf16 v[72:75], v[204:207], v[48:51], v[84:87]
	ds_read_b64_tr_b16 v[204:205], v3 offset:384
	ds_read_b64_tr_b16 v[206:207], v3 offset:8832
	s_waitcnt lgkmcnt(14)
	v_mfma_f32_16x16x32_bf16 v[112:115], v[208:211], v[44:47], v[72:75]
	ds_read_b64_tr_b16 v[208:209], v3 offset:17280
	ds_read_b64_tr_b16 v[210:211], v3 offset:25728
	s_waitcnt lgkmcnt(14)
	v_mfma_f32_16x16x32_bf16 v[72:75], v[218:221], v[48:51], v[88:91]
	ds_read_b64_tr_b16 v[218:219], v3 offset:416
	ds_read_b64_tr_b16 v[220:221], v3 offset:8864
	s_waitcnt lgkmcnt(14)
	v_mfma_f32_16x16x32_bf16 v[128:131], v[224:227], v[44:47], v[72:75]
	ds_read_b64_tr_b16 v[224:225], v3 offset:17312
	ds_read_b64_tr_b16 v[226:227], v3 offset:25760
	s_waitcnt lgkmcnt(14)
	v_mfma_f32_16x16x32_bf16 v[72:75], v[228:231], v[48:51], v[92:95]
	ds_read_b64_tr_b16 v[228:229], v3 offset:448
	ds_read_b64_tr_b16 v[230:231], v3 offset:8896
	s_waitcnt lgkmcnt(14)
	v_mfma_f32_16x16x32_bf16 v[92:95], v[232:235], v[44:47], v[72:75]
	ds_read_b64_tr_b16 v[232:233], v3 offset:17344
	ds_read_b64_tr_b16 v[234:235], v3 offset:25792
	s_waitcnt lgkmcnt(14)
	v_mfma_f32_16x16x32_bf16 v[72:75], v[236:239], v[48:51], v[116:119]
	s_waitcnt lgkmcnt(12)
	v_mfma_f32_16x16x32_bf16 v[116:119], v[240:243], v[44:47], v[72:75]
	s_waitcnt lgkmcnt(10)
	v_mfma_f32_16x16x32_bf16 v[72:75], v[204:207], v[48:51], v[96:99]
	s_waitcnt lgkmcnt(8)
	v_mfma_f32_16x16x32_bf16 v[96:99], v[208:211], v[44:47], v[72:75]
	s_waitcnt lgkmcnt(6)
	v_mfma_f32_16x16x32_bf16 v[72:75], v[218:221], v[48:51], v[100:103]
	s_waitcnt lgkmcnt(4)
	v_mfma_f32_16x16x32_bf16 v[100:103], v[224:227], v[44:47], v[72:75]
	s_waitcnt lgkmcnt(2)
	v_mfma_f32_16x16x32_bf16 v[72:75], v[228:231], v[48:51], v[104:107]
	s_waitcnt lgkmcnt(0)
	v_mfma_f32_16x16x32_bf16 v[104:107], v[232:235], v[44:47], v[72:75]
	s_nop 5
	ds_read_b64_tr_b16 v[72:73], v3 offset:480
	ds_read_b64_tr_b16 v[74:75], v3 offset:8928
	ds_read_b64_tr_b16 v[76:77], v3 offset:17376
	ds_read_b64_tr_b16 v[78:79], v3 offset:25824
	s_waitcnt vmcnt(7)
	ds_write_b128 v170, v[28:31]
	s_waitcnt vmcnt(6)
	ds_write_b128 v170, v[32:35] offset:128
	s_waitcnt vmcnt(5)
	ds_write_b128 v170, v[36:39] offset:256
	s_waitcnt vmcnt(4)
	ds_write_b128 v170, v[40:43] offset:384
	s_waitcnt lgkmcnt(0)
	s_barrier
	ds_read_b64_tr_b16 v[204:205], v169
	ds_read_b64_tr_b16 v[206:207], v169 offset:8448
	ds_read_b64_tr_b16 v[208:209], v169 offset:16896
	ds_read_b64_tr_b16 v[210:211], v169 offset:25344
	ds_read_b64_tr_b16 v[218:219], v169 offset:32
	ds_read_b64_tr_b16 v[220:221], v169 offset:8480
	ds_read_b64_tr_b16 v[224:225], v169 offset:16928
	ds_read_b64_tr_b16 v[226:227], v169 offset:25376
	ds_read_b64_tr_b16 v[228:229], v169 offset:64
	ds_read_b64_tr_b16 v[230:231], v169 offset:8512
	ds_read_b64_tr_b16 v[232:233], v169 offset:16960
	ds_read_b64_tr_b16 v[234:235], v169 offset:25408
	ds_read_b64_tr_b16 v[236:237], v169 offset:96
	ds_read_b64_tr_b16 v[238:239], v169 offset:8544
	ds_read_b64_tr_b16 v[240:241], v169 offset:16992
	ds_read_b64_tr_b16 v[242:243], v169 offset:25440
	v_mfma_f32_16x16x32_bf16 v[48:51], v[72:75], v[48:51], v[120:123]
	s_waitcnt lgkmcnt(14)
	v_mfma_f32_16x16x32_bf16 v[28:31], v[204:207], v[8:11], v[52:55]
	ds_read_b64_tr_b16 v[204:205], v169 offset:128
	ds_read_b64_tr_b16 v[206:207], v169 offset:8576
	v_mfma_f32_16x16x32_bf16 v[88:91], v[76:79], v[44:47], v[48:51]
	s_waitcnt lgkmcnt(14)
	v_mfma_f32_16x16x32_bf16 v[76:79], v[208:211], v[4:7], v[28:31]
	ds_read_b64_tr_b16 v[208:209], v169 offset:17024
	ds_read_b64_tr_b16 v[210:211], v169 offset:25472
	s_waitcnt lgkmcnt(14)
	v_mfma_f32_16x16x32_bf16 v[32:35], v[218:221], v[8:11], v[56:59]
	ds_read_b64_tr_b16 v[218:219], v169 offset:160
	ds_read_b64_tr_b16 v[220:221], v169 offset:8608
	s_waitcnt lgkmcnt(14)
	v_mfma_f32_16x16x32_bf16 v[80:83], v[224:227], v[4:7], v[32:35]
	ds_read_b64_tr_b16 v[224:225], v169 offset:17056
	ds_read_b64_tr_b16 v[226:227], v169 offset:25504
	s_waitcnt lgkmcnt(14)
	v_mfma_f32_16x16x32_bf16 v[28:31], v[228:231], v[8:11], v[60:63]
	ds_read_b64_tr_b16 v[228:229], v169 offset:192
	ds_read_b64_tr_b16 v[230:231], v169 offset:8640
	s_waitcnt lgkmcnt(14)
	v_mfma_f32_16x16x32_bf16 v[84:87], v[232:235], v[4:7], v[28:31]
	ds_read_b64_tr_b16 v[232:233], v169 offset:17088
	ds_read_b64_tr_b16 v[234:235], v169 offset:25536
	s_waitcnt lgkmcnt(14)
	v_mfma_f32_16x16x32_bf16 v[28:31], v[236:239], v[8:11], v[64:67]
	ds_read_b64_tr_b16 v[236:237], v169 offset:224
	ds_read_b64_tr_b16 v[238:239], v169 offset:8672
	s_waitcnt lgkmcnt(14)
	v_mfma_f32_16x16x32_bf16 v[72:75], v[240:243], v[4:7], v[28:31]
	ds_read_b64_tr_b16 v[240:241], v169 offset:17120
	ds_read_b64_tr_b16 v[242:243], v169 offset:25568
	s_waitcnt lgkmcnt(14)
	v_mfma_f32_16x16x32_bf16 v[28:31], v[204:207], v[8:11], v[68:71]
	ds_read_b64_tr_b16 v[204:205], v169 offset:256
	ds_read_b64_tr_b16 v[206:207], v169 offset:8704
	s_waitcnt lgkmcnt(14)
	v_mfma_f32_16x16x32_bf16 v[28:31], v[208:211], v[4:7], v[28:31]
	ds_read_b64_tr_b16 v[208:209], v169 offset:17152
	ds_read_b64_tr_b16 v[210:211], v169 offset:25600
	s_waitcnt lgkmcnt(14)
	v_mfma_f32_16x16x32_bf16 v[32:35], v[218:221], v[8:11], v[108:111]
	ds_read_b64_tr_b16 v[218:219], v169 offset:288
	ds_read_b64_tr_b16 v[220:221], v169 offset:8736
	s_waitcnt lgkmcnt(14)
	v_mfma_f32_16x16x32_bf16 v[32:35], v[224:227], v[4:7], v[32:35]
	ds_read_b64_tr_b16 v[224:225], v169 offset:17184
	ds_read_b64_tr_b16 v[226:227], v169 offset:25632
	s_waitcnt lgkmcnt(14)
	v_mfma_f32_16x16x32_bf16 v[36:39], v[228:231], v[8:11], v[124:127]
	ds_read_b64_tr_b16 v[228:229], v169 offset:320
	ds_read_b64_tr_b16 v[230:231], v169 offset:8768
	s_waitcnt lgkmcnt(14)
	v_mfma_f32_16x16x32_bf16 v[36:39], v[232:235], v[4:7], v[36:39]
	ds_read_b64_tr_b16 v[232:233], v169 offset:17216
	ds_read_b64_tr_b16 v[234:235], v169 offset:25664
	s_waitcnt lgkmcnt(14)
	v_mfma_f32_16x16x32_bf16 v[40:43], v[236:239], v[8:11], v[132:135]
	ds_read_b64_tr_b16 v[236:237], v169 offset:352
	ds_read_b64_tr_b16 v[238:239], v169 offset:8800
	s_waitcnt lgkmcnt(14)
	v_mfma_f32_16x16x32_bf16 v[64:67], v[240:243], v[4:7], v[40:43]
	ds_read_b64_tr_b16 v[240:241], v169 offset:17248
	ds_read_b64_tr_b16 v[242:243], v169 offset:25696
	s_waitcnt lgkmcnt(14)
	v_mfma_f32_16x16x32_bf16 v[40:43], v[204:207], v[8:11], v[112:115]
	ds_read_b64_tr_b16 v[204:205], v169 offset:384
	ds_read_b64_tr_b16 v[206:207], v169 offset:8832
	s_waitcnt lgkmcnt(14)
	v_mfma_f32_16x16x32_bf16 v[40:43], v[208:211], v[4:7], v[40:43]
	ds_read_b64_tr_b16 v[208:209], v169 offset:17280
	ds_read_b64_tr_b16 v[210:211], v169 offset:25728
	s_waitcnt lgkmcnt(14)
	v_mfma_f32_16x16x32_bf16 v[44:47], v[218:221], v[8:11], v[128:131]
	ds_read_b64_tr_b16 v[218:219], v169 offset:416
	ds_read_b64_tr_b16 v[220:221], v169 offset:8864
	s_waitcnt lgkmcnt(14)
	v_mfma_f32_16x16x32_bf16 v[44:47], v[224:227], v[4:7], v[44:47]
	ds_read_b64_tr_b16 v[224:225], v169 offset:17312
	ds_read_b64_tr_b16 v[226:227], v169 offset:25760
	s_waitcnt lgkmcnt(14)
	v_mfma_f32_16x16x32_bf16 v[48:51], v[228:231], v[8:11], v[92:95]
	ds_read_b64_tr_b16 v[228:229], v169 offset:448
	ds_read_b64_tr_b16 v[230:231], v169 offset:8896
	s_waitcnt lgkmcnt(14)
	v_mfma_f32_16x16x32_bf16 v[48:51], v[232:235], v[4:7], v[48:51]
	ds_read_b64_tr_b16 v[232:233], v169 offset:17344
	ds_read_b64_tr_b16 v[234:235], v169 offset:25792
	s_waitcnt lgkmcnt(14)
	v_mfma_f32_16x16x32_bf16 v[52:55], v[236:239], v[8:11], v[116:119]
	ds_read_b64_tr_b16 v[236:237], v169 offset:480
	ds_read_b64_tr_b16 v[238:239], v169 offset:8928
	s_waitcnt lgkmcnt(14)
	v_mfma_f32_16x16x32_bf16 v[68:71], v[240:243], v[4:7], v[52:55]
	s_waitcnt lgkmcnt(12)
	v_mfma_f32_16x16x32_bf16 v[52:55], v[204:207], v[8:11], v[96:99]
	s_waitcnt lgkmcnt(10)
	v_mfma_f32_16x16x32_bf16 v[52:55], v[208:211], v[4:7], v[52:55]
	s_waitcnt lgkmcnt(8)
	v_mfma_f32_16x16x32_bf16 v[56:59], v[218:221], v[8:11], v[100:103]
	s_waitcnt lgkmcnt(6)
	v_mfma_f32_16x16x32_bf16 v[56:59], v[224:227], v[4:7], v[56:59]
	s_waitcnt lgkmcnt(4)
	v_mfma_f32_16x16x32_bf16 v[60:63], v[228:231], v[8:11], v[104:107]
	s_waitcnt lgkmcnt(2)
	v_mfma_f32_16x16x32_bf16 v[60:63], v[232:235], v[4:7], v[60:63]
	ds_read_b64_tr_b16 v[96:97], v169 offset:17376
	ds_read_b64_tr_b16 v[98:99], v169 offset:25824
	s_waitcnt vmcnt(3)
	ds_write_b128 v168, v[12:15]
	s_waitcnt vmcnt(2)
	ds_write_b128 v168, v[16:19] offset:128
	s_waitcnt vmcnt(1)
	ds_write_b128 v168, v[20:23] offset:256
	s_waitcnt vmcnt(0)
	ds_write_b128 v168, v[24:27] offset:384
	s_waitcnt lgkmcnt(0)
	s_waitcnt lgkmcnt(6)
	v_mfma_f32_16x16x32_bf16 v[8:11], v[236:239], v[8:11], v[88:91]
	s_barrier
	v_cvt_pk_bf16_f32 v20, v139, v140
	s_waitcnt lgkmcnt(4)
	v_mfma_f32_16x16x32_bf16 v[4:7], v[96:99], v[4:7], v[8:11]
	s_nop 3
	ds_read_b64_tr_b16 v[204:205], v3
	ds_read_b64_tr_b16 v[206:207], v3 offset:8448
	ds_read_b64_tr_b16 v[208:209], v3 offset:16896
	ds_read_b64_tr_b16 v[210:211], v3 offset:25344
	ds_read_b64_tr_b16 v[218:219], v3 offset:32
	ds_read_b64_tr_b16 v[220:221], v3 offset:8480
	ds_read_b64_tr_b16 v[224:225], v3 offset:16928
	ds_read_b64_tr_b16 v[226:227], v3 offset:25376
	ds_read_b64_tr_b16 v[228:229], v3 offset:64
	ds_read_b64_tr_b16 v[230:231], v3 offset:8512
	ds_read_b64_tr_b16 v[232:233], v3 offset:16960
	ds_read_b64_tr_b16 v[234:235], v3 offset:25408
	ds_read_b64_tr_b16 v[236:237], v3 offset:96
	ds_read_b64_tr_b16 v[238:239], v3 offset:8544
	ds_read_b64_tr_b16 v[240:241], v3 offset:16992
	ds_read_b64_tr_b16 v[242:243], v3 offset:25440
	v_cvt_pk_bf16_f32 v21, v141, v142
	v_cvt_pk_bf16_f32 v22, v143, v144
	v_cvt_pk_bf16_f32 v23, v145, v146
	v_cvt_pk_bf16_f32 v16, v147, v148
	v_cvt_pk_bf16_f32 v17, v149, v150
	s_waitcnt lgkmcnt(14)
	v_mfma_f32_16x16x32_bf16 v[8:11], v[204:207], v[20:23], v[76:79]
	ds_read_b64_tr_b16 v[204:205], v3 offset:128
	ds_read_b64_tr_b16 v[206:207], v3 offset:8576
	v_cvt_pk_bf16_f32 v18, v151, v152
	v_cvt_pk_bf16_f32 v19, v153, v154
	v_add_u32_e32 v88, 0x80, v136
	v_ashrrev_i32_e32 v89, 31, v88
	s_waitcnt lgkmcnt(14)
	v_mfma_f32_16x16x32_bf16 v[12:15], v[208:211], v[16:19], v[8:11]
	ds_read_b64_tr_b16 v[208:209], v3 offset:17024
	ds_read_b64_tr_b16 v[210:211], v3 offset:25472
	s_waitcnt lgkmcnt(14)
	v_mfma_f32_16x16x32_bf16 v[24:27], v[218:221], v[20:23], v[80:83]
	ds_read_b64_tr_b16 v[218:219], v3 offset:160
	ds_read_b64_tr_b16 v[220:221], v3 offset:8608
	s_waitcnt lgkmcnt(14)
	v_mfma_f32_16x16x32_bf16 v[8:11], v[224:227], v[16:19], v[24:27]
	ds_read_b64_tr_b16 v[224:225], v3 offset:17056
	ds_read_b64_tr_b16 v[226:227], v3 offset:25504
	s_waitcnt lgkmcnt(14)
	v_mfma_f32_16x16x32_bf16 v[24:27], v[228:231], v[20:23], v[84:87]
	ds_read_b64_tr_b16 v[228:229], v3 offset:192
	ds_read_b64_tr_b16 v[230:231], v3 offset:8640
	s_waitcnt lgkmcnt(14)
	v_mfma_f32_16x16x32_bf16 v[24:27], v[232:235], v[16:19], v[24:27]
	ds_read_b64_tr_b16 v[232:233], v3 offset:17088
	ds_read_b64_tr_b16 v[234:235], v3 offset:25536
	s_waitcnt lgkmcnt(14)
	v_mfma_f32_16x16x32_bf16 v[72:75], v[236:239], v[20:23], v[72:75]
	ds_read_b64_tr_b16 v[236:237], v3 offset:224
	ds_read_b64_tr_b16 v[238:239], v3 offset:8672
	s_waitcnt lgkmcnt(14)
	v_mfma_f32_16x16x32_bf16 v[72:75], v[240:243], v[16:19], v[72:75]
	ds_read_b64_tr_b16 v[240:241], v3 offset:17120
	ds_read_b64_tr_b16 v[242:243], v3 offset:25568
	s_waitcnt lgkmcnt(14)
	v_mfma_f32_16x16x32_bf16 v[28:31], v[204:207], v[20:23], v[28:31]
	ds_read_b64_tr_b16 v[204:205], v3 offset:256
	ds_read_b64_tr_b16 v[206:207], v3 offset:8704
	s_waitcnt lgkmcnt(14)
	v_mfma_f32_16x16x32_bf16 v[28:31], v[208:211], v[16:19], v[28:31]
	ds_read_b64_tr_b16 v[208:209], v3 offset:17152
	ds_read_b64_tr_b16 v[210:211], v3 offset:25600
	s_waitcnt lgkmcnt(14)
	v_mfma_f32_16x16x32_bf16 v[32:35], v[218:221], v[20:23], v[32:35]
	ds_read_b64_tr_b16 v[218:219], v3 offset:288
	ds_read_b64_tr_b16 v[220:221], v3 offset:8736
	s_waitcnt lgkmcnt(14)
	v_mfma_f32_16x16x32_bf16 v[32:35], v[224:227], v[16:19], v[32:35]
	ds_read_b64_tr_b16 v[224:225], v3 offset:17184
	ds_read_b64_tr_b16 v[226:227], v3 offset:25632
	s_waitcnt lgkmcnt(14)
	v_mfma_f32_16x16x32_bf16 v[36:39], v[228:231], v[20:23], v[36:39]
	ds_read_b64_tr_b16 v[228:229], v3 offset:320
	ds_read_b64_tr_b16 v[230:231], v3 offset:8768
	s_waitcnt lgkmcnt(14)
	v_mfma_f32_16x16x32_bf16 v[36:39], v[232:235], v[16:19], v[36:39]
	ds_read_b64_tr_b16 v[232:233], v3 offset:17216
	ds_read_b64_tr_b16 v[234:235], v3 offset:25664
	s_waitcnt lgkmcnt(14)
	v_mfma_f32_16x16x32_bf16 v[64:67], v[236:239], v[20:23], v[64:67]
	ds_read_b64_tr_b16 v[236:237], v3 offset:352
	ds_read_b64_tr_b16 v[238:239], v3 offset:8800
	s_waitcnt lgkmcnt(14)
	v_mfma_f32_16x16x32_bf16 v[64:67], v[240:243], v[16:19], v[64:67]
	ds_read_b64_tr_b16 v[240:241], v3 offset:17248
	ds_read_b64_tr_b16 v[242:243], v3 offset:25696
	s_waitcnt lgkmcnt(14)
	v_mfma_f32_16x16x32_bf16 v[40:43], v[204:207], v[20:23], v[40:43]
	ds_read_b64_tr_b16 v[204:205], v3 offset:384
	ds_read_b64_tr_b16 v[206:207], v3 offset:8832
	s_waitcnt lgkmcnt(14)
	v_mfma_f32_16x16x32_bf16 v[40:43], v[208:211], v[16:19], v[40:43]
	ds_read_b64_tr_b16 v[208:209], v3 offset:17280
	ds_read_b64_tr_b16 v[210:211], v3 offset:25728
	s_waitcnt lgkmcnt(14)
	v_mfma_f32_16x16x32_bf16 v[44:47], v[218:221], v[20:23], v[44:47]
	ds_read_b64_tr_b16 v[218:219], v3 offset:416
	ds_read_b64_tr_b16 v[220:221], v3 offset:8864
	s_waitcnt lgkmcnt(14)
	v_mfma_f32_16x16x32_bf16 v[44:47], v[224:227], v[16:19], v[44:47]
	ds_read_b64_tr_b16 v[224:225], v3 offset:17312
	ds_read_b64_tr_b16 v[226:227], v3 offset:25760
	s_waitcnt lgkmcnt(14)
	v_mfma_f32_16x16x32_bf16 v[48:51], v[228:231], v[20:23], v[48:51]
	ds_read_b64_tr_b16 v[228:229], v3 offset:448
	ds_read_b64_tr_b16 v[230:231], v3 offset:8896
	s_waitcnt lgkmcnt(14)
	v_mfma_f32_16x16x32_bf16 v[48:51], v[232:235], v[16:19], v[48:51]
	ds_read_b64_tr_b16 v[232:233], v3 offset:17344
	ds_read_b64_tr_b16 v[234:235], v3 offset:25792
	s_waitcnt lgkmcnt(14)
	v_mfma_f32_16x16x32_bf16 v[68:71], v[236:239], v[20:23], v[68:71]
	ds_read_b64_tr_b16 v[236:237], v3 offset:480
	ds_read_b64_tr_b16 v[238:239], v3 offset:8928
	s_waitcnt lgkmcnt(14)
	v_mfma_f32_16x16x32_bf16 v[68:71], v[240:243], v[16:19], v[68:71]
	ds_read_b64_tr_b16 v[240:241], v3 offset:17376
	ds_read_b64_tr_b16 v[242:243], v3 offset:25824
	s_waitcnt lgkmcnt(14)
	v_mfma_f32_16x16x32_bf16 v[52:55], v[204:207], v[20:23], v[52:55]
	s_waitcnt lgkmcnt(12)
	v_mfma_f32_16x16x32_bf16 v[52:55], v[208:211], v[16:19], v[52:55]
	s_waitcnt lgkmcnt(10)
	v_mfma_f32_16x16x32_bf16 v[56:59], v[218:221], v[20:23], v[56:59]
	s_waitcnt lgkmcnt(8)
	v_mfma_f32_16x16x32_bf16 v[56:59], v[224:227], v[16:19], v[56:59]
	s_waitcnt lgkmcnt(6)
	v_mfma_f32_16x16x32_bf16 v[60:63], v[228:231], v[20:23], v[60:63]
	s_waitcnt lgkmcnt(4)
	v_mfma_f32_16x16x32_bf16 v[60:63], v[232:235], v[16:19], v[60:63]
	v_add_f32_e32 v3, v137, v138
	s_waitcnt lgkmcnt(2)
	v_mfma_f32_16x16x32_bf16 v[4:7], v[236:239], v[20:23], v[4:7]
	s_waitcnt lgkmcnt(0)
	v_mfma_f32_16x16x32_bf16 v[4:7], v[240:243], v[16:19], v[4:7]
	v_div_scale_f32 v16, s[12:13], v3, v3, 1.0
	v_rcp_f32_e32 v17, v16
	s_nop 0
	v_fma_f32 v18, -v16, v17, 1.0
	v_fmac_f32_e32 v17, v18, v17
	v_div_scale_f32 v18, vcc, 1.0, v3, 1.0
	v_mul_f32_e32 v19, v18, v17
	v_fma_f32 v20, -v16, v19, v18
	v_fmac_f32_e32 v19, v20, v17
	v_fma_f32 v16, -v16, v19, v18
	v_div_fmas_f32 v16, v16, v17, v19
	v_lshlrev_b64 v[18:19], 11, v[88:89]
	v_lshl_add_u64 v[18:19], s[10:11], 0, v[18:19]
	v_div_fixup_f32 v16, v16, v3, 1.0
	v_mad_i64_i32 v[18:19], s[6:7], s6, v155, v[18:19]
	v_lshl_add_u64 v[18:19], v[18:19], 0, s[8:9]
	v_pk_mul_f32 v[8:9], v[16:17], v[8:9] op_sel_hi:[0,1]
	v_pk_mul_f32 v[10:11], v[16:17], v[10:11] op_sel_hi:[0,1]
	v_lshl_add_u64 v[0:1], v[18:19], 0, v[0:1]
	v_cvt_pk_bf16_f32 v8, v8, v9
	v_cvt_pk_bf16_f32 v9, v10, v11
	global_store_dwordx2 v[0:1], v[8:9], off offset:32
	v_pk_mul_f32 v[8:9], v[16:17], v[24:25] op_sel_hi:[0,1]
	v_pk_mul_f32 v[10:11], v[16:17], v[26:27] op_sel_hi:[0,1]
	v_cvt_pk_bf16_f32 v8, v8, v9
	v_cvt_pk_bf16_f32 v9, v10, v11
	global_store_dwordx2 v[0:1], v[8:9], off offset:64
	v_pk_mul_f32 v[8:9], v[16:17], v[72:73] op_sel_hi:[0,1]
	v_pk_mul_f32 v[10:11], v[16:17], v[74:75] op_sel_hi:[0,1]
	v_cvt_pk_bf16_f32 v8, v8, v9
	v_cvt_pk_bf16_f32 v9, v10, v11
	global_store_dwordx2 v[0:1], v[8:9], off offset:96
	v_pk_mul_f32 v[8:9], v[16:17], v[28:29] op_sel_hi:[0,1]
	v_pk_mul_f32 v[10:11], v[16:17], v[30:31] op_sel_hi:[0,1]
	v_cvt_pk_bf16_f32 v8, v8, v9
	v_cvt_pk_bf16_f32 v9, v10, v11
	global_store_dwordx2 v[0:1], v[8:9], off offset:128
	v_pk_mul_f32 v[8:9], v[16:17], v[32:33] op_sel_hi:[0,1]
	v_pk_mul_f32 v[10:11], v[16:17], v[34:35] op_sel_hi:[0,1]
	v_cvt_pk_bf16_f32 v8, v8, v9
	v_cvt_pk_bf16_f32 v9, v10, v11
	global_store_dwordx2 v[0:1], v[8:9], off offset:160
	v_pk_mul_f32 v[8:9], v[16:17], v[36:37] op_sel_hi:[0,1]
	v_pk_mul_f32 v[10:11], v[16:17], v[38:39] op_sel_hi:[0,1]
	v_cvt_pk_bf16_f32 v8, v8, v9
	v_cvt_pk_bf16_f32 v9, v10, v11
	global_store_dwordx2 v[0:1], v[8:9], off offset:192
	v_pk_mul_f32 v[8:9], v[16:17], v[64:65] op_sel_hi:[0,1]
	v_pk_mul_f32 v[10:11], v[16:17], v[66:67] op_sel_hi:[0,1]
	v_cvt_pk_bf16_f32 v8, v8, v9
	v_cvt_pk_bf16_f32 v9, v10, v11
	global_store_dwordx2 v[0:1], v[8:9], off offset:224
	v_pk_mul_f32 v[8:9], v[16:17], v[40:41] op_sel_hi:[0,1]
	v_pk_mul_f32 v[10:11], v[16:17], v[42:43] op_sel_hi:[0,1]
	v_cvt_pk_bf16_f32 v8, v8, v9
	v_cvt_pk_bf16_f32 v9, v10, v11
	global_store_dwordx2 v[0:1], v[8:9], off offset:256
	v_pk_mul_f32 v[8:9], v[16:17], v[44:45] op_sel_hi:[0,1]
	v_pk_mul_f32 v[10:11], v[16:17], v[46:47] op_sel_hi:[0,1]
	v_cvt_pk_bf16_f32 v8, v8, v9
	v_cvt_pk_bf16_f32 v9, v10, v11
	global_store_dwordx2 v[0:1], v[8:9], off offset:288
	v_pk_mul_f32 v[8:9], v[16:17], v[48:49] op_sel_hi:[0,1]
	v_pk_mul_f32 v[10:11], v[16:17], v[50:51] op_sel_hi:[0,1]
	v_cvt_pk_bf16_f32 v8, v8, v9
	v_cvt_pk_bf16_f32 v9, v10, v11
	global_store_dwordx2 v[0:1], v[8:9], off offset:320
	v_pk_mul_f32 v[8:9], v[16:17], v[68:69] op_sel_hi:[0,1]
	v_pk_mul_f32 v[10:11], v[16:17], v[70:71] op_sel_hi:[0,1]
	v_cvt_pk_bf16_f32 v8, v8, v9
	v_cvt_pk_bf16_f32 v9, v10, v11
	global_store_dwordx2 v[0:1], v[8:9], off offset:352
	v_pk_mul_f32 v[8:9], v[16:17], v[52:53] op_sel_hi:[0,1]
	v_pk_mul_f32 v[10:11], v[16:17], v[54:55] op_sel_hi:[0,1]
	v_cvt_pk_bf16_f32 v8, v8, v9
	v_cvt_pk_bf16_f32 v9, v10, v11
	global_store_dwordx2 v[0:1], v[8:9], off offset:384
	v_pk_mul_f32 v[8:9], v[16:17], v[56:57] op_sel_hi:[0,1]
	v_pk_mul_f32 v[10:11], v[16:17], v[58:59] op_sel_hi:[0,1]
	v_cvt_pk_bf16_f32 v8, v8, v9
	v_cvt_pk_bf16_f32 v9, v10, v11
	v_pk_mul_f32 v[12:13], v[16:17], v[12:13] op_sel_hi:[0,1]
	v_pk_mul_f32 v[14:15], v[16:17], v[14:15] op_sel_hi:[0,1]
	global_store_dwordx2 v[0:1], v[8:9], off offset:416
	v_pk_mul_f32 v[8:9], v[16:17], v[60:61] op_sel_hi:[0,1]
	v_pk_mul_f32 v[10:11], v[16:17], v[62:63] op_sel_hi:[0,1]
	v_pk_mul_f32 v[4:5], v[16:17], v[4:5] op_sel_hi:[0,1]
	v_pk_mul_f32 v[6:7], v[16:17], v[6:7] op_sel_hi:[0,1]
	v_cvt_pk_bf16_f32 v12, v12, v13
	v_cvt_pk_bf16_f32 v13, v14, v15
	v_cvt_pk_bf16_f32 v8, v8, v9
	v_cvt_pk_bf16_f32 v9, v10, v11
	v_cvt_pk_bf16_f32 v4, v4, v5
	v_cvt_pk_bf16_f32 v5, v6, v7
	global_store_dwordx2 v[0:1], v[12:13], off
	global_store_dwordx2 v[0:1], v[8:9], off offset:448
	global_store_dwordx2 v[0:1], v[4:5], off offset:480
	s_waitcnt lgkmcnt(0)
	s_barrier
